# GEMM main loops: MFMA issue order changed to a snake: each accumulator's two K-halves back to back, and neighbouring MFMAs share an operand fragment
# speedup vs baseline: 1.0201x; 1.0065x over previous
.LBB0_472:
	ds_read_b128 v[152:155], v148
	ds_read_b128 v[156:159], v148 offset:1024
	ds_read_b128 v[166:169], v148 offset:2048
	ds_read_b128 v[170:173], v148 offset:3072
	ds_read_b128 v[174:177], v149
	ds_read_b128 v[178:181], v149 offset:1024
	ds_read_b128 v[182:185], v149 offset:2048
	ds_read_b128 v[186:189], v149 offset:3072
	s_add_u32 s44, s54, 0xfff00080
	s_addc_u32 s56, s55, -1
	s_cmp_eq_u32 s72, 60
	s_cselect_b32 s59, s17, s56
	s_cselect_b32 s58, s68, s44
	s_cselect_b32 s57, s15, s71
	s_cselect_b32 s56, s69, s70
	v_lshl_add_u64 v[160:161], s[54:55], 0, v[138:139]
	s_add_i32 m0, s41, 0xc000
	ds_read_b128 v[190:193], v150
	ds_read_b128 v[194:197], v150 offset:1024
	ds_read_b128 v[198:201], v150 offset:2048
	ds_read_b128 v[202:205], v150 offset:3072
	ds_read_b128 v[206:209], v150 offset:4096
	ds_read_b128 v[210:213], v150 offset:5120
	ds_read_b128 v[214:217], v150 offset:6144
	ds_read_b128 v[218:221], v150 offset:7168
	global_load_lds_dwordx4 v[160:161], off
	v_lshl_add_u64 v[160:161], s[54:55], 0, v[140:141]
	s_add_i32 m0, s41, 0xe000
	s_nop 0
	global_load_lds_dwordx4 v[160:161], off
	s_waitcnt vmcnt(8)
	s_waitcnt lgkmcnt(0)
	s_barrier
	s_setprio 1
	s_waitcnt lgkmcnt(0)
	v_mfma_f32_16x16x32_bf16 v[126:129], v[152:155], v[190:193], v[126:129]
	v_mfma_f32_16x16x32_bf16 v[126:129], v[156:159], v[194:197], v[126:129]
	v_mfma_f32_16x16x32_bf16 v[122:125], v[170:173], v[194:197], v[122:125]
	v_mfma_f32_16x16x32_bf16 v[122:125], v[166:169], v[190:193], v[122:125]
	v_mfma_f32_16x16x32_bf16 v[110:113], v[166:169], v[198:201], v[110:113]
	v_mfma_f32_16x16x32_bf16 v[110:113], v[170:173], v[202:205], v[110:113]
	v_mfma_f32_16x16x32_bf16 v[118:121], v[156:159], v[202:205], v[118:121]
	v_mfma_f32_16x16x32_bf16 v[118:121], v[152:155], v[198:201], v[118:121]
	v_mfma_f32_16x16x32_bf16 v[102:105], v[152:155], v[206:209], v[102:105]
	v_mfma_f32_16x16x32_bf16 v[102:105], v[156:159], v[210:213], v[102:105]
	v_mfma_f32_16x16x32_bf16 v[94:97], v[170:173], v[210:213], v[94:97]
	v_mfma_f32_16x16x32_bf16 v[94:97], v[166:169], v[206:209], v[94:97]
	v_mfma_f32_16x16x32_bf16 v[78:81], v[166:169], v[214:217], v[78:81]
	v_mfma_f32_16x16x32_bf16 v[78:81], v[170:173], v[218:221], v[78:81]
	v_mfma_f32_16x16x32_bf16 v[86:89], v[156:159], v[218:221], v[86:89]
	v_mfma_f32_16x16x32_bf16 v[86:89], v[152:155], v[214:217], v[86:89]
	s_setprio 0
	s_setprio 1
	v_mfma_f32_16x16x32_bf16 v[114:117], v[174:177], v[190:193], v[114:117]
	v_mfma_f32_16x16x32_bf16 v[114:117], v[178:181], v[194:197], v[114:117]
	v_mfma_f32_16x16x32_bf16 v[106:109], v[186:189], v[194:197], v[106:109]
	v_mfma_f32_16x16x32_bf16 v[106:109], v[182:185], v[190:193], v[106:109]
	v_mfma_f32_16x16x32_bf16 v[90:93], v[182:185], v[198:201], v[90:93]
	v_mfma_f32_16x16x32_bf16 v[90:93], v[186:189], v[202:205], v[90:93]
	v_mfma_f32_16x16x32_bf16 v[98:101], v[178:181], v[202:205], v[98:101]
	v_mfma_f32_16x16x32_bf16 v[98:101], v[174:177], v[198:201], v[98:101]
	v_mfma_f32_16x16x32_bf16 v[82:85], v[174:177], v[206:209], v[82:85]
	v_mfma_f32_16x16x32_bf16 v[82:85], v[178:181], v[210:213], v[82:85]
	v_mfma_f32_16x16x32_bf16 v[74:77], v[186:189], v[210:213], v[74:77]
	v_mfma_f32_16x16x32_bf16 v[74:77], v[182:185], v[206:209], v[74:77]
	v_mfma_f32_16x16x32_bf16 v[66:69], v[182:185], v[214:217], v[66:69]
	v_mfma_f32_16x16x32_bf16 v[66:69], v[186:189], v[218:221], v[66:69]
	v_mfma_f32_16x16x32_bf16 v[70:73], v[178:181], v[218:221], v[70:73]
	v_mfma_f32_16x16x32_bf16 v[70:73], v[174:177], v[214:217], v[70:73]
	s_setprio 0
	s_barrier
	s_add_i32 s44, s64, s27
	v_lshl_add_u64 v[160:161], s[56:57], 0, v[134:135]
	s_mov_b32 m0, s44
	ds_read_b128 v[190:193], v150 offset:16384
	ds_read_b128 v[194:197], v150 offset:17408
	ds_read_b128 v[198:201], v150 offset:18432
	ds_read_b128 v[202:205], v150 offset:19456
	ds_read_b128 v[206:209], v150 offset:20480
	ds_read_b128 v[210:213], v150 offset:21504
	ds_read_b128 v[214:217], v150 offset:22528
	ds_read_b128 v[218:221], v150 offset:23552
	global_load_lds_dwordx4 v[160:161], off
	s_add_i32 m0, s44, 0x2000
	s_add_u32 s74, s56, 0x100000
	v_lshl_add_u64 v[222:223], s[56:57], 0, v[130:131]
	s_addc_u32 s75, s57, 0
	s_add_i32 s44, s65, s27
	global_load_lds_dwordx4 v[222:223], off
	v_lshl_add_u64 v[224:225], s[74:75], 0, v[134:135]
	s_mov_b32 m0, s44
	v_lshl_add_u64 v[226:227], s[58:59], 0, v[132:133]
	global_load_lds_dwordx4 v[224:225], off
	v_lshl_add_u64 v[224:225], s[74:75], 0, v[130:131]
	s_add_i32 m0, s44, 0x2000
	s_nop 0
	global_load_lds_dwordx4 v[224:225], off
	v_lshl_add_u64 v[224:225], s[58:59], 0, v[136:137]
	s_mov_b32 m0, s41
	s_nop 0
	global_load_lds_dwordx4 v[224:225], off
	s_mov_b32 m0, s43
	s_nop 0
	global_load_lds_dwordx4 v[226:227], off
	s_waitcnt vmcnt(8)
	s_waitcnt lgkmcnt(0)
	s_barrier
	s_setprio 1
	s_waitcnt lgkmcnt(0)
	v_mfma_f32_16x16x32_bf16 v[62:65], v[152:155], v[190:193], v[62:65]
	v_mfma_f32_16x16x32_bf16 v[62:65], v[156:159], v[194:197], v[62:65]
	v_mfma_f32_16x16x32_bf16 v[58:61], v[170:173], v[194:197], v[58:61]
	v_mfma_f32_16x16x32_bf16 v[58:61], v[166:169], v[190:193], v[58:61]
	v_mfma_f32_16x16x32_bf16 v[46:49], v[166:169], v[198:201], v[46:49]
	v_mfma_f32_16x16x32_bf16 v[46:49], v[170:173], v[202:205], v[46:49]
	v_mfma_f32_16x16x32_bf16 v[54:57], v[156:159], v[202:205], v[54:57]
	v_mfma_f32_16x16x32_bf16 v[54:57], v[152:155], v[198:201], v[54:57]
	v_mfma_f32_16x16x32_bf16 v[38:41], v[152:155], v[206:209], v[38:41]
	v_mfma_f32_16x16x32_bf16 v[38:41], v[156:159], v[210:213], v[38:41]
	v_mfma_f32_16x16x32_bf16 v[30:33], v[170:173], v[210:213], v[30:33]
	v_mfma_f32_16x16x32_bf16 v[30:33], v[166:169], v[206:209], v[30:33]
	v_mfma_f32_16x16x32_bf16 v[14:17], v[166:169], v[214:217], v[14:17]
	v_mfma_f32_16x16x32_bf16 v[14:17], v[170:173], v[218:221], v[14:17]
	v_mfma_f32_16x16x32_bf16 v[22:25], v[156:159], v[218:221], v[22:25]
	v_mfma_f32_16x16x32_bf16 v[22:25], v[152:155], v[214:217], v[22:25]
	s_setprio 0
	s_setprio 1
	v_mfma_f32_16x16x32_bf16 v[50:53], v[174:177], v[190:193], v[50:53]
	v_mfma_f32_16x16x32_bf16 v[50:53], v[178:181], v[194:197], v[50:53]
	v_mfma_f32_16x16x32_bf16 v[42:45], v[186:189], v[194:197], v[42:45]
	v_mfma_f32_16x16x32_bf16 v[42:45], v[182:185], v[190:193], v[42:45]
	v_mfma_f32_16x16x32_bf16 v[26:29], v[182:185], v[198:201], v[26:29]
	v_mfma_f32_16x16x32_bf16 v[26:29], v[186:189], v[202:205], v[26:29]
	v_mfma_f32_16x16x32_bf16 v[34:37], v[178:181], v[202:205], v[34:37]
	v_mfma_f32_16x16x32_bf16 v[34:37], v[174:177], v[198:201], v[34:37]
	v_mfma_f32_16x16x32_bf16 v[18:21], v[174:177], v[206:209], v[18:21]
	v_mfma_f32_16x16x32_bf16 v[18:21], v[178:181], v[210:213], v[18:21]
	v_mfma_f32_16x16x32_bf16 v[10:13], v[186:189], v[210:213], v[10:13]
	v_mfma_f32_16x16x32_bf16 v[10:13], v[182:185], v[206:209], v[10:13]
	v_mfma_f32_16x16x32_bf16 v[2:5], v[182:185], v[214:217], v[2:5]
	v_mfma_f32_16x16x32_bf16 v[2:5], v[186:189], v[218:221], v[2:5]
	v_mfma_f32_16x16x32_bf16 v[6:9], v[178:181], v[218:221], v[6:9]
	v_mfma_f32_16x16x32_bf16 v[6:9], v[174:177], v[214:217], v[6:9]
	s_setprio 0
	s_barrier
	s_add_i32 s44, 0, 0x18000
	v_add_u32_e32 v151, s44, v146
	s_add_i32 s73, 0, 0x1c000
	ds_read_b128 v[152:155], v151
	ds_read_b128 v[156:159], v151 offset:1024
	ds_read_b128 v[166:169], v151 offset:2048
	ds_read_b128 v[170:173], v151 offset:3072
	v_add_u32_e32 v151, s73, v146
	ds_read_b128 v[174:177], v151
	ds_read_b128 v[178:181], v151 offset:1024
	ds_read_b128 v[182:185], v151 offset:2048
	ds_read_b128 v[186:189], v151 offset:3072
	s_add_u32 s58, s58, 0x100000
	s_addc_u32 s59, s59, 0
	s_mov_b32 m0, s45
	v_lshl_add_u64 v[228:229], s[58:59], 0, v[136:137]
	ds_read_b128 v[190:193], v150 offset:32768
	ds_read_b128 v[194:197], v150 offset:33792
	ds_read_b128 v[198:201], v150 offset:34816
	ds_read_b128 v[202:205], v150 offset:35840
	ds_read_b128 v[206:209], v150 offset:36864
	ds_read_b128 v[210:213], v150 offset:37888
	ds_read_b128 v[214:217], v150 offset:38912
	ds_read_b128 v[218:221], v150 offset:39936
	global_load_lds_dwordx4 v[228:229], off
	v_lshl_add_u64 v[228:229], s[58:59], 0, v[132:133]
	s_mov_b32 m0, s53
	s_nop 0
	global_load_lds_dwordx4 v[228:229], off
	s_waitcnt vmcnt(8)
	s_waitcnt lgkmcnt(0)
	s_barrier
	s_setprio 1
	s_waitcnt lgkmcnt(0)
	v_mfma_f32_16x16x32_bf16 v[126:129], v[152:155], v[190:193], v[126:129]
	v_mfma_f32_16x16x32_bf16 v[126:129], v[156:159], v[194:197], v[126:129]
	v_mfma_f32_16x16x32_bf16 v[122:125], v[170:173], v[194:197], v[122:125]
	v_mfma_f32_16x16x32_bf16 v[122:125], v[166:169], v[190:193], v[122:125]
	v_mfma_f32_16x16x32_bf16 v[110:113], v[166:169], v[198:201], v[110:113]
	v_mfma_f32_16x16x32_bf16 v[110:113], v[170:173], v[202:205], v[110:113]
	v_mfma_f32_16x16x32_bf16 v[118:121], v[156:159], v[202:205], v[118:121]
	v_mfma_f32_16x16x32_bf16 v[118:121], v[152:155], v[198:201], v[118:121]
	v_mfma_f32_16x16x32_bf16 v[102:105], v[152:155], v[206:209], v[102:105]
	v_mfma_f32_16x16x32_bf16 v[102:105], v[156:159], v[210:213], v[102:105]
	v_mfma_f32_16x16x32_bf16 v[94:97], v[170:173], v[210:213], v[94:97]
	v_mfma_f32_16x16x32_bf16 v[94:97], v[166:169], v[206:209], v[94:97]
	v_mfma_f32_16x16x32_bf16 v[78:81], v[166:169], v[214:217], v[78:81]
	v_mfma_f32_16x16x32_bf16 v[78:81], v[170:173], v[218:221], v[78:81]
	v_mfma_f32_16x16x32_bf16 v[86:89], v[156:159], v[218:221], v[86:89]
	v_mfma_f32_16x16x32_bf16 v[86:89], v[152:155], v[214:217], v[86:89]
	s_setprio 0
	s_setprio 1
	v_mfma_f32_16x16x32_bf16 v[114:117], v[174:177], v[190:193], v[114:117]
	v_mfma_f32_16x16x32_bf16 v[114:117], v[178:181], v[194:197], v[114:117]
	v_mfma_f32_16x16x32_bf16 v[106:109], v[186:189], v[194:197], v[106:109]
	v_mfma_f32_16x16x32_bf16 v[106:109], v[182:185], v[190:193], v[106:109]
	v_mfma_f32_16x16x32_bf16 v[90:93], v[182:185], v[198:201], v[90:93]
	v_mfma_f32_16x16x32_bf16 v[90:93], v[186:189], v[202:205], v[90:93]
	v_mfma_f32_16x16x32_bf16 v[98:101], v[178:181], v[202:205], v[98:101]
	v_mfma_f32_16x16x32_bf16 v[98:101], v[174:177], v[198:201], v[98:101]
	v_mfma_f32_16x16x32_bf16 v[82:85], v[174:177], v[206:209], v[82:85]
	v_mfma_f32_16x16x32_bf16 v[82:85], v[178:181], v[210:213], v[82:85]
	v_mfma_f32_16x16x32_bf16 v[74:77], v[186:189], v[210:213], v[74:77]
	v_mfma_f32_16x16x32_bf16 v[74:77], v[182:185], v[206:209], v[74:77]
	v_mfma_f32_16x16x32_bf16 v[66:69], v[182:185], v[214:217], v[66:69]
	v_mfma_f32_16x16x32_bf16 v[66:69], v[186:189], v[218:221], v[66:69]
	v_mfma_f32_16x16x32_bf16 v[70:73], v[178:181], v[218:221], v[70:73]
	v_mfma_f32_16x16x32_bf16 v[70:73], v[174:177], v[214:217], v[70:73]
	s_setprio 0
	s_barrier
	s_add_i32 s44, s44, s27
	v_lshl_add_u64 v[160:161], v[160:161], 0, s[10:11]
	s_mov_b32 m0, s44
	ds_read_b128 v[190:193], v150 offset:49152
	ds_read_b128 v[194:197], v150 offset:50176
	ds_read_b128 v[198:201], v150 offset:51200
	ds_read_b128 v[202:205], v150 offset:52224
	ds_read_b128 v[206:209], v150 offset:53248
	ds_read_b128 v[210:213], v150 offset:54272
	ds_read_b128 v[214:217], v150 offset:55296
	ds_read_b128 v[218:221], v150 offset:56320
	global_load_lds_dwordx4 v[160:161], off
	s_add_i32 m0, s44, 0x2000
	s_add_u32 s56, s56, 0x100080
	v_lshl_add_u64 v[160:161], v[222:223], 0, s[10:11]
	s_addc_u32 s57, s57, 0
	s_add_i32 s44, s73, s27
	global_load_lds_dwordx4 v[160:161], off
	v_lshl_add_u64 v[160:161], s[56:57], 0, v[134:135]
	s_mov_b32 m0, s44
	s_nop 0
	global_load_lds_dwordx4 v[160:161], off
	v_lshl_add_u64 v[160:161], s[56:57], 0, v[130:131]
	s_add_i32 m0, s44, 0x2000
	s_nop 0
	global_load_lds_dwordx4 v[160:161], off
	v_lshl_add_u64 v[160:161], v[224:225], 0, s[10:11]
	s_mov_b32 m0, s61
	s_nop 0
	global_load_lds_dwordx4 v[160:161], off
	v_lshl_add_u64 v[160:161], v[226:227], 0, s[10:11]
	s_mov_b32 m0, s62
	s_nop 0
	global_load_lds_dwordx4 v[160:161], off
	s_waitcnt vmcnt(8)
	s_waitcnt lgkmcnt(0)
	s_barrier
	s_setprio 1
	s_waitcnt lgkmcnt(0)
	v_mfma_f32_16x16x32_bf16 v[62:65], v[152:155], v[190:193], v[62:65]
	v_mfma_f32_16x16x32_bf16 v[62:65], v[156:159], v[194:197], v[62:65]
	v_mfma_f32_16x16x32_bf16 v[58:61], v[170:173], v[194:197], v[58:61]
	v_mfma_f32_16x16x32_bf16 v[58:61], v[166:169], v[190:193], v[58:61]
	v_mfma_f32_16x16x32_bf16 v[46:49], v[166:169], v[198:201], v[46:49]
	v_mfma_f32_16x16x32_bf16 v[46:49], v[170:173], v[202:205], v[46:49]
	v_mfma_f32_16x16x32_bf16 v[54:57], v[156:159], v[202:205], v[54:57]
	v_mfma_f32_16x16x32_bf16 v[54:57], v[152:155], v[198:201], v[54:57]
	v_mfma_f32_16x16x32_bf16 v[38:41], v[152:155], v[206:209], v[38:41]
	v_mfma_f32_16x16x32_bf16 v[38:41], v[156:159], v[210:213], v[38:41]
	v_mfma_f32_16x16x32_bf16 v[30:33], v[170:173], v[210:213], v[30:33]
	v_mfma_f32_16x16x32_bf16 v[30:33], v[166:169], v[206:209], v[30:33]
	v_mfma_f32_16x16x32_bf16 v[14:17], v[166:169], v[214:217], v[14:17]
	v_mfma_f32_16x16x32_bf16 v[14:17], v[170:173], v[218:221], v[14:17]
	v_mfma_f32_16x16x32_bf16 v[22:25], v[156:159], v[218:221], v[22:25]
	v_mfma_f32_16x16x32_bf16 v[22:25], v[152:155], v[214:217], v[22:25]
	s_setprio 0
	s_setprio 1
	v_mfma_f32_16x16x32_bf16 v[50:53], v[174:177], v[190:193], v[50:53]
	v_mfma_f32_16x16x32_bf16 v[50:53], v[178:181], v[194:197], v[50:53]
	v_mfma_f32_16x16x32_bf16 v[42:45], v[186:189], v[194:197], v[42:45]
	v_mfma_f32_16x16x32_bf16 v[42:45], v[182:185], v[190:193], v[42:45]
	v_mfma_f32_16x16x32_bf16 v[26:29], v[182:185], v[198:201], v[26:29]
	v_mfma_f32_16x16x32_bf16 v[26:29], v[186:189], v[202:205], v[26:29]
	v_mfma_f32_16x16x32_bf16 v[34:37], v[178:181], v[202:205], v[34:37]
	v_mfma_f32_16x16x32_bf16 v[34:37], v[174:177], v[198:201], v[34:37]
	v_mfma_f32_16x16x32_bf16 v[18:21], v[174:177], v[206:209], v[18:21]
	v_mfma_f32_16x16x32_bf16 v[18:21], v[178:181], v[210:213], v[18:21]
	v_mfma_f32_16x16x32_bf16 v[10:13], v[186:189], v[210:213], v[10:13]
	v_mfma_f32_16x16x32_bf16 v[10:13], v[182:185], v[206:209], v[10:13]
	v_mfma_f32_16x16x32_bf16 v[2:5], v[182:185], v[214:217], v[2:5]
	v_mfma_f32_16x16x32_bf16 v[2:5], v[186:189], v[218:221], v[2:5]
	v_mfma_f32_16x16x32_bf16 v[6:9], v[178:181], v[218:221], v[6:9]
	v_mfma_f32_16x16x32_bf16 v[6:9], v[174:177], v[214:217], v[6:9]
	s_setprio 0
	s_barrier
	s_add_i32 s72, s72, 2
	s_add_u32 s54, s54, 0x100
	s_addc_u32 s55, s55, 0
	s_add_u32 s70, s70, 0x100
	s_addc_u32 s71, s71, 0
	s_cmp_gt_u32 s72, 61
	s_cbranch_scc0 .LBB0_472
	s_and_b64 vcc, exec, s[12:13]
	s_cbranch_vccz .LBB0_475
	s_barrier

.LBB0_706:
	s_add_u32 s72, s60, s44
	s_addc_u32 s73, s61, 0
	s_add_u32 s68, s72, 0x100
	s_addc_u32 s69, s73, 0
	s_and_b64 s[66:67], s[64:65], exec
	s_cselect_b32 s69, s17, s69
	s_cselect_b32 s68, s86, s68
	s_add_u32 s44, s56, s44
	s_addc_u32 s66, s57, 0
	s_add_u32 s44, s44, 0x100
	s_addc_u32 s66, s66, 0
	s_and_b64 s[64:65], s[64:65], exec
	s_cselect_b32 s71, s15, s66
	s_cselect_b32 s70, s87, s44
	s_add_u32 s74, s72, 0x10080
	s_addc_u32 s75, s73, 0
	s_add_i32 vcc_hi, s82, s27
	ds_read_b128 v[150:153], v147
	ds_read_b128 v[154:157], v147 offset:1024
	ds_read_b128 v[158:161], v147 offset:2048
	ds_read_b128 v[166:169], v147 offset:3072
	ds_read_b128 v[170:173], v148
	ds_read_b128 v[174:177], v148 offset:1024
	ds_read_b128 v[178:181], v148 offset:2048
	ds_read_b128 v[182:185], v148 offset:3072
	s_add_i32 m0, s36, 0xc000
	s_add_i32 s45, s36, 0xe000
	s_add_i32 s96, vcc_hi, 0x2000
	s_add_u32 s72, s70, 0x10000
	s_addc_u32 s73, s71, 0
	s_add_i32 vcc_lo, s83, s27
	s_add_i32 s97, vcc_lo, 0x2000
	s_add_i32 s95, 0, 0x18000
	s_add_i32 s94, 0, 0x1c000
	s_add_u32 s66, s68, 0x10000
	s_addc_u32 s67, s69, 0
	s_add_i32 s93, s95, s27
	s_add_i32 s89, s93, 0x2000
	s_add_u32 s64, s70, 0x10080
	s_addc_u32 s65, s71, 0
	s_add_i32 s92, s94, s27
	s_add_i32 s44, s92, 0x2000
	v_lshl_add_u64 v[198:199], s[74:75], 0, v[130:131]
	ds_read_b128 v[186:189], v149
	ds_read_b128 v[190:193], v149 offset:1024
	ds_read_b128 v[194:197], v149 offset:2048
	ds_read_b128 v[202:205], v149 offset:3072
	ds_read_b128 v[206:209], v149 offset:4096
	ds_read_b128 v[210:213], v149 offset:5120
	ds_read_b128 v[214:217], v149 offset:6144
	ds_read_b128 v[218:221], v149 offset:7168
	global_load_lds_dwordx4 v[198:199], off
	v_lshl_add_u64 v[198:199], s[74:75], 0, v[134:135]
	s_mov_b32 m0, s45
	s_nop 0
	global_load_lds_dwordx4 v[198:199], off
	s_waitcnt vmcnt(8)
	s_waitcnt lgkmcnt(0)
	s_barrier
	s_setprio 1
	s_waitcnt lgkmcnt(0)
	v_mfma_f32_16x16x32_bf16 v[126:129], v[150:153], v[186:189], v[126:129]
	v_mfma_f32_16x16x32_bf16 v[126:129], v[154:157], v[190:193], v[126:129]
	v_mfma_f32_16x16x32_bf16 v[122:125], v[166:169], v[190:193], v[122:125]
	v_mfma_f32_16x16x32_bf16 v[122:125], v[158:161], v[186:189], v[122:125]
	v_mfma_f32_16x16x32_bf16 v[110:113], v[158:161], v[194:197], v[110:113]
	v_mfma_f32_16x16x32_bf16 v[110:113], v[166:169], v[202:205], v[110:113]
	v_mfma_f32_16x16x32_bf16 v[118:121], v[154:157], v[202:205], v[118:121]
	v_mfma_f32_16x16x32_bf16 v[118:121], v[150:153], v[194:197], v[118:121]
	v_mfma_f32_16x16x32_bf16 v[102:105], v[150:153], v[206:209], v[102:105]
	v_mfma_f32_16x16x32_bf16 v[102:105], v[154:157], v[210:213], v[102:105]
	v_mfma_f32_16x16x32_bf16 v[94:97], v[166:169], v[210:213], v[94:97]
	v_mfma_f32_16x16x32_bf16 v[94:97], v[158:161], v[206:209], v[94:97]
	v_mfma_f32_16x16x32_bf16 v[78:81], v[158:161], v[214:217], v[78:81]
	v_mfma_f32_16x16x32_bf16 v[78:81], v[166:169], v[218:221], v[78:81]
	v_mfma_f32_16x16x32_bf16 v[86:89], v[154:157], v[218:221], v[86:89]
	v_mfma_f32_16x16x32_bf16 v[86:89], v[150:153], v[214:217], v[86:89]
	s_setprio 0
	s_setprio 1
	v_mfma_f32_16x16x32_bf16 v[114:117], v[170:173], v[186:189], v[114:117]
	v_mfma_f32_16x16x32_bf16 v[114:117], v[174:177], v[190:193], v[114:117]
	v_mfma_f32_16x16x32_bf16 v[106:109], v[182:185], v[190:193], v[106:109]
	v_mfma_f32_16x16x32_bf16 v[106:109], v[178:181], v[186:189], v[106:109]
	v_mfma_f32_16x16x32_bf16 v[90:93], v[178:181], v[194:197], v[90:93]
	v_mfma_f32_16x16x32_bf16 v[90:93], v[182:185], v[202:205], v[90:93]
	v_mfma_f32_16x16x32_bf16 v[98:101], v[174:177], v[202:205], v[98:101]
	v_mfma_f32_16x16x32_bf16 v[98:101], v[170:173], v[194:197], v[98:101]
	v_mfma_f32_16x16x32_bf16 v[82:85], v[170:173], v[206:209], v[82:85]
	v_mfma_f32_16x16x32_bf16 v[82:85], v[174:177], v[210:213], v[82:85]
	v_mfma_f32_16x16x32_bf16 v[74:77], v[182:185], v[210:213], v[74:77]
	v_mfma_f32_16x16x32_bf16 v[74:77], v[178:181], v[206:209], v[74:77]
	v_mfma_f32_16x16x32_bf16 v[66:69], v[178:181], v[214:217], v[66:69]
	v_mfma_f32_16x16x32_bf16 v[66:69], v[182:185], v[218:221], v[66:69]
	v_mfma_f32_16x16x32_bf16 v[70:73], v[174:177], v[218:221], v[70:73]
	v_mfma_f32_16x16x32_bf16 v[70:73], v[170:173], v[214:217], v[70:73]
	s_setprio 0
	s_barrier
	s_mov_b32 m0, vcc_hi
	v_lshl_add_u64 v[198:199], s[70:71], 0, v[132:133]
	ds_read_b128 v[186:189], v149 offset:16384
	ds_read_b128 v[190:193], v149 offset:17408
	ds_read_b128 v[194:197], v149 offset:18432
	ds_read_b128 v[202:205], v149 offset:19456
	ds_read_b128 v[206:209], v149 offset:20480
	ds_read_b128 v[210:213], v149 offset:21504
	ds_read_b128 v[214:217], v149 offset:22528
	ds_read_b128 v[218:221], v149 offset:23552
	global_load_lds_dwordx4 v[198:199], off
	v_lshl_add_u64 v[222:223], s[70:71], 0, v[136:137]
	s_mov_b32 m0, s96
	v_lshl_add_u64 v[224:225], s[72:73], 0, v[132:133]
	global_load_lds_dwordx4 v[222:223], off
	s_mov_b32 m0, vcc_lo
	v_lshl_add_u64 v[226:227], s[68:69], 0, v[134:135]
	global_load_lds_dwordx4 v[224:225], off
	v_lshl_add_u64 v[224:225], s[72:73], 0, v[136:137]
	s_mov_b32 m0, s97
	s_nop 0
	global_load_lds_dwordx4 v[224:225], off
	v_lshl_add_u64 v[224:225], s[68:69], 0, v[130:131]
	s_mov_b32 m0, s36
	s_nop 0
	global_load_lds_dwordx4 v[224:225], off
	s_mov_b32 m0, s55
	s_nop 0
	global_load_lds_dwordx4 v[226:227], off
	s_waitcnt vmcnt(8)
	s_waitcnt lgkmcnt(0)
	s_barrier
	s_setprio 1
	s_waitcnt lgkmcnt(0)
	v_mfma_f32_16x16x32_bf16 v[62:65], v[150:153], v[186:189], v[62:65]
	v_mfma_f32_16x16x32_bf16 v[62:65], v[154:157], v[190:193], v[62:65]
	v_mfma_f32_16x16x32_bf16 v[58:61], v[166:169], v[190:193], v[58:61]
	v_mfma_f32_16x16x32_bf16 v[58:61], v[158:161], v[186:189], v[58:61]
	v_mfma_f32_16x16x32_bf16 v[46:49], v[158:161], v[194:197], v[46:49]
	v_mfma_f32_16x16x32_bf16 v[46:49], v[166:169], v[202:205], v[46:49]
	v_mfma_f32_16x16x32_bf16 v[54:57], v[154:157], v[202:205], v[54:57]
	v_mfma_f32_16x16x32_bf16 v[54:57], v[150:153], v[194:197], v[54:57]
	v_mfma_f32_16x16x32_bf16 v[38:41], v[150:153], v[206:209], v[38:41]
	v_mfma_f32_16x16x32_bf16 v[38:41], v[154:157], v[210:213], v[38:41]
	v_mfma_f32_16x16x32_bf16 v[30:33], v[166:169], v[210:213], v[30:33]
	v_mfma_f32_16x16x32_bf16 v[30:33], v[158:161], v[206:209], v[30:33]
	v_mfma_f32_16x16x32_bf16 v[14:17], v[158:161], v[214:217], v[14:17]
	v_mfma_f32_16x16x32_bf16 v[14:17], v[166:169], v[218:221], v[14:17]
	v_mfma_f32_16x16x32_bf16 v[22:25], v[154:157], v[218:221], v[22:25]
	v_mfma_f32_16x16x32_bf16 v[22:25], v[150:153], v[214:217], v[22:25]
	s_setprio 0
	s_setprio 1
	v_mfma_f32_16x16x32_bf16 v[50:53], v[170:173], v[186:189], v[50:53]
	v_mfma_f32_16x16x32_bf16 v[50:53], v[174:177], v[190:193], v[50:53]
	v_mfma_f32_16x16x32_bf16 v[42:45], v[182:185], v[190:193], v[42:45]
	v_mfma_f32_16x16x32_bf16 v[42:45], v[178:181], v[186:189], v[42:45]
	v_mfma_f32_16x16x32_bf16 v[26:29], v[178:181], v[194:197], v[26:29]
	v_mfma_f32_16x16x32_bf16 v[26:29], v[182:185], v[202:205], v[26:29]
	v_mfma_f32_16x16x32_bf16 v[34:37], v[174:177], v[202:205], v[34:37]
	v_mfma_f32_16x16x32_bf16 v[34:37], v[170:173], v[194:197], v[34:37]
	v_mfma_f32_16x16x32_bf16 v[18:21], v[170:173], v[206:209], v[18:21]
	v_mfma_f32_16x16x32_bf16 v[18:21], v[174:177], v[210:213], v[18:21]
	v_mfma_f32_16x16x32_bf16 v[10:13], v[182:185], v[210:213], v[10:13]
	v_mfma_f32_16x16x32_bf16 v[10:13], v[178:181], v[206:209], v[10:13]
	v_mfma_f32_16x16x32_bf16 v[2:5], v[178:181], v[214:217], v[2:5]
	v_mfma_f32_16x16x32_bf16 v[2:5], v[182:185], v[218:221], v[2:5]
	v_mfma_f32_16x16x32_bf16 v[6:9], v[174:177], v[218:221], v[6:9]
	v_mfma_f32_16x16x32_bf16 v[6:9], v[170:173], v[214:217], v[6:9]
	s_setprio 0
	s_barrier
	v_add_u32_e32 v166, s95, v145
	v_add_u32_e32 v182, s94, v145
	ds_read_b128 v[150:153], v166
	ds_read_b128 v[154:157], v166 offset:1024
	ds_read_b128 v[158:161], v166 offset:2048
	ds_read_b128 v[166:169], v166 offset:3072
	ds_read_b128 v[170:173], v182
	ds_read_b128 v[174:177], v182 offset:1024
	ds_read_b128 v[178:181], v182 offset:2048
	ds_read_b128 v[182:185], v182 offset:3072
	s_mov_b32 m0, s76
	v_lshl_add_u64 v[228:229], s[66:67], 0, v[130:131]
	ds_read_b128 v[186:189], v149 offset:32768
	ds_read_b128 v[190:193], v149 offset:33792
	ds_read_b128 v[194:197], v149 offset:34816
	ds_read_b128 v[202:205], v149 offset:35840
	ds_read_b128 v[206:209], v149 offset:36864
	ds_read_b128 v[210:213], v149 offset:37888
	ds_read_b128 v[214:217], v149 offset:38912
	ds_read_b128 v[218:221], v149 offset:39936
	global_load_lds_dwordx4 v[228:229], off
	v_lshl_add_u64 v[228:229], s[66:67], 0, v[134:135]
	s_mov_b32 m0, s77
	s_nop 0
	global_load_lds_dwordx4 v[228:229], off
	s_waitcnt vmcnt(8)
	s_waitcnt lgkmcnt(0)
	s_barrier
	s_setprio 1
	s_waitcnt lgkmcnt(0)
	v_mfma_f32_16x16x32_bf16 v[126:129], v[150:153], v[186:189], v[126:129]
	v_mfma_f32_16x16x32_bf16 v[126:129], v[154:157], v[190:193], v[126:129]
	v_mfma_f32_16x16x32_bf16 v[122:125], v[166:169], v[190:193], v[122:125]
	v_mfma_f32_16x16x32_bf16 v[122:125], v[158:161], v[186:189], v[122:125]
	v_mfma_f32_16x16x32_bf16 v[110:113], v[158:161], v[194:197], v[110:113]
	v_mfma_f32_16x16x32_bf16 v[110:113], v[166:169], v[202:205], v[110:113]
	v_mfma_f32_16x16x32_bf16 v[118:121], v[154:157], v[202:205], v[118:121]
	v_mfma_f32_16x16x32_bf16 v[118:121], v[150:153], v[194:197], v[118:121]
	v_mfma_f32_16x16x32_bf16 v[102:105], v[150:153], v[206:209], v[102:105]
	v_mfma_f32_16x16x32_bf16 v[102:105], v[154:157], v[210:213], v[102:105]
	v_mfma_f32_16x16x32_bf16 v[94:97], v[166:169], v[210:213], v[94:97]
	v_mfma_f32_16x16x32_bf16 v[94:97], v[158:161], v[206:209], v[94:97]
	v_mfma_f32_16x16x32_bf16 v[78:81], v[158:161], v[214:217], v[78:81]
	v_mfma_f32_16x16x32_bf16 v[78:81], v[166:169], v[218:221], v[78:81]
	v_mfma_f32_16x16x32_bf16 v[86:89], v[154:157], v[218:221], v[86:89]
	v_mfma_f32_16x16x32_bf16 v[86:89], v[150:153], v[214:217], v[86:89]
	s_setprio 0
	s_setprio 1
	v_mfma_f32_16x16x32_bf16 v[114:117], v[170:173], v[186:189], v[114:117]
	v_mfma_f32_16x16x32_bf16 v[114:117], v[174:177], v[190:193], v[114:117]
	v_mfma_f32_16x16x32_bf16 v[106:109], v[182:185], v[190:193], v[106:109]
	v_mfma_f32_16x16x32_bf16 v[106:109], v[178:181], v[186:189], v[106:109]
	v_mfma_f32_16x16x32_bf16 v[90:93], v[178:181], v[194:197], v[90:93]
	v_mfma_f32_16x16x32_bf16 v[90:93], v[182:185], v[202:205], v[90:93]
	v_mfma_f32_16x16x32_bf16 v[98:101], v[174:177], v[202:205], v[98:101]
	v_mfma_f32_16x16x32_bf16 v[98:101], v[170:173], v[194:197], v[98:101]
	v_mfma_f32_16x16x32_bf16 v[82:85], v[170:173], v[206:209], v[82:85]
	v_mfma_f32_16x16x32_bf16 v[82:85], v[174:177], v[210:213], v[82:85]
	v_mfma_f32_16x16x32_bf16 v[74:77], v[182:185], v[210:213], v[74:77]
	v_mfma_f32_16x16x32_bf16 v[74:77], v[178:181], v[206:209], v[74:77]
	v_mfma_f32_16x16x32_bf16 v[66:69], v[178:181], v[214:217], v[66:69]
	v_mfma_f32_16x16x32_bf16 v[66:69], v[182:185], v[218:221], v[66:69]
	v_mfma_f32_16x16x32_bf16 v[70:73], v[174:177], v[218:221], v[70:73]
	v_mfma_f32_16x16x32_bf16 v[70:73], v[170:173], v[214:217], v[70:73]
	s_setprio 0
	s_barrier
	s_mov_b32 m0, s93
	v_lshl_add_u64 v[198:199], v[198:199], 0, s[10:11]
	ds_read_b128 v[186:189], v149 offset:49152
	ds_read_b128 v[190:193], v149 offset:50176
	ds_read_b128 v[194:197], v149 offset:51200
	ds_read_b128 v[202:205], v149 offset:52224
	ds_read_b128 v[206:209], v149 offset:53248
	ds_read_b128 v[210:213], v149 offset:54272
	ds_read_b128 v[214:217], v149 offset:55296
	ds_read_b128 v[218:221], v149 offset:56320
	global_load_lds_dwordx4 v[198:199], off
	v_lshl_add_u64 v[198:199], v[222:223], 0, s[10:11]
	s_mov_b32 m0, s89
	s_nop 0
	global_load_lds_dwordx4 v[198:199], off
	v_lshl_add_u64 v[198:199], s[64:65], 0, v[132:133]
	s_mov_b32 m0, s92
	s_nop 0
	global_load_lds_dwordx4 v[198:199], off
	v_lshl_add_u64 v[198:199], s[64:65], 0, v[136:137]
	s_mov_b32 m0, s44
	s_nop 0
	global_load_lds_dwordx4 v[198:199], off
	v_lshl_add_u64 v[198:199], v[224:225], 0, s[10:11]
	s_mov_b32 m0, s79
	s_nop 0
	global_load_lds_dwordx4 v[198:199], off
	v_lshl_add_u64 v[198:199], v[226:227], 0, s[10:11]
	s_mov_b32 m0, s80
	s_nop 0
	global_load_lds_dwordx4 v[198:199], off
	s_waitcnt vmcnt(8)
	s_waitcnt lgkmcnt(0)
	s_barrier
	s_setprio 1
	s_waitcnt lgkmcnt(0)
	v_mfma_f32_16x16x32_bf16 v[62:65], v[150:153], v[186:189], v[62:65]
	v_mfma_f32_16x16x32_bf16 v[62:65], v[154:157], v[190:193], v[62:65]
	v_mfma_f32_16x16x32_bf16 v[58:61], v[166:169], v[190:193], v[58:61]
	v_mfma_f32_16x16x32_bf16 v[58:61], v[158:161], v[186:189], v[58:61]
	v_mfma_f32_16x16x32_bf16 v[46:49], v[158:161], v[194:197], v[46:49]
	v_mfma_f32_16x16x32_bf16 v[46:49], v[166:169], v[202:205], v[46:49]
	v_mfma_f32_16x16x32_bf16 v[54:57], v[154:157], v[202:205], v[54:57]
	v_mfma_f32_16x16x32_bf16 v[54:57], v[150:153], v[194:197], v[54:57]
	v_mfma_f32_16x16x32_bf16 v[38:41], v[150:153], v[206:209], v[38:41]
	v_mfma_f32_16x16x32_bf16 v[38:41], v[154:157], v[210:213], v[38:41]
	v_mfma_f32_16x16x32_bf16 v[30:33], v[166:169], v[210:213], v[30:33]
	v_mfma_f32_16x16x32_bf16 v[30:33], v[158:161], v[206:209], v[30:33]
	v_mfma_f32_16x16x32_bf16 v[14:17], v[158:161], v[214:217], v[14:17]
	v_mfma_f32_16x16x32_bf16 v[14:17], v[166:169], v[218:221], v[14:17]
	v_mfma_f32_16x16x32_bf16 v[22:25], v[154:157], v[218:221], v[22:25]
	v_mfma_f32_16x16x32_bf16 v[22:25], v[150:153], v[214:217], v[22:25]
	s_setprio 0
	s_setprio 1
	v_mfma_f32_16x16x32_bf16 v[50:53], v[170:173], v[186:189], v[50:53]
	v_mfma_f32_16x16x32_bf16 v[50:53], v[174:177], v[190:193], v[50:53]
	v_mfma_f32_16x16x32_bf16 v[42:45], v[182:185], v[190:193], v[42:45]
	v_mfma_f32_16x16x32_bf16 v[42:45], v[178:181], v[186:189], v[42:45]
	v_mfma_f32_16x16x32_bf16 v[26:29], v[178:181], v[194:197], v[26:29]
	v_mfma_f32_16x16x32_bf16 v[26:29], v[182:185], v[202:205], v[26:29]
	v_mfma_f32_16x16x32_bf16 v[34:37], v[174:177], v[202:205], v[34:37]
	v_mfma_f32_16x16x32_bf16 v[34:37], v[170:173], v[194:197], v[34:37]
	v_mfma_f32_16x16x32_bf16 v[18:21], v[170:173], v[206:209], v[18:21]
	v_mfma_f32_16x16x32_bf16 v[18:21], v[174:177], v[210:213], v[18:21]
	v_mfma_f32_16x16x32_bf16 v[10:13], v[182:185], v[210:213], v[10:13]
	v_mfma_f32_16x16x32_bf16 v[10:13], v[178:181], v[206:209], v[10:13]
	v_mfma_f32_16x16x32_bf16 v[2:5], v[178:181], v[214:217], v[2:5]
	v_mfma_f32_16x16x32_bf16 v[2:5], v[182:185], v[218:221], v[2:5]
	v_mfma_f32_16x16x32_bf16 v[6:9], v[174:177], v[218:221], v[6:9]
	v_mfma_f32_16x16x32_bf16 v[6:9], v[170:173], v[214:217], v[6:9]
	s_setprio 0
	s_barrier
	s_movk_i32 s44, 0x100
	s_andn2_b64 vcc, exec, s[62:63]
	s_mov_b64 s[64:65], -1
	s_mov_b64 s[62:63], 0
	s_cbranch_vccz .LBB0_706
	s_and_b64 vcc, exec, s[12:13]
	s_cbranch_vccz .LBB0_709
	s_barrier

.LBB0_722:
	s_add_u32 s36, s56, s44
	s_addc_u32 s37, s57, 0
	s_add_u32 s66, s36, 0x100
	s_addc_u32 s67, s37, 0
	s_and_b64 s[64:65], s[62:63], exec
	s_cselect_b32 s67, s17, s67
	s_cselect_b32 s66, s83, s66
	s_add_u32 s44, s54, s44
	s_addc_u32 s64, s55, 0
	s_add_u32 s44, s44, 0x100
	s_addc_u32 s64, s64, 0
	s_and_b64 s[62:63], s[62:63], exec
	s_cselect_b32 s69, s15, s64
	s_cselect_b32 s68, s84, s44
	s_add_u32 s72, s36, 0x10080
	s_addc_u32 s73, s37, 0
	s_add_i32 s96, s79, s27
	ds_read_b128 v[148:151], v143
	ds_read_b128 v[152:155], v143 offset:1024
	ds_read_b128 v[156:159], v143 offset:2048
	ds_read_b128 v[166:169], v143 offset:3072
	ds_read_b128 v[170:173], v145
	ds_read_b128 v[174:177], v145 offset:1024
	ds_read_b128 v[178:181], v145 offset:2048
	ds_read_b128 v[182:185], v145 offset:3072
	s_add_i32 m0, s43, 0xc000
	s_add_i32 s97, s43, 0xe000
	s_add_i32 s93, s96, 0x2000
	s_add_u32 s70, s68, 0x10000
	s_addc_u32 s71, s69, 0
	s_add_i32 s95, s80, s27
	s_add_i32 s94, s95, 0x2000
	s_add_i32 s92, 0, 0x18000
	s_add_i32 s89, 0, 0x1c000
	s_add_u32 s64, s66, 0x10000
	s_addc_u32 s65, s67, 0
	s_add_i32 s87, s92, s27
	s_add_i32 s85, s87, 0x2000
	s_add_u32 s62, s68, 0x10080
	s_addc_u32 s63, s69, 0
	s_add_i32 s86, s89, s27
	s_add_i32 s44, s86, 0x2000
	v_lshl_add_u64 v[160:161], s[72:73], 0, v[130:131]
	ds_read_b128 v[186:189], v146
	ds_read_b128 v[190:193], v146 offset:1024
	ds_read_b128 v[194:197], v146 offset:2048
	ds_read_b128 v[202:205], v146 offset:3072
	ds_read_b128 v[206:209], v146 offset:4096
	ds_read_b128 v[210:213], v146 offset:5120
	ds_read_b128 v[214:217], v146 offset:6144
	ds_read_b128 v[218:221], v146 offset:7168
	global_load_lds_dwordx4 v[160:161], off
	v_lshl_add_u64 v[160:161], s[72:73], 0, v[134:135]
	s_mov_b32 m0, s97
	s_nop 0
	global_load_lds_dwordx4 v[160:161], off
	s_waitcnt vmcnt(8)
	s_waitcnt lgkmcnt(0)
	s_barrier
	s_setprio 1
	s_waitcnt lgkmcnt(0)
	v_mfma_f32_16x16x32_bf16 v[126:129], v[148:151], v[186:189], v[126:129]
	v_mfma_f32_16x16x32_bf16 v[126:129], v[152:155], v[190:193], v[126:129]
	v_mfma_f32_16x16x32_bf16 v[122:125], v[166:169], v[190:193], v[122:125]
	v_mfma_f32_16x16x32_bf16 v[122:125], v[156:159], v[186:189], v[122:125]
	v_mfma_f32_16x16x32_bf16 v[110:113], v[156:159], v[194:197], v[110:113]
	v_mfma_f32_16x16x32_bf16 v[110:113], v[166:169], v[202:205], v[110:113]
	v_mfma_f32_16x16x32_bf16 v[118:121], v[152:155], v[202:205], v[118:121]
	v_mfma_f32_16x16x32_bf16 v[118:121], v[148:151], v[194:197], v[118:121]
	v_mfma_f32_16x16x32_bf16 v[102:105], v[148:151], v[206:209], v[102:105]
	v_mfma_f32_16x16x32_bf16 v[102:105], v[152:155], v[210:213], v[102:105]
	v_mfma_f32_16x16x32_bf16 v[94:97], v[166:169], v[210:213], v[94:97]
	v_mfma_f32_16x16x32_bf16 v[94:97], v[156:159], v[206:209], v[94:97]
	v_mfma_f32_16x16x32_bf16 v[78:81], v[156:159], v[214:217], v[78:81]
	v_mfma_f32_16x16x32_bf16 v[78:81], v[166:169], v[218:221], v[78:81]
	v_mfma_f32_16x16x32_bf16 v[86:89], v[152:155], v[218:221], v[86:89]
	v_mfma_f32_16x16x32_bf16 v[86:89], v[148:151], v[214:217], v[86:89]
	s_setprio 0
	s_setprio 1
	v_mfma_f32_16x16x32_bf16 v[114:117], v[170:173], v[186:189], v[114:117]
	v_mfma_f32_16x16x32_bf16 v[114:117], v[174:177], v[190:193], v[114:117]
	v_mfma_f32_16x16x32_bf16 v[106:109], v[182:185], v[190:193], v[106:109]
	v_mfma_f32_16x16x32_bf16 v[106:109], v[178:181], v[186:189], v[106:109]
	v_mfma_f32_16x16x32_bf16 v[90:93], v[178:181], v[194:197], v[90:93]
	v_mfma_f32_16x16x32_bf16 v[90:93], v[182:185], v[202:205], v[90:93]
	v_mfma_f32_16x16x32_bf16 v[98:101], v[174:177], v[202:205], v[98:101]
	v_mfma_f32_16x16x32_bf16 v[98:101], v[170:173], v[194:197], v[98:101]
	v_mfma_f32_16x16x32_bf16 v[82:85], v[170:173], v[206:209], v[82:85]
	v_mfma_f32_16x16x32_bf16 v[82:85], v[174:177], v[210:213], v[82:85]
	v_mfma_f32_16x16x32_bf16 v[74:77], v[182:185], v[210:213], v[74:77]
	v_mfma_f32_16x16x32_bf16 v[74:77], v[178:181], v[206:209], v[74:77]
	v_mfma_f32_16x16x32_bf16 v[66:69], v[178:181], v[214:217], v[66:69]
	v_mfma_f32_16x16x32_bf16 v[66:69], v[182:185], v[218:221], v[66:69]
	v_mfma_f32_16x16x32_bf16 v[70:73], v[174:177], v[218:221], v[70:73]
	v_mfma_f32_16x16x32_bf16 v[70:73], v[170:173], v[214:217], v[70:73]
	s_setprio 0
	s_barrier
	s_mov_b32 m0, s96
	v_lshl_add_u64 v[160:161], s[68:69], 0, v[132:133]
	ds_read_b128 v[186:189], v146 offset:16384
	ds_read_b128 v[190:193], v146 offset:17408
	ds_read_b128 v[194:197], v146 offset:18432
	ds_read_b128 v[202:205], v146 offset:19456
	ds_read_b128 v[206:209], v146 offset:20480
	ds_read_b128 v[210:213], v146 offset:21504
	ds_read_b128 v[214:217], v146 offset:22528
	ds_read_b128 v[218:221], v146 offset:23552
	global_load_lds_dwordx4 v[160:161], off
	v_lshl_add_u64 v[198:199], s[68:69], 0, v[136:137]
	s_mov_b32 m0, s93
	v_lshl_add_u64 v[222:223], s[70:71], 0, v[132:133]
	global_load_lds_dwordx4 v[198:199], off
	s_mov_b32 m0, s95
	v_lshl_add_u64 v[224:225], s[66:67], 0, v[134:135]
	global_load_lds_dwordx4 v[222:223], off
	v_lshl_add_u64 v[222:223], s[70:71], 0, v[136:137]
	s_mov_b32 m0, s94
	s_nop 0
	global_load_lds_dwordx4 v[222:223], off
	v_lshl_add_u64 v[222:223], s[66:67], 0, v[130:131]
	s_mov_b32 m0, s43
	s_nop 0
	global_load_lds_dwordx4 v[222:223], off
	s_mov_b32 m0, s45
	s_nop 0
	global_load_lds_dwordx4 v[224:225], off
	s_waitcnt vmcnt(8)
	s_waitcnt lgkmcnt(0)
	s_barrier
	s_setprio 1
	s_waitcnt lgkmcnt(0)
	v_mfma_f32_16x16x32_bf16 v[62:65], v[148:151], v[186:189], v[62:65]
	v_mfma_f32_16x16x32_bf16 v[62:65], v[152:155], v[190:193], v[62:65]
	v_mfma_f32_16x16x32_bf16 v[58:61], v[166:169], v[190:193], v[58:61]
	v_mfma_f32_16x16x32_bf16 v[58:61], v[156:159], v[186:189], v[58:61]
	v_mfma_f32_16x16x32_bf16 v[46:49], v[156:159], v[194:197], v[46:49]
	v_mfma_f32_16x16x32_bf16 v[46:49], v[166:169], v[202:205], v[46:49]
	v_mfma_f32_16x16x32_bf16 v[54:57], v[152:155], v[202:205], v[54:57]
	v_mfma_f32_16x16x32_bf16 v[54:57], v[148:151], v[194:197], v[54:57]
	v_mfma_f32_16x16x32_bf16 v[38:41], v[148:151], v[206:209], v[38:41]
	v_mfma_f32_16x16x32_bf16 v[38:41], v[152:155], v[210:213], v[38:41]
	v_mfma_f32_16x16x32_bf16 v[30:33], v[166:169], v[210:213], v[30:33]
	v_mfma_f32_16x16x32_bf16 v[30:33], v[156:159], v[206:209], v[30:33]
	v_mfma_f32_16x16x32_bf16 v[14:17], v[156:159], v[214:217], v[14:17]
	v_mfma_f32_16x16x32_bf16 v[14:17], v[166:169], v[218:221], v[14:17]
	v_mfma_f32_16x16x32_bf16 v[22:25], v[152:155], v[218:221], v[22:25]
	v_mfma_f32_16x16x32_bf16 v[22:25], v[148:151], v[214:217], v[22:25]
	s_setprio 0
	s_setprio 1
	v_mfma_f32_16x16x32_bf16 v[50:53], v[170:173], v[186:189], v[50:53]
	v_mfma_f32_16x16x32_bf16 v[50:53], v[174:177], v[190:193], v[50:53]
	v_mfma_f32_16x16x32_bf16 v[42:45], v[182:185], v[190:193], v[42:45]
	v_mfma_f32_16x16x32_bf16 v[42:45], v[178:181], v[186:189], v[42:45]
	v_mfma_f32_16x16x32_bf16 v[26:29], v[178:181], v[194:197], v[26:29]
	v_mfma_f32_16x16x32_bf16 v[26:29], v[182:185], v[202:205], v[26:29]
	v_mfma_f32_16x16x32_bf16 v[34:37], v[174:177], v[202:205], v[34:37]
	v_mfma_f32_16x16x32_bf16 v[34:37], v[170:173], v[194:197], v[34:37]
	v_mfma_f32_16x16x32_bf16 v[18:21], v[170:173], v[206:209], v[18:21]
	v_mfma_f32_16x16x32_bf16 v[18:21], v[174:177], v[210:213], v[18:21]
	v_mfma_f32_16x16x32_bf16 v[10:13], v[182:185], v[210:213], v[10:13]
	v_mfma_f32_16x16x32_bf16 v[10:13], v[178:181], v[206:209], v[10:13]
	v_mfma_f32_16x16x32_bf16 v[2:5], v[178:181], v[214:217], v[2:5]
	v_mfma_f32_16x16x32_bf16 v[2:5], v[182:185], v[218:221], v[2:5]
	v_mfma_f32_16x16x32_bf16 v[6:9], v[174:177], v[218:221], v[6:9]
	v_mfma_f32_16x16x32_bf16 v[6:9], v[170:173], v[214:217], v[6:9]
	s_setprio 0
	s_barrier
	v_add_u32_e32 v147, s92, v142
	ds_read_b128 v[148:151], v147
	ds_read_b128 v[152:155], v147 offset:1024
	ds_read_b128 v[156:159], v147 offset:2048
	ds_read_b128 v[166:169], v147 offset:3072
	v_add_u32_e32 v147, s89, v142
	ds_read_b128 v[170:173], v147
	ds_read_b128 v[174:177], v147 offset:1024
	ds_read_b128 v[178:181], v147 offset:2048
	ds_read_b128 v[182:185], v147 offset:3072
	s_mov_b32 m0, s49
	v_lshl_add_u64 v[226:227], s[64:65], 0, v[130:131]
	ds_read_b128 v[186:189], v146 offset:32768
	ds_read_b128 v[190:193], v146 offset:33792
	ds_read_b128 v[194:197], v146 offset:34816
	ds_read_b128 v[202:205], v146 offset:35840
	ds_read_b128 v[206:209], v146 offset:36864
	ds_read_b128 v[210:213], v146 offset:37888
	ds_read_b128 v[214:217], v146 offset:38912
	ds_read_b128 v[218:221], v146 offset:39936
	global_load_lds_dwordx4 v[226:227], off
	v_lshl_add_u64 v[226:227], s[64:65], 0, v[134:135]
	s_mov_b32 m0, s74
	s_nop 0
	global_load_lds_dwordx4 v[226:227], off
	s_waitcnt vmcnt(8)
	s_waitcnt lgkmcnt(0)
	s_barrier
	s_setprio 1
	s_waitcnt lgkmcnt(0)
	v_mfma_f32_16x16x32_bf16 v[126:129], v[148:151], v[186:189], v[126:129]
	v_mfma_f32_16x16x32_bf16 v[126:129], v[152:155], v[190:193], v[126:129]
	v_mfma_f32_16x16x32_bf16 v[122:125], v[166:169], v[190:193], v[122:125]
	v_mfma_f32_16x16x32_bf16 v[122:125], v[156:159], v[186:189], v[122:125]
	v_mfma_f32_16x16x32_bf16 v[110:113], v[156:159], v[194:197], v[110:113]
	v_mfma_f32_16x16x32_bf16 v[110:113], v[166:169], v[202:205], v[110:113]
	v_mfma_f32_16x16x32_bf16 v[118:121], v[152:155], v[202:205], v[118:121]
	v_mfma_f32_16x16x32_bf16 v[118:121], v[148:151], v[194:197], v[118:121]
	v_mfma_f32_16x16x32_bf16 v[102:105], v[148:151], v[206:209], v[102:105]
	v_mfma_f32_16x16x32_bf16 v[102:105], v[152:155], v[210:213], v[102:105]
	v_mfma_f32_16x16x32_bf16 v[94:97], v[166:169], v[210:213], v[94:97]
	v_mfma_f32_16x16x32_bf16 v[94:97], v[156:159], v[206:209], v[94:97]
	v_mfma_f32_16x16x32_bf16 v[78:81], v[156:159], v[214:217], v[78:81]
	v_mfma_f32_16x16x32_bf16 v[78:81], v[166:169], v[218:221], v[78:81]
	v_mfma_f32_16x16x32_bf16 v[86:89], v[152:155], v[218:221], v[86:89]
	v_mfma_f32_16x16x32_bf16 v[86:89], v[148:151], v[214:217], v[86:89]
	s_setprio 0
	s_setprio 1
	v_mfma_f32_16x16x32_bf16 v[114:117], v[170:173], v[186:189], v[114:117]
	v_mfma_f32_16x16x32_bf16 v[114:117], v[174:177], v[190:193], v[114:117]
	v_mfma_f32_16x16x32_bf16 v[106:109], v[182:185], v[190:193], v[106:109]
	v_mfma_f32_16x16x32_bf16 v[106:109], v[178:181], v[186:189], v[106:109]
	v_mfma_f32_16x16x32_bf16 v[90:93], v[178:181], v[194:197], v[90:93]
	v_mfma_f32_16x16x32_bf16 v[90:93], v[182:185], v[202:205], v[90:93]
	v_mfma_f32_16x16x32_bf16 v[98:101], v[174:177], v[202:205], v[98:101]
	v_mfma_f32_16x16x32_bf16 v[98:101], v[170:173], v[194:197], v[98:101]
	v_mfma_f32_16x16x32_bf16 v[82:85], v[170:173], v[206:209], v[82:85]
	v_mfma_f32_16x16x32_bf16 v[82:85], v[174:177], v[210:213], v[82:85]
	v_mfma_f32_16x16x32_bf16 v[74:77], v[182:185], v[210:213], v[74:77]
	v_mfma_f32_16x16x32_bf16 v[74:77], v[178:181], v[206:209], v[74:77]
	v_mfma_f32_16x16x32_bf16 v[66:69], v[178:181], v[214:217], v[66:69]
	v_mfma_f32_16x16x32_bf16 v[66:69], v[182:185], v[218:221], v[66:69]
	v_mfma_f32_16x16x32_bf16 v[70:73], v[174:177], v[218:221], v[70:73]
	v_mfma_f32_16x16x32_bf16 v[70:73], v[170:173], v[214:217], v[70:73]
	s_setprio 0
	s_barrier
	s_mov_b32 m0, s87
	v_lshl_add_u64 v[160:161], v[160:161], 0, s[10:11]
	ds_read_b128 v[186:189], v146 offset:49152
	ds_read_b128 v[190:193], v146 offset:50176
	ds_read_b128 v[194:197], v146 offset:51200
	ds_read_b128 v[202:205], v146 offset:52224
	ds_read_b128 v[206:209], v146 offset:53248
	ds_read_b128 v[210:213], v146 offset:54272
	ds_read_b128 v[214:217], v146 offset:55296
	ds_read_b128 v[218:221], v146 offset:56320
	global_load_lds_dwordx4 v[160:161], off
	v_lshl_add_u64 v[160:161], v[198:199], 0, s[10:11]
	s_mov_b32 m0, s85
	s_nop 0
	global_load_lds_dwordx4 v[160:161], off
	v_lshl_add_u64 v[160:161], s[62:63], 0, v[132:133]
	s_mov_b32 m0, s86
	s_nop 0
	global_load_lds_dwordx4 v[160:161], off
	v_lshl_add_u64 v[160:161], s[62:63], 0, v[136:137]
	s_mov_b32 m0, s44
	s_nop 0
	global_load_lds_dwordx4 v[160:161], off
	v_lshl_add_u64 v[160:161], v[222:223], 0, s[10:11]
	s_mov_b32 m0, s76
	s_nop 0
	global_load_lds_dwordx4 v[160:161], off
	v_lshl_add_u64 v[160:161], v[224:225], 0, s[10:11]
	s_mov_b32 m0, s77
	s_nop 0
	global_load_lds_dwordx4 v[160:161], off
	s_waitcnt vmcnt(8)
	s_waitcnt lgkmcnt(0)
	s_barrier
	s_setprio 1
	s_waitcnt lgkmcnt(0)
	v_mfma_f32_16x16x32_bf16 v[62:65], v[148:151], v[186:189], v[62:65]
	v_mfma_f32_16x16x32_bf16 v[62:65], v[152:155], v[190:193], v[62:65]
	v_mfma_f32_16x16x32_bf16 v[58:61], v[166:169], v[190:193], v[58:61]
	v_mfma_f32_16x16x32_bf16 v[58:61], v[156:159], v[186:189], v[58:61]
	v_mfma_f32_16x16x32_bf16 v[46:49], v[156:159], v[194:197], v[46:49]
	v_mfma_f32_16x16x32_bf16 v[46:49], v[166:169], v[202:205], v[46:49]
	v_mfma_f32_16x16x32_bf16 v[54:57], v[152:155], v[202:205], v[54:57]
	v_mfma_f32_16x16x32_bf16 v[54:57], v[148:151], v[194:197], v[54:57]
	v_mfma_f32_16x16x32_bf16 v[38:41], v[148:151], v[206:209], v[38:41]
	v_mfma_f32_16x16x32_bf16 v[38:41], v[152:155], v[210:213], v[38:41]
	v_mfma_f32_16x16x32_bf16 v[30:33], v[166:169], v[210:213], v[30:33]
	v_mfma_f32_16x16x32_bf16 v[30:33], v[156:159], v[206:209], v[30:33]
	v_mfma_f32_16x16x32_bf16 v[14:17], v[156:159], v[214:217], v[14:17]
	v_mfma_f32_16x16x32_bf16 v[14:17], v[166:169], v[218:221], v[14:17]
	v_mfma_f32_16x16x32_bf16 v[22:25], v[152:155], v[218:221], v[22:25]
	v_mfma_f32_16x16x32_bf16 v[22:25], v[148:151], v[214:217], v[22:25]
	s_setprio 0
	s_setprio 1
	v_mfma_f32_16x16x32_bf16 v[50:53], v[170:173], v[186:189], v[50:53]
	v_mfma_f32_16x16x32_bf16 v[50:53], v[174:177], v[190:193], v[50:53]
	v_mfma_f32_16x16x32_bf16 v[42:45], v[182:185], v[190:193], v[42:45]
	v_mfma_f32_16x16x32_bf16 v[42:45], v[178:181], v[186:189], v[42:45]
	v_mfma_f32_16x16x32_bf16 v[26:29], v[178:181], v[194:197], v[26:29]
	v_mfma_f32_16x16x32_bf16 v[26:29], v[182:185], v[202:205], v[26:29]
	v_mfma_f32_16x16x32_bf16 v[34:37], v[174:177], v[202:205], v[34:37]
	v_mfma_f32_16x16x32_bf16 v[34:37], v[170:173], v[194:197], v[34:37]
	v_mfma_f32_16x16x32_bf16 v[18:21], v[170:173], v[206:209], v[18:21]
	v_mfma_f32_16x16x32_bf16 v[18:21], v[174:177], v[210:213], v[18:21]
	v_mfma_f32_16x16x32_bf16 v[10:13], v[182:185], v[210:213], v[10:13]
	v_mfma_f32_16x16x32_bf16 v[10:13], v[178:181], v[206:209], v[10:13]
	v_mfma_f32_16x16x32_bf16 v[2:5], v[178:181], v[214:217], v[2:5]
	v_mfma_f32_16x16x32_bf16 v[2:5], v[182:185], v[218:221], v[2:5]
	v_mfma_f32_16x16x32_bf16 v[6:9], v[174:177], v[218:221], v[6:9]
	v_mfma_f32_16x16x32_bf16 v[6:9], v[170:173], v[214:217], v[6:9]
	s_setprio 0
	s_barrier
	s_movk_i32 s44, 0x100
	s_andn2_b64 vcc, exec, s[60:61]
	s_mov_b64 s[62:63], -1
	s_mov_b64 s[60:61], 0
	s_cbranch_vccz .LBB0_722
	s_and_b64 vcc, exec, s[12:13]
	s_cbranch_vccz .LBB0_725
	s_barrier

.LBB0_1226:
	v_add_u32_e32 v3, s71, v165
	ds_read_b128 v[150:153], v3
	ds_read_b128 v[154:157], v3 offset:1024
	ds_read_b128 v[158:161], v3 offset:2048
	ds_read_b128 v[170:173], v3 offset:3072
	v_add_u32_e32 v3, s72, v165
	ds_read_b128 v[174:177], v3
	ds_read_b128 v[178:181], v3 offset:1024
	ds_read_b128 v[182:185], v3 offset:2048
	ds_read_b128 v[186:189], v3 offset:3072
	s_add_u32 s36, s52, 0xfff80080
	s_addc_u32 s37, s53, -1
	s_cmp_eq_u32 s78, 28
	s_cselect_b32 s59, s21, s37
	s_cselect_b32 s58, s44, s36
	s_cselect_b32 s57, s19, s77
	s_cselect_b32 s56, s55, s76
	v_lshl_add_u64 v[4:5], s[52:53], 0, v[142:143]
	s_add_i32 m0, s63, 0xc000
	ds_read_b128 v[190:193], v169
	ds_read_b128 v[194:197], v169 offset:1024
	ds_read_b128 v[202:205], v169 offset:2048
	ds_read_b128 v[206:209], v169 offset:3072
	ds_read_b128 v[210:213], v169 offset:4096
	ds_read_b128 v[214:217], v169 offset:5120
	ds_read_b128 v[218:221], v169 offset:6144
	ds_read_b128 v[222:225], v169 offset:7168
	global_load_lds_dwordx4 v[4:5], off
	v_lshl_add_u64 v[4:5], s[52:53], 0, v[144:145]
	s_add_i32 m0, s63, 0xe000
	s_nop 0
	global_load_lds_dwordx4 v[4:5], off
	s_waitcnt vmcnt(8)
	s_waitcnt lgkmcnt(0)
	s_barrier
	s_setprio 1
	s_waitcnt lgkmcnt(0)
	v_mfma_f32_16x16x32_bf16 v[130:133], v[150:153], v[190:193], v[130:133]
	v_mfma_f32_16x16x32_bf16 v[130:133], v[154:157], v[194:197], v[130:133]
	v_mfma_f32_16x16x32_bf16 v[126:129], v[170:173], v[194:197], v[126:129]
	v_mfma_f32_16x16x32_bf16 v[126:129], v[158:161], v[190:193], v[126:129]
	v_mfma_f32_16x16x32_bf16 v[118:121], v[158:161], v[202:205], v[118:121]
	v_mfma_f32_16x16x32_bf16 v[118:121], v[170:173], v[206:209], v[118:121]
	v_mfma_f32_16x16x32_bf16 v[122:125], v[154:157], v[206:209], v[122:125]
	v_mfma_f32_16x16x32_bf16 v[122:125], v[150:153], v[202:205], v[122:125]
	v_mfma_f32_16x16x32_bf16 v[114:117], v[150:153], v[210:213], v[114:117]
	v_mfma_f32_16x16x32_bf16 v[114:117], v[154:157], v[214:217], v[114:117]
	v_mfma_f32_16x16x32_bf16 v[110:113], v[170:173], v[214:217], v[110:113]
	v_mfma_f32_16x16x32_bf16 v[110:113], v[158:161], v[210:213], v[110:113]
	v_mfma_f32_16x16x32_bf16 v[102:105], v[158:161], v[218:221], v[102:105]
	v_mfma_f32_16x16x32_bf16 v[102:105], v[170:173], v[222:225], v[102:105]
	v_mfma_f32_16x16x32_bf16 v[106:109], v[154:157], v[222:225], v[106:109]
	v_mfma_f32_16x16x32_bf16 v[106:109], v[150:153], v[218:221], v[106:109]
	s_setprio 0
	s_setprio 1
	v_mfma_f32_16x16x32_bf16 v[98:101], v[174:177], v[190:193], v[98:101]
	v_mfma_f32_16x16x32_bf16 v[98:101], v[178:181], v[194:197], v[98:101]
	v_mfma_f32_16x16x32_bf16 v[94:97], v[186:189], v[194:197], v[94:97]
	v_mfma_f32_16x16x32_bf16 v[94:97], v[182:185], v[190:193], v[94:97]
	v_mfma_f32_16x16x32_bf16 v[86:89], v[182:185], v[202:205], v[86:89]
	v_mfma_f32_16x16x32_bf16 v[86:89], v[186:189], v[206:209], v[86:89]
	v_mfma_f32_16x16x32_bf16 v[90:93], v[178:181], v[206:209], v[90:93]
	v_mfma_f32_16x16x32_bf16 v[90:93], v[174:177], v[202:205], v[90:93]
	v_mfma_f32_16x16x32_bf16 v[82:85], v[174:177], v[210:213], v[82:85]
	v_mfma_f32_16x16x32_bf16 v[82:85], v[178:181], v[214:217], v[82:85]
	v_mfma_f32_16x16x32_bf16 v[78:81], v[186:189], v[214:217], v[78:81]
	v_mfma_f32_16x16x32_bf16 v[78:81], v[182:185], v[210:213], v[78:81]
	v_mfma_f32_16x16x32_bf16 v[70:73], v[182:185], v[218:221], v[70:73]
	v_mfma_f32_16x16x32_bf16 v[70:73], v[186:189], v[222:225], v[70:73]
	v_mfma_f32_16x16x32_bf16 v[74:77], v[178:181], v[222:225], v[74:77]
	v_mfma_f32_16x16x32_bf16 v[74:77], v[174:177], v[218:221], v[74:77]
	s_setprio 0
	s_barrier
	s_add_i32 s36, s71, s43
	v_lshl_add_u64 v[166:167], s[56:57], 0, v[138:139]
	s_mov_b32 m0, s36
	ds_read_b128 v[190:193], v169 offset:16384
	ds_read_b128 v[194:197], v169 offset:17408
	ds_read_b128 v[202:205], v169 offset:18432
	ds_read_b128 v[206:209], v169 offset:19456
	ds_read_b128 v[210:213], v169 offset:20480
	ds_read_b128 v[214:217], v169 offset:21504
	ds_read_b128 v[218:221], v169 offset:22528
	ds_read_b128 v[222:225], v169 offset:23552
	global_load_lds_dwordx4 v[166:167], off
	s_add_i32 m0, s36, 0x2000
	s_add_u32 s80, s56, 0x80000
	v_lshl_add_u64 v[198:199], s[56:57], 0, v[134:135]
	s_addc_u32 s81, s57, 0
	s_add_i32 s36, s72, s43
	global_load_lds_dwordx4 v[198:199], off
	v_lshl_add_u64 v[4:5], s[80:81], 0, v[138:139]
	s_mov_b32 m0, s36
	v_lshl_add_u64 v[226:227], s[58:59], 0, v[140:141]
	global_load_lds_dwordx4 v[4:5], off
	v_lshl_add_u64 v[4:5], s[80:81], 0, v[134:135]
	s_add_i32 m0, s36, 0x2000
	v_lshl_add_u64 v[228:229], s[58:59], 0, v[136:137]
	global_load_lds_dwordx4 v[4:5], off
	s_mov_b32 m0, s63
	s_nop 0
	global_load_lds_dwordx4 v[226:227], off
	s_mov_b32 m0, s64
	s_nop 0
	global_load_lds_dwordx4 v[228:229], off
	s_waitcnt vmcnt(8)
	s_waitcnt lgkmcnt(0)
	s_barrier
	s_setprio 1
	s_waitcnt lgkmcnt(0)
	v_mfma_f32_16x16x32_bf16 v[66:69], v[150:153], v[190:193], v[66:69]
	v_mfma_f32_16x16x32_bf16 v[66:69], v[154:157], v[194:197], v[66:69]
	v_mfma_f32_16x16x32_bf16 v[62:65], v[170:173], v[194:197], v[62:65]
	v_mfma_f32_16x16x32_bf16 v[62:65], v[158:161], v[190:193], v[62:65]
	v_mfma_f32_16x16x32_bf16 v[54:57], v[158:161], v[202:205], v[54:57]
	v_mfma_f32_16x16x32_bf16 v[54:57], v[170:173], v[206:209], v[54:57]
	v_mfma_f32_16x16x32_bf16 v[58:61], v[154:157], v[206:209], v[58:61]
	v_mfma_f32_16x16x32_bf16 v[58:61], v[150:153], v[202:205], v[58:61]
	v_mfma_f32_16x16x32_bf16 v[50:53], v[150:153], v[210:213], v[50:53]
	v_mfma_f32_16x16x32_bf16 v[50:53], v[154:157], v[214:217], v[50:53]
	v_mfma_f32_16x16x32_bf16 v[46:49], v[170:173], v[214:217], v[46:49]
	v_mfma_f32_16x16x32_bf16 v[46:49], v[158:161], v[210:213], v[46:49]
	v_mfma_f32_16x16x32_bf16 v[38:41], v[158:161], v[218:221], v[38:41]
	v_mfma_f32_16x16x32_bf16 v[38:41], v[170:173], v[222:225], v[38:41]
	v_mfma_f32_16x16x32_bf16 v[42:45], v[154:157], v[222:225], v[42:45]
	v_mfma_f32_16x16x32_bf16 v[42:45], v[150:153], v[218:221], v[42:45]
	s_setprio 0
	s_setprio 1
	v_mfma_f32_16x16x32_bf16 v[34:37], v[174:177], v[190:193], v[34:37]
	v_mfma_f32_16x16x32_bf16 v[30:33], v[182:185], v[190:193], v[30:33]
	v_mfma_f32_16x16x32_bf16 v[26:29], v[174:177], v[202:205], v[26:29]
	v_mfma_f32_16x16x32_bf16 v[22:25], v[182:185], v[202:205], v[22:25]
	v_mfma_f32_16x16x32_bf16 v[18:21], v[174:177], v[210:213], v[18:21]
	v_mfma_f32_16x16x32_bf16 v[14:17], v[182:185], v[210:213], v[14:17]
	v_mfma_f32_16x16x32_bf16 v[10:13], v[174:177], v[218:221], v[10:13]
	v_mfma_f32_16x16x32_bf16 v[4:7], v[182:185], v[218:221], v[6:9]
	v_mfma_f32_16x16x32_bf16 v[34:37], v[178:181], v[194:197], v[34:37]
	v_mfma_f32_16x16x32_bf16 v[30:33], v[186:189], v[194:197], v[30:33]
	v_mfma_f32_16x16x32_bf16 v[26:29], v[178:181], v[206:209], v[26:29]
	v_mfma_f32_16x16x32_bf16 v[22:25], v[186:189], v[206:209], v[22:25]
	v_mfma_f32_16x16x32_bf16 v[18:21], v[178:181], v[214:217], v[18:21]
	v_mfma_f32_16x16x32_bf16 v[14:17], v[186:189], v[214:217], v[14:17]
	v_mfma_f32_16x16x32_bf16 v[10:13], v[178:181], v[222:225], v[10:13]
	v_mfma_f32_16x16x32_bf16 v[4:7], v[186:189], v[222:225], v[4:7]
	s_setprio 0
	s_barrier
	s_add_i32 s36, 0, 0x18000
	v_add_u32_e32 v3, s36, v165
	s_add_i32 s37, 0, 0x1c000
	ds_read_b128 v[150:153], v3
	ds_read_b128 v[154:157], v3 offset:1024
	ds_read_b128 v[158:161], v3 offset:2048
	ds_read_b128 v[170:173], v3 offset:3072
	v_add_u32_e32 v3, s37, v165
	ds_read_b128 v[174:177], v3
	ds_read_b128 v[178:181], v3 offset:1024
	ds_read_b128 v[182:185], v3 offset:2048
	ds_read_b128 v[186:189], v3 offset:3072
	s_add_u32 s58, s58, 0x80000
	s_addc_u32 s59, s59, 0
	s_mov_b32 m0, s65
	v_lshl_add_u64 v[8:9], s[58:59], 0, v[140:141]
	ds_read_b128 v[190:193], v169 offset:32768
	ds_read_b128 v[194:197], v169 offset:33792
	ds_read_b128 v[202:205], v169 offset:34816
	ds_read_b128 v[206:209], v169 offset:35840
	ds_read_b128 v[210:213], v169 offset:36864
	ds_read_b128 v[214:217], v169 offset:37888
	ds_read_b128 v[218:221], v169 offset:38912
	ds_read_b128 v[222:225], v169 offset:39936
	global_load_lds_dwordx4 v[8:9], off
	v_lshl_add_u64 v[8:9], s[58:59], 0, v[136:137]
	s_mov_b32 m0, s66
	s_nop 0
	global_load_lds_dwordx4 v[8:9], off
	s_waitcnt vmcnt(8)
	s_waitcnt lgkmcnt(0)
	s_barrier
	s_setprio 1
	s_waitcnt lgkmcnt(0)
	v_mfma_f32_16x16x32_bf16 v[130:133], v[150:153], v[190:193], v[130:133]
	v_mfma_f32_16x16x32_bf16 v[130:133], v[154:157], v[194:197], v[130:133]
	v_mfma_f32_16x16x32_bf16 v[126:129], v[170:173], v[194:197], v[126:129]
	v_mfma_f32_16x16x32_bf16 v[126:129], v[158:161], v[190:193], v[126:129]
	v_mfma_f32_16x16x32_bf16 v[118:121], v[158:161], v[202:205], v[118:121]
	v_mfma_f32_16x16x32_bf16 v[118:121], v[170:173], v[206:209], v[118:121]
	v_mfma_f32_16x16x32_bf16 v[122:125], v[154:157], v[206:209], v[122:125]
	v_mfma_f32_16x16x32_bf16 v[122:125], v[150:153], v[202:205], v[122:125]
	v_mfma_f32_16x16x32_bf16 v[114:117], v[150:153], v[210:213], v[114:117]
	v_mfma_f32_16x16x32_bf16 v[114:117], v[154:157], v[214:217], v[114:117]
	v_mfma_f32_16x16x32_bf16 v[110:113], v[170:173], v[214:217], v[110:113]
	v_mfma_f32_16x16x32_bf16 v[110:113], v[158:161], v[210:213], v[110:113]
	v_mfma_f32_16x16x32_bf16 v[102:105], v[158:161], v[218:221], v[102:105]
	v_mfma_f32_16x16x32_bf16 v[102:105], v[170:173], v[222:225], v[102:105]
	v_mfma_f32_16x16x32_bf16 v[106:109], v[154:157], v[222:225], v[106:109]
	v_mfma_f32_16x16x32_bf16 v[106:109], v[150:153], v[218:221], v[106:109]
	s_setprio 0
	s_setprio 1
	v_mfma_f32_16x16x32_bf16 v[98:101], v[174:177], v[190:193], v[98:101]
	v_mfma_f32_16x16x32_bf16 v[98:101], v[178:181], v[194:197], v[98:101]
	v_mfma_f32_16x16x32_bf16 v[94:97], v[186:189], v[194:197], v[94:97]
	v_mfma_f32_16x16x32_bf16 v[94:97], v[182:185], v[190:193], v[94:97]
	v_mfma_f32_16x16x32_bf16 v[86:89], v[182:185], v[202:205], v[86:89]
	v_mfma_f32_16x16x32_bf16 v[86:89], v[186:189], v[206:209], v[86:89]
	v_mfma_f32_16x16x32_bf16 v[90:93], v[178:181], v[206:209], v[90:93]
	v_mfma_f32_16x16x32_bf16 v[90:93], v[174:177], v[202:205], v[90:93]
	v_mfma_f32_16x16x32_bf16 v[82:85], v[174:177], v[210:213], v[82:85]
	v_mfma_f32_16x16x32_bf16 v[82:85], v[178:181], v[214:217], v[82:85]
	v_mfma_f32_16x16x32_bf16 v[78:81], v[186:189], v[214:217], v[78:81]
	v_mfma_f32_16x16x32_bf16 v[78:81], v[182:185], v[210:213], v[78:81]
	v_mfma_f32_16x16x32_bf16 v[70:73], v[182:185], v[218:221], v[70:73]
	v_mfma_f32_16x16x32_bf16 v[70:73], v[186:189], v[222:225], v[70:73]
	v_mfma_f32_16x16x32_bf16 v[74:77], v[178:181], v[222:225], v[74:77]
	v_mfma_f32_16x16x32_bf16 v[74:77], v[174:177], v[218:221], v[74:77]
	s_setprio 0
	s_barrier
	s_add_i32 s36, s36, s43
	v_lshl_add_u64 v[8:9], v[166:167], 0, s[10:11]
	s_mov_b32 m0, s36
	ds_read_b128 v[190:193], v169 offset:49152
	ds_read_b128 v[194:197], v169 offset:50176
	ds_read_b128 v[202:205], v169 offset:51200
	ds_read_b128 v[206:209], v169 offset:52224
	ds_read_b128 v[210:213], v169 offset:53248
	ds_read_b128 v[214:217], v169 offset:54272
	ds_read_b128 v[218:221], v169 offset:55296
	ds_read_b128 v[222:225], v169 offset:56320
	global_load_lds_dwordx4 v[8:9], off
	s_add_i32 m0, s36, 0x2000
	s_add_u32 s56, s56, 0x80080
	v_lshl_add_u64 v[8:9], v[198:199], 0, s[10:11]
	s_addc_u32 s57, s57, 0
	s_add_i32 s36, s37, s43
	global_load_lds_dwordx4 v[8:9], off
	v_lshl_add_u64 v[8:9], s[56:57], 0, v[138:139]
	s_mov_b32 m0, s36
	s_nop 0
	global_load_lds_dwordx4 v[8:9], off
	v_lshl_add_u64 v[8:9], s[56:57], 0, v[134:135]
	s_add_i32 m0, s36, 0x2000
	s_nop 0
	global_load_lds_dwordx4 v[8:9], off
	v_lshl_add_u64 v[8:9], v[226:227], 0, s[10:11]
	s_mov_b32 m0, s69
	s_nop 0
	global_load_lds_dwordx4 v[8:9], off
	v_lshl_add_u64 v[8:9], v[228:229], 0, s[10:11]
	s_mov_b32 m0, s70
	s_nop 0
	global_load_lds_dwordx4 v[8:9], off
	s_waitcnt vmcnt(8)
	s_waitcnt lgkmcnt(0)
	s_barrier
	s_setprio 1
	s_waitcnt lgkmcnt(0)
	v_mfma_f32_16x16x32_bf16 v[66:69], v[150:153], v[190:193], v[66:69]
	v_mfma_f32_16x16x32_bf16 v[66:69], v[154:157], v[194:197], v[66:69]
	v_mfma_f32_16x16x32_bf16 v[62:65], v[170:173], v[194:197], v[62:65]
	v_mfma_f32_16x16x32_bf16 v[62:65], v[158:161], v[190:193], v[62:65]
	v_mfma_f32_16x16x32_bf16 v[54:57], v[158:161], v[202:205], v[54:57]
	v_mfma_f32_16x16x32_bf16 v[54:57], v[170:173], v[206:209], v[54:57]
	v_mfma_f32_16x16x32_bf16 v[58:61], v[154:157], v[206:209], v[58:61]
	v_mfma_f32_16x16x32_bf16 v[58:61], v[150:153], v[202:205], v[58:61]
	v_mfma_f32_16x16x32_bf16 v[50:53], v[150:153], v[210:213], v[50:53]
	v_mfma_f32_16x16x32_bf16 v[50:53], v[154:157], v[214:217], v[50:53]
	v_mfma_f32_16x16x32_bf16 v[46:49], v[170:173], v[214:217], v[46:49]
	v_mfma_f32_16x16x32_bf16 v[46:49], v[158:161], v[210:213], v[46:49]
	v_mfma_f32_16x16x32_bf16 v[38:41], v[158:161], v[218:221], v[38:41]
	v_mfma_f32_16x16x32_bf16 v[38:41], v[170:173], v[222:225], v[38:41]
	v_mfma_f32_16x16x32_bf16 v[42:45], v[154:157], v[222:225], v[42:45]
	v_mfma_f32_16x16x32_bf16 v[42:45], v[150:153], v[218:221], v[42:45]
	s_setprio 0
	s_setprio 1
	v_mfma_f32_16x16x32_bf16 v[34:37], v[174:177], v[190:193], v[34:37]
	v_mfma_f32_16x16x32_bf16 v[30:33], v[182:185], v[190:193], v[30:33]
	v_mfma_f32_16x16x32_bf16 v[26:29], v[174:177], v[202:205], v[26:29]
	v_mfma_f32_16x16x32_bf16 v[22:25], v[182:185], v[202:205], v[22:25]
	v_mfma_f32_16x16x32_bf16 v[18:21], v[174:177], v[210:213], v[18:21]
	v_mfma_f32_16x16x32_bf16 v[14:17], v[182:185], v[210:213], v[14:17]
	v_mfma_f32_16x16x32_bf16 v[8:11], v[174:177], v[218:221], v[10:13]
	v_mfma_f32_16x16x32_bf16 v[4:7], v[182:185], v[218:221], v[4:7]
	v_mfma_f32_16x16x32_bf16 v[34:37], v[178:181], v[194:197], v[34:37]
	v_mfma_f32_16x16x32_bf16 v[30:33], v[186:189], v[194:197], v[30:33]
	v_mfma_f32_16x16x32_bf16 v[26:29], v[178:181], v[206:209], v[26:29]
	v_mfma_f32_16x16x32_bf16 v[22:25], v[186:189], v[206:209], v[22:25]
	v_mfma_f32_16x16x32_bf16 v[18:21], v[178:181], v[214:217], v[18:21]
	v_mfma_f32_16x16x32_bf16 v[14:17], v[186:189], v[214:217], v[14:17]
	v_mfma_f32_16x16x32_bf16 v[10:13], v[178:181], v[222:225], v[8:11]
	v_mfma_f32_16x16x32_bf16 v[6:9], v[186:189], v[222:225], v[4:7]
	s_setprio 0
	s_barrier
	s_add_i32 s78, s78, 2
	s_add_u32 s52, s52, 0x100
	s_addc_u32 s53, s53, 0
	s_add_u32 s76, s76, 0x100
	s_addc_u32 s77, s77, 0
	s_cmp_gt_u32 s78, 29
	s_cbranch_scc0 .LBB0_1226
	s_and_b64 vcc, exec, s[12:13]
	s_cbranch_vccz .LBB0_1229
	s_barrier

.LBB0_1397:
	ds_read_b128 v[146:149], v154
	ds_read_b128 v[158:161], v154 offset:1024
	ds_read_b128 v[166:169], v154 offset:2048
	ds_read_b128 v[170:173], v154 offset:3072
	ds_read_b128 v[174:177], v155
	ds_read_b128 v[178:181], v155 offset:1024
	ds_read_b128 v[182:185], v155 offset:2048
	ds_read_b128 v[186:189], v155 offset:3072
	s_add_i32 s93, s44, 2
	s_add_u32 s36, s62, 0xfff00080
	s_addc_u32 s37, s63, -1
	s_cmp_eq_u32 s59, s44
	s_cselect_b32 s67, s38, s37
	s_cselect_b32 s66, s39, s36
	s_cselect_b32 s65, s51, s92
	s_cselect_b32 s64, s53, s61
	v_lshl_add_u64 v[150:151], s[62:63], 0, v[140:141]
	s_add_i32 m0, s72, 0xc000
	ds_read_b128 v[190:193], v156
	ds_read_b128 v[194:197], v156 offset:1024
	ds_read_b128 v[202:205], v156 offset:2048
	ds_read_b128 v[206:209], v156 offset:3072
	ds_read_b128 v[210:213], v156 offset:4096
	ds_read_b128 v[214:217], v156 offset:5120
	ds_read_b128 v[218:221], v156 offset:6144
	ds_read_b128 v[222:225], v156 offset:7168
	global_load_lds_dwordx4 v[150:151], off
	v_lshl_add_u64 v[150:151], s[62:63], 0, v[142:143]
	s_add_i32 m0, s72, 0xe000
	s_nop 0
	global_load_lds_dwordx4 v[150:151], off
	s_waitcnt vmcnt(8)
	s_waitcnt lgkmcnt(0)
	s_barrier
	s_setprio 1
	s_waitcnt lgkmcnt(0)
	v_mfma_f32_16x16x32_bf16 v[126:129], v[146:149], v[190:193], v[126:129]
	v_mfma_f32_16x16x32_bf16 v[126:129], v[158:161], v[194:197], v[126:129]
	v_mfma_f32_16x16x32_bf16 v[122:125], v[170:173], v[194:197], v[122:125]
	v_mfma_f32_16x16x32_bf16 v[122:125], v[166:169], v[190:193], v[122:125]
	v_mfma_f32_16x16x32_bf16 v[106:109], v[166:169], v[202:205], v[106:109]
	v_mfma_f32_16x16x32_bf16 v[106:109], v[170:173], v[206:209], v[106:109]
	v_mfma_f32_16x16x32_bf16 v[110:113], v[158:161], v[206:209], v[110:113]
	v_mfma_f32_16x16x32_bf16 v[110:113], v[146:149], v[202:205], v[110:113]
	v_mfma_f32_16x16x32_bf16 v[94:97], v[146:149], v[210:213], v[94:97]
	v_mfma_f32_16x16x32_bf16 v[94:97], v[158:161], v[214:217], v[94:97]
	v_mfma_f32_16x16x32_bf16 v[90:93], v[170:173], v[214:217], v[90:93]
	v_mfma_f32_16x16x32_bf16 v[90:93], v[166:169], v[210:213], v[90:93]
	v_mfma_f32_16x16x32_bf16 v[74:77], v[166:169], v[218:221], v[74:77]
	v_mfma_f32_16x16x32_bf16 v[74:77], v[170:173], v[222:225], v[74:77]
	v_mfma_f32_16x16x32_bf16 v[78:81], v[158:161], v[222:225], v[78:81]
	v_mfma_f32_16x16x32_bf16 v[78:81], v[146:149], v[218:221], v[78:81]
	s_setprio 0
	s_setprio 1
	v_mfma_f32_16x16x32_bf16 v[118:121], v[174:177], v[190:193], v[118:121]
	v_mfma_f32_16x16x32_bf16 v[118:121], v[178:181], v[194:197], v[118:121]
	v_mfma_f32_16x16x32_bf16 v[114:117], v[186:189], v[194:197], v[114:117]
	v_mfma_f32_16x16x32_bf16 v[114:117], v[182:185], v[190:193], v[114:117]
	v_mfma_f32_16x16x32_bf16 v[98:101], v[182:185], v[202:205], v[98:101]
	v_mfma_f32_16x16x32_bf16 v[98:101], v[186:189], v[206:209], v[98:101]
	v_mfma_f32_16x16x32_bf16 v[102:105], v[178:181], v[206:209], v[102:105]
	v_mfma_f32_16x16x32_bf16 v[102:105], v[174:177], v[202:205], v[102:105]
	v_mfma_f32_16x16x32_bf16 v[86:89], v[174:177], v[210:213], v[86:89]
	v_mfma_f32_16x16x32_bf16 v[86:89], v[178:181], v[214:217], v[86:89]
	v_mfma_f32_16x16x32_bf16 v[82:85], v[186:189], v[214:217], v[82:85]
	v_mfma_f32_16x16x32_bf16 v[82:85], v[182:185], v[210:213], v[82:85]
	v_mfma_f32_16x16x32_bf16 v[66:69], v[182:185], v[218:221], v[66:69]
	v_mfma_f32_16x16x32_bf16 v[66:69], v[186:189], v[222:225], v[66:69]
	v_mfma_f32_16x16x32_bf16 v[70:73], v[178:181], v[222:225], v[70:73]
	v_mfma_f32_16x16x32_bf16 v[70:73], v[174:177], v[218:221], v[70:73]
	s_setprio 0
	s_barrier
	s_add_i32 s36, s82, s69
	v_lshl_add_u64 v[150:151], s[64:65], 0, v[132:133]
	s_mov_b32 m0, s36
	ds_read_b128 v[190:193], v156 offset:16384
	ds_read_b128 v[194:197], v156 offset:17408
	ds_read_b128 v[202:205], v156 offset:18432
	ds_read_b128 v[206:209], v156 offset:19456
	ds_read_b128 v[210:213], v156 offset:20480
	ds_read_b128 v[214:217], v156 offset:21504
	ds_read_b128 v[218:221], v156 offset:22528
	ds_read_b128 v[222:225], v156 offset:23552
	global_load_lds_dwordx4 v[150:151], off
	s_add_i32 m0, s36, 0x2000
	s_add_u32 s94, s64, 0x100000
	v_lshl_add_u64 v[198:199], s[64:65], 0, v[136:137]
	s_addc_u32 s95, s65, 0
	s_add_i32 s36, s83, s69
	global_load_lds_dwordx4 v[198:199], off
	v_lshl_add_u64 v[226:227], s[94:95], 0, v[132:133]
	s_mov_b32 m0, s36
	v_lshl_add_u64 v[228:229], s[66:67], 0, v[134:135]
	global_load_lds_dwordx4 v[226:227], off
	v_lshl_add_u64 v[226:227], s[94:95], 0, v[136:137]
	s_add_i32 m0, s36, 0x2000
	s_nop 0
	global_load_lds_dwordx4 v[226:227], off
	v_lshl_add_u64 v[226:227], s[66:67], 0, v[130:131]
	s_mov_b32 m0, s72
	s_nop 0
	global_load_lds_dwordx4 v[226:227], off
	s_mov_b32 m0, s73
	s_nop 0
	global_load_lds_dwordx4 v[228:229], off
	s_waitcnt vmcnt(8)
	s_waitcnt lgkmcnt(0)
	s_barrier
	s_setprio 1
	s_waitcnt lgkmcnt(0)
	v_mfma_f32_16x16x32_bf16 v[62:65], v[146:149], v[190:193], v[62:65]
	v_mfma_f32_16x16x32_bf16 v[62:65], v[158:161], v[194:197], v[62:65]
	v_mfma_f32_16x16x32_bf16 v[58:61], v[170:173], v[194:197], v[58:61]
	v_mfma_f32_16x16x32_bf16 v[58:61], v[166:169], v[190:193], v[58:61]
	v_mfma_f32_16x16x32_bf16 v[42:45], v[166:169], v[202:205], v[42:45]
	v_mfma_f32_16x16x32_bf16 v[42:45], v[170:173], v[206:209], v[42:45]
	v_mfma_f32_16x16x32_bf16 v[46:49], v[158:161], v[206:209], v[46:49]
	v_mfma_f32_16x16x32_bf16 v[46:49], v[146:149], v[202:205], v[46:49]
	v_mfma_f32_16x16x32_bf16 v[30:33], v[146:149], v[210:213], v[30:33]
	v_mfma_f32_16x16x32_bf16 v[30:33], v[158:161], v[214:217], v[30:33]
	v_mfma_f32_16x16x32_bf16 v[26:29], v[170:173], v[214:217], v[26:29]
	v_mfma_f32_16x16x32_bf16 v[26:29], v[166:169], v[210:213], v[26:29]
	v_mfma_f32_16x16x32_bf16 v[10:13], v[166:169], v[218:221], v[10:13]
	v_mfma_f32_16x16x32_bf16 v[10:13], v[170:173], v[222:225], v[10:13]
	v_mfma_f32_16x16x32_bf16 v[14:17], v[158:161], v[222:225], v[14:17]
	v_mfma_f32_16x16x32_bf16 v[14:17], v[146:149], v[218:221], v[14:17]
	s_setprio 0
	s_setprio 1
	v_mfma_f32_16x16x32_bf16 v[54:57], v[174:177], v[190:193], v[54:57]
	v_mfma_f32_16x16x32_bf16 v[54:57], v[178:181], v[194:197], v[54:57]
	v_mfma_f32_16x16x32_bf16 v[50:53], v[186:189], v[194:197], v[50:53]
	v_mfma_f32_16x16x32_bf16 v[50:53], v[182:185], v[190:193], v[50:53]
	v_mfma_f32_16x16x32_bf16 v[34:37], v[182:185], v[202:205], v[34:37]
	v_mfma_f32_16x16x32_bf16 v[34:37], v[186:189], v[206:209], v[34:37]
	v_mfma_f32_16x16x32_bf16 v[38:41], v[178:181], v[206:209], v[38:41]
	v_mfma_f32_16x16x32_bf16 v[38:41], v[174:177], v[202:205], v[38:41]
	v_mfma_f32_16x16x32_bf16 v[22:25], v[174:177], v[210:213], v[22:25]
	v_mfma_f32_16x16x32_bf16 v[22:25], v[178:181], v[214:217], v[22:25]
	v_mfma_f32_16x16x32_bf16 v[18:21], v[186:189], v[214:217], v[18:21]
	v_mfma_f32_16x16x32_bf16 v[18:21], v[182:185], v[210:213], v[18:21]
	v_mfma_f32_16x16x32_bf16 v[2:5], v[182:185], v[218:221], v[2:5]
	v_mfma_f32_16x16x32_bf16 v[2:5], v[186:189], v[222:225], v[2:5]
	v_mfma_f32_16x16x32_bf16 v[6:9], v[178:181], v[222:225], v[6:9]
	v_mfma_f32_16x16x32_bf16 v[6:9], v[174:177], v[218:221], v[6:9]
	s_setprio 0
	s_barrier
	s_add_i32 s36, 0, 0x18000
	v_add_u32_e32 v138, s36, v152
	s_add_i32 s37, 0, 0x1c000
	ds_read_b128 v[146:149], v138
	ds_read_b128 v[158:161], v138 offset:1024
	ds_read_b128 v[166:169], v138 offset:2048
	ds_read_b128 v[170:173], v138 offset:3072
	v_add_u32_e32 v138, s37, v152
	ds_read_b128 v[174:177], v138
	ds_read_b128 v[178:181], v138 offset:1024
	ds_read_b128 v[182:185], v138 offset:2048
	ds_read_b128 v[186:189], v138 offset:3072
	s_add_u32 s66, s66, 0x100000
	s_addc_u32 s67, s67, 0
	s_mov_b32 m0, s74
	v_lshl_add_u64 v[230:231], s[66:67], 0, v[130:131]
	ds_read_b128 v[190:193], v156 offset:32768
	ds_read_b128 v[194:197], v156 offset:33792
	ds_read_b128 v[202:205], v156 offset:34816
	ds_read_b128 v[206:209], v156 offset:35840
	ds_read_b128 v[210:213], v156 offset:36864
	ds_read_b128 v[214:217], v156 offset:37888
	ds_read_b128 v[218:221], v156 offset:38912
	ds_read_b128 v[222:225], v156 offset:39936
	global_load_lds_dwordx4 v[230:231], off
	v_lshl_add_u64 v[230:231], s[66:67], 0, v[134:135]
	s_mov_b32 m0, s75
	s_nop 0
	global_load_lds_dwordx4 v[230:231], off
	s_waitcnt vmcnt(8)
	s_waitcnt lgkmcnt(0)
	s_barrier
	s_setprio 1
	s_waitcnt lgkmcnt(0)
	v_mfma_f32_16x16x32_bf16 v[126:129], v[146:149], v[190:193], v[126:129]
	v_mfma_f32_16x16x32_bf16 v[126:129], v[158:161], v[194:197], v[126:129]
	v_mfma_f32_16x16x32_bf16 v[122:125], v[170:173], v[194:197], v[122:125]
	v_mfma_f32_16x16x32_bf16 v[122:125], v[166:169], v[190:193], v[122:125]
	v_mfma_f32_16x16x32_bf16 v[106:109], v[166:169], v[202:205], v[106:109]
	v_mfma_f32_16x16x32_bf16 v[106:109], v[170:173], v[206:209], v[106:109]
	v_mfma_f32_16x16x32_bf16 v[110:113], v[158:161], v[206:209], v[110:113]
	v_mfma_f32_16x16x32_bf16 v[110:113], v[146:149], v[202:205], v[110:113]
	v_mfma_f32_16x16x32_bf16 v[94:97], v[146:149], v[210:213], v[94:97]
	v_mfma_f32_16x16x32_bf16 v[94:97], v[158:161], v[214:217], v[94:97]
	v_mfma_f32_16x16x32_bf16 v[90:93], v[170:173], v[214:217], v[90:93]
	v_mfma_f32_16x16x32_bf16 v[90:93], v[166:169], v[210:213], v[90:93]
	v_mfma_f32_16x16x32_bf16 v[74:77], v[166:169], v[218:221], v[74:77]
	v_mfma_f32_16x16x32_bf16 v[74:77], v[170:173], v[222:225], v[74:77]
	v_mfma_f32_16x16x32_bf16 v[78:81], v[158:161], v[222:225], v[78:81]
	v_mfma_f32_16x16x32_bf16 v[78:81], v[146:149], v[218:221], v[78:81]
	s_setprio 0
	s_setprio 1
	v_mfma_f32_16x16x32_bf16 v[118:121], v[174:177], v[190:193], v[118:121]
	v_mfma_f32_16x16x32_bf16 v[118:121], v[178:181], v[194:197], v[118:121]
	v_mfma_f32_16x16x32_bf16 v[114:117], v[186:189], v[194:197], v[114:117]
	v_mfma_f32_16x16x32_bf16 v[114:117], v[182:185], v[190:193], v[114:117]
	v_mfma_f32_16x16x32_bf16 v[98:101], v[182:185], v[202:205], v[98:101]
	v_mfma_f32_16x16x32_bf16 v[98:101], v[186:189], v[206:209], v[98:101]
	v_mfma_f32_16x16x32_bf16 v[102:105], v[178:181], v[206:209], v[102:105]
	v_mfma_f32_16x16x32_bf16 v[102:105], v[174:177], v[202:205], v[102:105]
	v_mfma_f32_16x16x32_bf16 v[86:89], v[174:177], v[210:213], v[86:89]
	v_mfma_f32_16x16x32_bf16 v[86:89], v[178:181], v[214:217], v[86:89]
	v_mfma_f32_16x16x32_bf16 v[82:85], v[186:189], v[214:217], v[82:85]
	v_mfma_f32_16x16x32_bf16 v[82:85], v[182:185], v[210:213], v[82:85]
	v_mfma_f32_16x16x32_bf16 v[66:69], v[182:185], v[218:221], v[66:69]
	v_mfma_f32_16x16x32_bf16 v[66:69], v[186:189], v[222:225], v[66:69]
	v_mfma_f32_16x16x32_bf16 v[70:73], v[178:181], v[222:225], v[70:73]
	v_mfma_f32_16x16x32_bf16 v[70:73], v[174:177], v[218:221], v[70:73]
	s_setprio 0
	s_barrier
	s_add_i32 s36, s36, s69
	v_lshl_add_u64 v[150:151], v[150:151], 0, s[16:17]
	s_mov_b32 m0, s36
	ds_read_b128 v[190:193], v156 offset:49152
	ds_read_b128 v[194:197], v156 offset:50176
	ds_read_b128 v[202:205], v156 offset:51200
	ds_read_b128 v[206:209], v156 offset:52224
	ds_read_b128 v[210:213], v156 offset:53248
	ds_read_b128 v[214:217], v156 offset:54272
	ds_read_b128 v[218:221], v156 offset:55296
	ds_read_b128 v[222:225], v156 offset:56320
	global_load_lds_dwordx4 v[150:151], off
	s_add_i32 m0, s36, 0x2000
	s_add_u32 s64, s64, 0x100080
	v_lshl_add_u64 v[150:151], v[198:199], 0, s[16:17]
	s_addc_u32 s65, s65, 0
	s_add_i32 s36, s37, s69
	global_load_lds_dwordx4 v[150:151], off
	v_lshl_add_u64 v[150:151], s[64:65], 0, v[132:133]
	s_mov_b32 m0, s36
	s_nop 0
	global_load_lds_dwordx4 v[150:151], off
	v_lshl_add_u64 v[150:151], s[64:65], 0, v[136:137]
	s_add_i32 m0, s36, 0x2000
	s_nop 0
	global_load_lds_dwordx4 v[150:151], off
	v_lshl_add_u64 v[150:151], v[226:227], 0, s[16:17]
	s_mov_b32 m0, s78
	s_nop 0
	global_load_lds_dwordx4 v[150:151], off
	v_lshl_add_u64 v[150:151], v[228:229], 0, s[16:17]
	s_mov_b32 m0, s79
	s_nop 0
	global_load_lds_dwordx4 v[150:151], off
	s_waitcnt vmcnt(8)
	s_waitcnt lgkmcnt(0)
	s_barrier
	s_setprio 1
	s_waitcnt lgkmcnt(0)
	v_mfma_f32_16x16x32_bf16 v[62:65], v[146:149], v[190:193], v[62:65]
	v_mfma_f32_16x16x32_bf16 v[62:65], v[158:161], v[194:197], v[62:65]
	v_mfma_f32_16x16x32_bf16 v[58:61], v[170:173], v[194:197], v[58:61]
	v_mfma_f32_16x16x32_bf16 v[58:61], v[166:169], v[190:193], v[58:61]
	v_mfma_f32_16x16x32_bf16 v[42:45], v[166:169], v[202:205], v[42:45]
	v_mfma_f32_16x16x32_bf16 v[42:45], v[170:173], v[206:209], v[42:45]
	v_mfma_f32_16x16x32_bf16 v[46:49], v[158:161], v[206:209], v[46:49]
	v_mfma_f32_16x16x32_bf16 v[46:49], v[146:149], v[202:205], v[46:49]
	v_mfma_f32_16x16x32_bf16 v[30:33], v[146:149], v[210:213], v[30:33]
	v_mfma_f32_16x16x32_bf16 v[30:33], v[158:161], v[214:217], v[30:33]
	v_mfma_f32_16x16x32_bf16 v[26:29], v[170:173], v[214:217], v[26:29]
	v_mfma_f32_16x16x32_bf16 v[26:29], v[166:169], v[210:213], v[26:29]
	v_mfma_f32_16x16x32_bf16 v[10:13], v[166:169], v[218:221], v[10:13]
	v_mfma_f32_16x16x32_bf16 v[10:13], v[170:173], v[222:225], v[10:13]
	v_mfma_f32_16x16x32_bf16 v[14:17], v[158:161], v[222:225], v[14:17]
	v_mfma_f32_16x16x32_bf16 v[14:17], v[146:149], v[218:221], v[14:17]
	s_setprio 0
	s_setprio 1
	v_mfma_f32_16x16x32_bf16 v[54:57], v[174:177], v[190:193], v[54:57]
	v_mfma_f32_16x16x32_bf16 v[54:57], v[178:181], v[194:197], v[54:57]
	v_mfma_f32_16x16x32_bf16 v[50:53], v[186:189], v[194:197], v[50:53]
	v_mfma_f32_16x16x32_bf16 v[50:53], v[182:185], v[190:193], v[50:53]
	v_mfma_f32_16x16x32_bf16 v[34:37], v[182:185], v[202:205], v[34:37]
	v_mfma_f32_16x16x32_bf16 v[34:37], v[186:189], v[206:209], v[34:37]
	v_mfma_f32_16x16x32_bf16 v[38:41], v[178:181], v[206:209], v[38:41]
	v_mfma_f32_16x16x32_bf16 v[38:41], v[174:177], v[202:205], v[38:41]
	v_mfma_f32_16x16x32_bf16 v[22:25], v[174:177], v[210:213], v[22:25]
	v_mfma_f32_16x16x32_bf16 v[22:25], v[178:181], v[214:217], v[22:25]
	v_mfma_f32_16x16x32_bf16 v[18:21], v[186:189], v[214:217], v[18:21]
	v_mfma_f32_16x16x32_bf16 v[18:21], v[182:185], v[210:213], v[18:21]
	v_mfma_f32_16x16x32_bf16 v[2:5], v[182:185], v[218:221], v[2:5]
	v_mfma_f32_16x16x32_bf16 v[2:5], v[186:189], v[222:225], v[2:5]
	v_mfma_f32_16x16x32_bf16 v[6:9], v[178:181], v[222:225], v[6:9]
	v_mfma_f32_16x16x32_bf16 v[6:9], v[174:177], v[218:221], v[6:9]
	s_setprio 0
	s_barrier
	s_add_u32 s62, s62, 0x100
	s_addc_u32 s63, s63, 0
	s_add_u32 s61, s61, 0x100
	s_addc_u32 s92, s92, 0
	s_cmp_ge_i32 s93, s11
	s_mov_b32 s44, s93
	s_cbranch_scc0 .LBB0_1397
	s_and_b64 vcc, exec, s[18:19]
	s_cbranch_vccz .LBB0_1400

.LBB0_1631:
	ds_read_b128 v[166:169], v158
	ds_read_b128 v[170:173], v158 offset:1024
	ds_read_b128 v[174:177], v158 offset:2048
	ds_read_b128 v[178:181], v158 offset:3072
	ds_read_b128 v[182:185], v159
	ds_read_b128 v[186:189], v159 offset:1024
	ds_read_b128 v[190:193], v159 offset:2048
	ds_read_b128 v[194:197], v159 offset:3072
	s_add_u32 s36, s54, 0xfff00080
	s_addc_u32 s37, s55, -1
	s_cmp_eq_u32 s78, 60
	s_cselect_b32 s59, s21, s37
	s_cselect_b32 s58, s74, s36
	s_cselect_b32 s57, s19, s77
	s_cselect_b32 s56, s75, s76
	v_lshl_add_u64 v[198:199], s[54:55], 0, v[140:141]
	s_add_i32 m0, s53, 0xc000
	ds_read_b128 v[202:205], v160
	ds_read_b128 v[206:209], v160 offset:1024
	ds_read_b128 v[210:213], v160 offset:2048
	ds_read_b128 v[214:217], v160 offset:3072
	ds_read_b128 v[218:221], v160 offset:4096
	ds_read_b128 v[222:225], v160 offset:5120
	ds_read_b128 v[226:229], v160 offset:6144
	ds_read_b128 v[230:233], v160 offset:7168
	global_load_lds_dwordx4 v[198:199], off
	v_lshl_add_u64 v[198:199], s[54:55], 0, v[142:143]
	s_add_i32 m0, s53, 0xe000
	s_nop 0
	global_load_lds_dwordx4 v[198:199], off
	s_waitcnt vmcnt(8)
	s_waitcnt lgkmcnt(0)
	s_barrier
	s_setprio 1
	s_waitcnt lgkmcnt(0)
	v_mfma_f32_16x16x32_bf16 v[126:129], v[166:169], v[202:205], v[126:129]
	v_mfma_f32_16x16x32_bf16 v[126:129], v[170:173], v[206:209], v[126:129]
	v_mfma_f32_16x16x32_bf16 v[122:125], v[178:181], v[206:209], v[122:125]
	v_mfma_f32_16x16x32_bf16 v[122:125], v[174:177], v[202:205], v[122:125]
	v_mfma_f32_16x16x32_bf16 v[110:113], v[174:177], v[210:213], v[110:113]
	v_mfma_f32_16x16x32_bf16 v[110:113], v[178:181], v[214:217], v[110:113]
	v_mfma_f32_16x16x32_bf16 v[118:121], v[170:173], v[214:217], v[118:121]
	v_mfma_f32_16x16x32_bf16 v[118:121], v[166:169], v[210:213], v[118:121]
	v_mfma_f32_16x16x32_bf16 v[102:105], v[166:169], v[218:221], v[102:105]
	v_mfma_f32_16x16x32_bf16 v[102:105], v[170:173], v[222:225], v[102:105]
	v_mfma_f32_16x16x32_bf16 v[94:97], v[178:181], v[222:225], v[94:97]
	v_mfma_f32_16x16x32_bf16 v[94:97], v[174:177], v[218:221], v[94:97]
	v_mfma_f32_16x16x32_bf16 v[78:81], v[174:177], v[226:229], v[78:81]
	v_mfma_f32_16x16x32_bf16 v[78:81], v[178:181], v[230:233], v[78:81]
	v_mfma_f32_16x16x32_bf16 v[86:89], v[170:173], v[230:233], v[86:89]
	v_mfma_f32_16x16x32_bf16 v[86:89], v[166:169], v[226:229], v[86:89]
	s_setprio 0
	s_setprio 1
	v_mfma_f32_16x16x32_bf16 v[114:117], v[182:185], v[202:205], v[114:117]
	v_mfma_f32_16x16x32_bf16 v[114:117], v[186:189], v[206:209], v[114:117]
	v_mfma_f32_16x16x32_bf16 v[106:109], v[194:197], v[206:209], v[106:109]
	v_mfma_f32_16x16x32_bf16 v[106:109], v[190:193], v[202:205], v[106:109]
	v_mfma_f32_16x16x32_bf16 v[90:93], v[190:193], v[210:213], v[90:93]
	v_mfma_f32_16x16x32_bf16 v[90:93], v[194:197], v[214:217], v[90:93]
	v_mfma_f32_16x16x32_bf16 v[98:101], v[186:189], v[214:217], v[98:101]
	v_mfma_f32_16x16x32_bf16 v[98:101], v[182:185], v[210:213], v[98:101]
	v_mfma_f32_16x16x32_bf16 v[82:85], v[182:185], v[218:221], v[82:85]
	v_mfma_f32_16x16x32_bf16 v[82:85], v[186:189], v[222:225], v[82:85]
	v_mfma_f32_16x16x32_bf16 v[74:77], v[194:197], v[222:225], v[74:77]
	v_mfma_f32_16x16x32_bf16 v[74:77], v[190:193], v[218:221], v[74:77]
	v_mfma_f32_16x16x32_bf16 v[66:69], v[190:193], v[226:229], v[66:69]
	v_mfma_f32_16x16x32_bf16 v[66:69], v[194:197], v[230:233], v[66:69]
	v_mfma_f32_16x16x32_bf16 v[70:73], v[186:189], v[230:233], v[70:73]
	v_mfma_f32_16x16x32_bf16 v[70:73], v[182:185], v[226:229], v[70:73]
	s_setprio 0
	s_barrier
	s_add_i32 s36, s68, s38
	v_lshl_add_u64 v[198:199], s[56:57], 0, v[136:137]
	s_mov_b32 m0, s36
	ds_read_b128 v[202:205], v160 offset:16384
	ds_read_b128 v[206:209], v160 offset:17408
	ds_read_b128 v[210:213], v160 offset:18432
	ds_read_b128 v[214:217], v160 offset:19456
	ds_read_b128 v[218:221], v160 offset:20480
	ds_read_b128 v[222:225], v160 offset:21504
	ds_read_b128 v[226:229], v160 offset:22528
	ds_read_b128 v[230:233], v160 offset:23552
	global_load_lds_dwordx4 v[198:199], off
	s_add_i32 m0, s36, 0x2000
	s_add_u32 s80, s56, 0x100000
	v_lshl_add_u64 v[234:235], s[56:57], 0, v[132:133]
	s_addc_u32 s81, s57, 0
	s_add_i32 s36, s69, s38
	global_load_lds_dwordx4 v[234:235], off
	v_lshl_add_u64 v[236:237], s[80:81], 0, v[136:137]
	s_mov_b32 m0, s36
	v_lshl_add_u64 v[238:239], s[58:59], 0, v[134:135]
	global_load_lds_dwordx4 v[236:237], off
	v_lshl_add_u64 v[236:237], s[80:81], 0, v[132:133]
	s_add_i32 m0, s36, 0x2000
	s_nop 0
	global_load_lds_dwordx4 v[236:237], off
	v_lshl_add_u64 v[236:237], s[58:59], 0, v[138:139]
	s_mov_b32 m0, s53
	s_nop 0
	global_load_lds_dwordx4 v[236:237], off
	s_mov_b32 m0, s61
	s_nop 0
	global_load_lds_dwordx4 v[238:239], off
	s_waitcnt vmcnt(8)
	s_waitcnt lgkmcnt(0)
	s_barrier
	s_setprio 1
	s_waitcnt lgkmcnt(0)
	v_mfma_f32_16x16x32_bf16 v[62:65], v[166:169], v[202:205], v[62:65]
	v_mfma_f32_16x16x32_bf16 v[62:65], v[170:173], v[206:209], v[62:65]
	v_mfma_f32_16x16x32_bf16 v[58:61], v[178:181], v[206:209], v[58:61]
	v_mfma_f32_16x16x32_bf16 v[58:61], v[174:177], v[202:205], v[58:61]
	v_mfma_f32_16x16x32_bf16 v[46:49], v[174:177], v[210:213], v[46:49]
	v_mfma_f32_16x16x32_bf16 v[46:49], v[178:181], v[214:217], v[46:49]
	v_mfma_f32_16x16x32_bf16 v[54:57], v[170:173], v[214:217], v[54:57]
	v_mfma_f32_16x16x32_bf16 v[54:57], v[166:169], v[210:213], v[54:57]
	v_mfma_f32_16x16x32_bf16 v[38:41], v[166:169], v[218:221], v[38:41]
	v_mfma_f32_16x16x32_bf16 v[38:41], v[170:173], v[222:225], v[38:41]
	v_mfma_f32_16x16x32_bf16 v[30:33], v[178:181], v[222:225], v[30:33]
	v_mfma_f32_16x16x32_bf16 v[30:33], v[174:177], v[218:221], v[30:33]
	v_mfma_f32_16x16x32_bf16 v[14:17], v[174:177], v[226:229], v[14:17]
	v_mfma_f32_16x16x32_bf16 v[14:17], v[178:181], v[230:233], v[14:17]
	v_mfma_f32_16x16x32_bf16 v[22:25], v[170:173], v[230:233], v[22:25]
	v_mfma_f32_16x16x32_bf16 v[22:25], v[166:169], v[226:229], v[22:25]
	s_setprio 0
	s_setprio 1
	v_mfma_f32_16x16x32_bf16 v[50:53], v[182:185], v[202:205], v[50:53]
	v_mfma_f32_16x16x32_bf16 v[50:53], v[186:189], v[206:209], v[50:53]
	v_mfma_f32_16x16x32_bf16 v[42:45], v[194:197], v[206:209], v[42:45]
	v_mfma_f32_16x16x32_bf16 v[42:45], v[190:193], v[202:205], v[42:45]
	v_mfma_f32_16x16x32_bf16 v[26:29], v[190:193], v[210:213], v[26:29]
	v_mfma_f32_16x16x32_bf16 v[26:29], v[194:197], v[214:217], v[26:29]
	v_mfma_f32_16x16x32_bf16 v[34:37], v[186:189], v[214:217], v[34:37]
	v_mfma_f32_16x16x32_bf16 v[34:37], v[182:185], v[210:213], v[34:37]
	v_mfma_f32_16x16x32_bf16 v[18:21], v[182:185], v[218:221], v[18:21]
	v_mfma_f32_16x16x32_bf16 v[18:21], v[186:189], v[222:225], v[18:21]
	v_mfma_f32_16x16x32_bf16 v[10:13], v[194:197], v[222:225], v[10:13]
	v_mfma_f32_16x16x32_bf16 v[10:13], v[190:193], v[218:221], v[10:13]
	v_mfma_f32_16x16x32_bf16 v[2:5], v[190:193], v[226:229], v[2:5]
	v_mfma_f32_16x16x32_bf16 v[2:5], v[194:197], v[230:233], v[2:5]
	v_mfma_f32_16x16x32_bf16 v[6:9], v[186:189], v[230:233], v[6:9]
	v_mfma_f32_16x16x32_bf16 v[6:9], v[182:185], v[226:229], v[6:9]
	s_setprio 0
	s_barrier
	s_add_i32 s36, 0, 0x18000
	v_add_u32_e32 v161, s36, v156
	s_add_i32 s37, 0, 0x1c000
	ds_read_b128 v[166:169], v161
	ds_read_b128 v[170:173], v161 offset:1024
	ds_read_b128 v[174:177], v161 offset:2048
	ds_read_b128 v[178:181], v161 offset:3072
	v_add_u32_e32 v161, s37, v156
	ds_read_b128 v[182:185], v161
	ds_read_b128 v[186:189], v161 offset:1024
	ds_read_b128 v[190:193], v161 offset:2048
	ds_read_b128 v[194:197], v161 offset:3072
	s_add_u32 s58, s58, 0x100000
	s_addc_u32 s59, s59, 0
	s_mov_b32 m0, s62
	v_lshl_add_u64 v[240:241], s[58:59], 0, v[138:139]
	ds_read_b128 v[202:205], v160 offset:32768
	ds_read_b128 v[206:209], v160 offset:33792
	ds_read_b128 v[210:213], v160 offset:34816
	ds_read_b128 v[214:217], v160 offset:35840
	ds_read_b128 v[218:221], v160 offset:36864
	ds_read_b128 v[222:225], v160 offset:37888
	ds_read_b128 v[226:229], v160 offset:38912
	ds_read_b128 v[230:233], v160 offset:39936
	global_load_lds_dwordx4 v[240:241], off
	v_lshl_add_u64 v[240:241], s[58:59], 0, v[134:135]
	s_mov_b32 m0, s63
	s_nop 0
	global_load_lds_dwordx4 v[240:241], off
	s_waitcnt vmcnt(8)
	s_waitcnt lgkmcnt(0)
	s_barrier
	s_setprio 1
	s_waitcnt lgkmcnt(0)
	v_mfma_f32_16x16x32_bf16 v[126:129], v[166:169], v[202:205], v[126:129]
	v_mfma_f32_16x16x32_bf16 v[126:129], v[170:173], v[206:209], v[126:129]
	v_mfma_f32_16x16x32_bf16 v[122:125], v[178:181], v[206:209], v[122:125]
	v_mfma_f32_16x16x32_bf16 v[122:125], v[174:177], v[202:205], v[122:125]
	v_mfma_f32_16x16x32_bf16 v[110:113], v[174:177], v[210:213], v[110:113]
	v_mfma_f32_16x16x32_bf16 v[110:113], v[178:181], v[214:217], v[110:113]
	v_mfma_f32_16x16x32_bf16 v[118:121], v[170:173], v[214:217], v[118:121]
	v_mfma_f32_16x16x32_bf16 v[118:121], v[166:169], v[210:213], v[118:121]
	v_mfma_f32_16x16x32_bf16 v[102:105], v[166:169], v[218:221], v[102:105]
	v_mfma_f32_16x16x32_bf16 v[102:105], v[170:173], v[222:225], v[102:105]
	v_mfma_f32_16x16x32_bf16 v[94:97], v[178:181], v[222:225], v[94:97]
	v_mfma_f32_16x16x32_bf16 v[94:97], v[174:177], v[218:221], v[94:97]
	v_mfma_f32_16x16x32_bf16 v[78:81], v[174:177], v[226:229], v[78:81]
	v_mfma_f32_16x16x32_bf16 v[78:81], v[178:181], v[230:233], v[78:81]
	v_mfma_f32_16x16x32_bf16 v[86:89], v[170:173], v[230:233], v[86:89]
	v_mfma_f32_16x16x32_bf16 v[86:89], v[166:169], v[226:229], v[86:89]
	s_setprio 0
	s_setprio 1
	v_mfma_f32_16x16x32_bf16 v[114:117], v[182:185], v[202:205], v[114:117]
	v_mfma_f32_16x16x32_bf16 v[114:117], v[186:189], v[206:209], v[114:117]
	v_mfma_f32_16x16x32_bf16 v[106:109], v[194:197], v[206:209], v[106:109]
	v_mfma_f32_16x16x32_bf16 v[106:109], v[190:193], v[202:205], v[106:109]
	v_mfma_f32_16x16x32_bf16 v[90:93], v[190:193], v[210:213], v[90:93]
	v_mfma_f32_16x16x32_bf16 v[90:93], v[194:197], v[214:217], v[90:93]
	v_mfma_f32_16x16x32_bf16 v[98:101], v[186:189], v[214:217], v[98:101]
	v_mfma_f32_16x16x32_bf16 v[98:101], v[182:185], v[210:213], v[98:101]
	v_mfma_f32_16x16x32_bf16 v[82:85], v[182:185], v[218:221], v[82:85]
	v_mfma_f32_16x16x32_bf16 v[82:85], v[186:189], v[222:225], v[82:85]
	v_mfma_f32_16x16x32_bf16 v[74:77], v[194:197], v[222:225], v[74:77]
	v_mfma_f32_16x16x32_bf16 v[74:77], v[190:193], v[218:221], v[74:77]
	v_mfma_f32_16x16x32_bf16 v[66:69], v[190:193], v[226:229], v[66:69]
	v_mfma_f32_16x16x32_bf16 v[66:69], v[194:197], v[230:233], v[66:69]
	v_mfma_f32_16x16x32_bf16 v[70:73], v[186:189], v[230:233], v[70:73]
	v_mfma_f32_16x16x32_bf16 v[70:73], v[182:185], v[226:229], v[70:73]
	s_setprio 0
	s_barrier
	s_add_i32 s36, s36, s38
	v_lshl_add_u64 v[198:199], v[198:199], 0, s[14:15]
	s_mov_b32 m0, s36
	ds_read_b128 v[202:205], v160 offset:49152
	ds_read_b128 v[206:209], v160 offset:50176
	ds_read_b128 v[210:213], v160 offset:51200
	ds_read_b128 v[214:217], v160 offset:52224
	ds_read_b128 v[218:221], v160 offset:53248
	ds_read_b128 v[222:225], v160 offset:54272
	ds_read_b128 v[226:229], v160 offset:55296
	ds_read_b128 v[230:233], v160 offset:56320
	global_load_lds_dwordx4 v[198:199], off
	s_add_i32 m0, s36, 0x2000
	s_add_u32 s56, s56, 0x100080
	v_lshl_add_u64 v[198:199], v[234:235], 0, s[14:15]
	s_addc_u32 s57, s57, 0
	s_add_i32 s36, s37, s38
	global_load_lds_dwordx4 v[198:199], off
	v_lshl_add_u64 v[198:199], s[56:57], 0, v[136:137]
	s_mov_b32 m0, s36
	s_nop 0
	global_load_lds_dwordx4 v[198:199], off
	v_lshl_add_u64 v[198:199], s[56:57], 0, v[132:133]
	s_add_i32 m0, s36, 0x2000
	s_nop 0
	global_load_lds_dwordx4 v[198:199], off
	v_lshl_add_u64 v[198:199], v[236:237], 0, s[14:15]
	s_mov_b32 m0, s65
	s_nop 0
	global_load_lds_dwordx4 v[198:199], off
	v_lshl_add_u64 v[198:199], v[238:239], 0, s[14:15]
	s_mov_b32 m0, s66
	s_nop 0
	global_load_lds_dwordx4 v[198:199], off
	s_waitcnt vmcnt(8)
	s_waitcnt lgkmcnt(0)
	s_barrier
	s_setprio 1
	s_waitcnt lgkmcnt(0)
	v_mfma_f32_16x16x32_bf16 v[62:65], v[166:169], v[202:205], v[62:65]
	v_mfma_f32_16x16x32_bf16 v[62:65], v[170:173], v[206:209], v[62:65]
	v_mfma_f32_16x16x32_bf16 v[58:61], v[178:181], v[206:209], v[58:61]
	v_mfma_f32_16x16x32_bf16 v[58:61], v[174:177], v[202:205], v[58:61]
	v_mfma_f32_16x16x32_bf16 v[46:49], v[174:177], v[210:213], v[46:49]
	v_mfma_f32_16x16x32_bf16 v[46:49], v[178:181], v[214:217], v[46:49]
	v_mfma_f32_16x16x32_bf16 v[54:57], v[170:173], v[214:217], v[54:57]
	v_mfma_f32_16x16x32_bf16 v[54:57], v[166:169], v[210:213], v[54:57]
	v_mfma_f32_16x16x32_bf16 v[38:41], v[166:169], v[218:221], v[38:41]
	v_mfma_f32_16x16x32_bf16 v[38:41], v[170:173], v[222:225], v[38:41]
	v_mfma_f32_16x16x32_bf16 v[30:33], v[178:181], v[222:225], v[30:33]
	v_mfma_f32_16x16x32_bf16 v[30:33], v[174:177], v[218:221], v[30:33]
	v_mfma_f32_16x16x32_bf16 v[14:17], v[174:177], v[226:229], v[14:17]
	v_mfma_f32_16x16x32_bf16 v[14:17], v[178:181], v[230:233], v[14:17]
	v_mfma_f32_16x16x32_bf16 v[22:25], v[170:173], v[230:233], v[22:25]
	v_mfma_f32_16x16x32_bf16 v[22:25], v[166:169], v[226:229], v[22:25]
	s_setprio 0
	s_setprio 1
	v_mfma_f32_16x16x32_bf16 v[50:53], v[182:185], v[202:205], v[50:53]
	v_mfma_f32_16x16x32_bf16 v[50:53], v[186:189], v[206:209], v[50:53]
	v_mfma_f32_16x16x32_bf16 v[42:45], v[194:197], v[206:209], v[42:45]
	v_mfma_f32_16x16x32_bf16 v[42:45], v[190:193], v[202:205], v[42:45]
	v_mfma_f32_16x16x32_bf16 v[26:29], v[190:193], v[210:213], v[26:29]
	v_mfma_f32_16x16x32_bf16 v[26:29], v[194:197], v[214:217], v[26:29]
	v_mfma_f32_16x16x32_bf16 v[34:37], v[186:189], v[214:217], v[34:37]
	v_mfma_f32_16x16x32_bf16 v[34:37], v[182:185], v[210:213], v[34:37]
	v_mfma_f32_16x16x32_bf16 v[18:21], v[182:185], v[218:221], v[18:21]
	v_mfma_f32_16x16x32_bf16 v[18:21], v[186:189], v[222:225], v[18:21]
	v_mfma_f32_16x16x32_bf16 v[10:13], v[194:197], v[222:225], v[10:13]
	v_mfma_f32_16x16x32_bf16 v[10:13], v[190:193], v[218:221], v[10:13]
	v_mfma_f32_16x16x32_bf16 v[2:5], v[190:193], v[226:229], v[2:5]
	v_mfma_f32_16x16x32_bf16 v[2:5], v[194:197], v[230:233], v[2:5]
	v_mfma_f32_16x16x32_bf16 v[6:9], v[186:189], v[230:233], v[6:9]
	v_mfma_f32_16x16x32_bf16 v[6:9], v[182:185], v[226:229], v[6:9]
	s_setprio 0
	s_barrier
	s_add_i32 s78, s78, 2
	s_add_u32 s54, s54, 0x100
	s_addc_u32 s55, s55, 0
	s_add_u32 s76, s76, 0x100
	s_addc_u32 s77, s77, 0
	s_cmp_gt_u32 s78, 61
	s_cbranch_scc0 .LBB0_1631
	s_and_b64 vcc, exec, s[16:17]
	s_cbranch_vccz .LBB0_1634
	s_barrier

.LBB0_1649:
	s_add_u32 s36, s56, s44
	s_addc_u32 s37, s57, 0
	s_add_u32 s64, s36, 0x100
	s_addc_u32 s65, s37, 0
	s_and_b64 s[62:63], s[60:61], exec
	s_cselect_b32 s65, s21, s65
	s_cselect_b32 s64, s87, s64
	s_add_u32 s44, s54, s44
	s_addc_u32 s62, s55, 0
	s_add_u32 s44, s44, 0x100
	s_addc_u32 s62, s62, 0
	s_and_b64 s[60:61], s[60:61], exec
	s_cselect_b32 s67, s19, s62
	s_cselect_b32 s66, s89, s44
	s_add_u32 s70, s36, 0x10080
	s_addc_u32 s71, s37, 0
	s_add_i32 vcc_lo, s84, s39
	ds_read_b128 v[158:161], v147
	ds_read_b128 v[166:169], v147 offset:1024
	ds_read_b128 v[170:173], v147 offset:2048
	ds_read_b128 v[174:177], v147 offset:3072
	ds_read_b128 v[178:181], v155
	ds_read_b128 v[182:185], v155 offset:1024
	ds_read_b128 v[186:189], v155 offset:2048
	ds_read_b128 v[190:193], v155 offset:3072
	s_add_i32 m0, s53, 0xc000
	s_add_i32 vcc_hi, s53, 0xe000
	s_add_i32 s95, vcc_lo, 0x2000
	s_add_u32 s68, s66, 0x10000
	s_addc_u32 s69, s67, 0
	s_add_i32 s97, s85, s39
	s_add_i32 s96, s97, 0x2000
	s_add_i32 s94, 0, 0x18000
	s_add_i32 s93, 0, 0x1c000
	s_add_u32 s62, s64, 0x10000
	s_addc_u32 s63, s65, 0
	s_add_i32 s92, s94, s39
	s_add_i32 s90, s92, 0x2000
	s_add_u32 s60, s66, 0x10080
	s_addc_u32 s61, s67, 0
	s_add_i32 s91, s93, s39
	s_add_i32 s44, s91, 0x2000
	v_lshl_add_u64 v[198:199], s[70:71], 0, v[138:139]
	ds_read_b128 v[194:197], v156
	ds_read_b128 v[202:205], v156 offset:1024
	ds_read_b128 v[206:209], v156 offset:2048
	ds_read_b128 v[210:213], v156 offset:3072
	ds_read_b128 v[214:217], v156 offset:4096
	ds_read_b128 v[218:221], v156 offset:5120
	ds_read_b128 v[222:225], v156 offset:6144
	ds_read_b128 v[226:229], v156 offset:7168
	global_load_lds_dwordx4 v[198:199], off
	v_lshl_add_u64 v[198:199], s[70:71], 0, v[134:135]
	s_mov_b32 m0, vcc_hi
	s_nop 0
	global_load_lds_dwordx4 v[198:199], off
	s_waitcnt vmcnt(8)
	s_waitcnt lgkmcnt(0)
	s_barrier
	s_setprio 1
	s_waitcnt lgkmcnt(0)
	v_mfma_f32_16x16x32_bf16 v[126:129], v[158:161], v[194:197], v[126:129]
	v_mfma_f32_16x16x32_bf16 v[126:129], v[166:169], v[202:205], v[126:129]
	v_mfma_f32_16x16x32_bf16 v[122:125], v[174:177], v[202:205], v[122:125]
	v_mfma_f32_16x16x32_bf16 v[122:125], v[170:173], v[194:197], v[122:125]
	v_mfma_f32_16x16x32_bf16 v[110:113], v[170:173], v[206:209], v[110:113]
	v_mfma_f32_16x16x32_bf16 v[110:113], v[174:177], v[210:213], v[110:113]
	v_mfma_f32_16x16x32_bf16 v[118:121], v[166:169], v[210:213], v[118:121]
	v_mfma_f32_16x16x32_bf16 v[118:121], v[158:161], v[206:209], v[118:121]
	v_mfma_f32_16x16x32_bf16 v[102:105], v[158:161], v[214:217], v[102:105]
	v_mfma_f32_16x16x32_bf16 v[102:105], v[166:169], v[218:221], v[102:105]
	v_mfma_f32_16x16x32_bf16 v[94:97], v[174:177], v[218:221], v[94:97]
	v_mfma_f32_16x16x32_bf16 v[94:97], v[170:173], v[214:217], v[94:97]
	v_mfma_f32_16x16x32_bf16 v[78:81], v[170:173], v[222:225], v[78:81]
	v_mfma_f32_16x16x32_bf16 v[78:81], v[174:177], v[226:229], v[78:81]
	v_mfma_f32_16x16x32_bf16 v[86:89], v[166:169], v[226:229], v[86:89]
	v_mfma_f32_16x16x32_bf16 v[86:89], v[158:161], v[222:225], v[86:89]
	s_setprio 0
	s_setprio 1
	v_mfma_f32_16x16x32_bf16 v[114:117], v[178:181], v[194:197], v[114:117]
	v_mfma_f32_16x16x32_bf16 v[114:117], v[182:185], v[202:205], v[114:117]
	v_mfma_f32_16x16x32_bf16 v[106:109], v[190:193], v[202:205], v[106:109]
	v_mfma_f32_16x16x32_bf16 v[106:109], v[186:189], v[194:197], v[106:109]
	v_mfma_f32_16x16x32_bf16 v[90:93], v[186:189], v[206:209], v[90:93]
	v_mfma_f32_16x16x32_bf16 v[90:93], v[190:193], v[210:213], v[90:93]
	v_mfma_f32_16x16x32_bf16 v[98:101], v[182:185], v[210:213], v[98:101]
	v_mfma_f32_16x16x32_bf16 v[98:101], v[178:181], v[206:209], v[98:101]
	v_mfma_f32_16x16x32_bf16 v[82:85], v[178:181], v[214:217], v[82:85]
	v_mfma_f32_16x16x32_bf16 v[82:85], v[182:185], v[218:221], v[82:85]
	v_mfma_f32_16x16x32_bf16 v[74:77], v[190:193], v[218:221], v[74:77]
	v_mfma_f32_16x16x32_bf16 v[74:77], v[186:189], v[214:217], v[74:77]
	v_mfma_f32_16x16x32_bf16 v[66:69], v[186:189], v[222:225], v[66:69]
	v_mfma_f32_16x16x32_bf16 v[66:69], v[190:193], v[226:229], v[66:69]
	v_mfma_f32_16x16x32_bf16 v[70:73], v[182:185], v[226:229], v[70:73]
	v_mfma_f32_16x16x32_bf16 v[70:73], v[178:181], v[222:225], v[70:73]
	s_setprio 0
	s_barrier
	s_mov_b32 m0, vcc_lo
	v_lshl_add_u64 v[198:199], s[66:67], 0, v[136:137]
	ds_read_b128 v[194:197], v156 offset:16384
	ds_read_b128 v[202:205], v156 offset:17408
	ds_read_b128 v[206:209], v156 offset:18432
	ds_read_b128 v[210:213], v156 offset:19456
	ds_read_b128 v[214:217], v156 offset:20480
	ds_read_b128 v[218:221], v156 offset:21504
	ds_read_b128 v[222:225], v156 offset:22528
	ds_read_b128 v[226:229], v156 offset:23552
	global_load_lds_dwordx4 v[198:199], off
	v_lshl_add_u64 v[230:231], s[66:67], 0, v[132:133]
	s_mov_b32 m0, s95
	v_lshl_add_u64 v[232:233], s[68:69], 0, v[136:137]
	global_load_lds_dwordx4 v[230:231], off
	s_mov_b32 m0, s97
	v_lshl_add_u64 v[234:235], s[64:65], 0, v[134:135]
	global_load_lds_dwordx4 v[232:233], off
	v_lshl_add_u64 v[232:233], s[68:69], 0, v[132:133]
	s_mov_b32 m0, s96
	s_nop 0
	global_load_lds_dwordx4 v[232:233], off
	v_lshl_add_u64 v[232:233], s[64:65], 0, v[138:139]
	s_mov_b32 m0, s53
	s_nop 0
	global_load_lds_dwordx4 v[232:233], off
	s_mov_b32 m0, s75
	s_nop 0
	global_load_lds_dwordx4 v[234:235], off
	s_waitcnt vmcnt(8)
	s_waitcnt lgkmcnt(0)
	s_barrier
	s_setprio 1
	s_waitcnt lgkmcnt(0)
	v_mfma_f32_16x16x32_bf16 v[62:65], v[158:161], v[194:197], v[62:65]
	v_mfma_f32_16x16x32_bf16 v[62:65], v[166:169], v[202:205], v[62:65]
	v_mfma_f32_16x16x32_bf16 v[58:61], v[174:177], v[202:205], v[58:61]
	v_mfma_f32_16x16x32_bf16 v[58:61], v[170:173], v[194:197], v[58:61]
	v_mfma_f32_16x16x32_bf16 v[46:49], v[170:173], v[206:209], v[46:49]
	v_mfma_f32_16x16x32_bf16 v[46:49], v[174:177], v[210:213], v[46:49]
	v_mfma_f32_16x16x32_bf16 v[54:57], v[166:169], v[210:213], v[54:57]
	v_mfma_f32_16x16x32_bf16 v[54:57], v[158:161], v[206:209], v[54:57]
	v_mfma_f32_16x16x32_bf16 v[38:41], v[158:161], v[214:217], v[38:41]
	v_mfma_f32_16x16x32_bf16 v[38:41], v[166:169], v[218:221], v[38:41]
	v_mfma_f32_16x16x32_bf16 v[30:33], v[174:177], v[218:221], v[30:33]
	v_mfma_f32_16x16x32_bf16 v[30:33], v[170:173], v[214:217], v[30:33]
	v_mfma_f32_16x16x32_bf16 v[14:17], v[170:173], v[222:225], v[14:17]
	v_mfma_f32_16x16x32_bf16 v[14:17], v[174:177], v[226:229], v[14:17]
	v_mfma_f32_16x16x32_bf16 v[22:25], v[166:169], v[226:229], v[22:25]
	v_mfma_f32_16x16x32_bf16 v[22:25], v[158:161], v[222:225], v[22:25]
	s_setprio 0
	s_setprio 1
	v_mfma_f32_16x16x32_bf16 v[50:53], v[178:181], v[194:197], v[50:53]
	v_mfma_f32_16x16x32_bf16 v[50:53], v[182:185], v[202:205], v[50:53]
	v_mfma_f32_16x16x32_bf16 v[42:45], v[190:193], v[202:205], v[42:45]
	v_mfma_f32_16x16x32_bf16 v[42:45], v[186:189], v[194:197], v[42:45]
	v_mfma_f32_16x16x32_bf16 v[26:29], v[186:189], v[206:209], v[26:29]
	v_mfma_f32_16x16x32_bf16 v[26:29], v[190:193], v[210:213], v[26:29]
	v_mfma_f32_16x16x32_bf16 v[34:37], v[182:185], v[210:213], v[34:37]
	v_mfma_f32_16x16x32_bf16 v[34:37], v[178:181], v[206:209], v[34:37]
	v_mfma_f32_16x16x32_bf16 v[18:21], v[178:181], v[214:217], v[18:21]
	v_mfma_f32_16x16x32_bf16 v[18:21], v[182:185], v[218:221], v[18:21]
	v_mfma_f32_16x16x32_bf16 v[10:13], v[190:193], v[218:221], v[10:13]
	v_mfma_f32_16x16x32_bf16 v[10:13], v[186:189], v[214:217], v[10:13]
	v_mfma_f32_16x16x32_bf16 v[2:5], v[186:189], v[222:225], v[2:5]
	v_mfma_f32_16x16x32_bf16 v[2:5], v[190:193], v[226:229], v[2:5]
	v_mfma_f32_16x16x32_bf16 v[6:9], v[182:185], v[226:229], v[6:9]
	v_mfma_f32_16x16x32_bf16 v[6:9], v[178:181], v[222:225], v[6:9]
	s_setprio 0
	s_barrier
	v_add_u32_e32 v157, s94, v145
	ds_read_b128 v[158:161], v157
	ds_read_b128 v[166:169], v157 offset:1024
	ds_read_b128 v[170:173], v157 offset:2048
	ds_read_b128 v[174:177], v157 offset:3072
	v_add_u32_e32 v157, s93, v145
	ds_read_b128 v[178:181], v157
	ds_read_b128 v[182:185], v157 offset:1024
	ds_read_b128 v[186:189], v157 offset:2048
	ds_read_b128 v[190:193], v157 offset:3072
	s_mov_b32 m0, s76
	v_lshl_add_u64 v[236:237], s[62:63], 0, v[138:139]
	ds_read_b128 v[194:197], v156 offset:32768
	ds_read_b128 v[202:205], v156 offset:33792
	ds_read_b128 v[206:209], v156 offset:34816
	ds_read_b128 v[210:213], v156 offset:35840
	ds_read_b128 v[214:217], v156 offset:36864
	ds_read_b128 v[218:221], v156 offset:37888
	ds_read_b128 v[222:225], v156 offset:38912
	ds_read_b128 v[226:229], v156 offset:39936
	global_load_lds_dwordx4 v[236:237], off
	v_lshl_add_u64 v[236:237], s[62:63], 0, v[134:135]
	s_mov_b32 m0, s77
	s_nop 0
	global_load_lds_dwordx4 v[236:237], off
	s_waitcnt vmcnt(8)
	s_waitcnt lgkmcnt(0)
	s_barrier
	s_setprio 1
	s_waitcnt lgkmcnt(0)
	v_mfma_f32_16x16x32_bf16 v[126:129], v[158:161], v[194:197], v[126:129]
	v_mfma_f32_16x16x32_bf16 v[126:129], v[166:169], v[202:205], v[126:129]
	v_mfma_f32_16x16x32_bf16 v[122:125], v[174:177], v[202:205], v[122:125]
	v_mfma_f32_16x16x32_bf16 v[122:125], v[170:173], v[194:197], v[122:125]
	v_mfma_f32_16x16x32_bf16 v[110:113], v[170:173], v[206:209], v[110:113]
	v_mfma_f32_16x16x32_bf16 v[110:113], v[174:177], v[210:213], v[110:113]
	v_mfma_f32_16x16x32_bf16 v[118:121], v[166:169], v[210:213], v[118:121]
	v_mfma_f32_16x16x32_bf16 v[118:121], v[158:161], v[206:209], v[118:121]
	v_mfma_f32_16x16x32_bf16 v[102:105], v[158:161], v[214:217], v[102:105]
	v_mfma_f32_16x16x32_bf16 v[102:105], v[166:169], v[218:221], v[102:105]
	v_mfma_f32_16x16x32_bf16 v[94:97], v[174:177], v[218:221], v[94:97]
	v_mfma_f32_16x16x32_bf16 v[94:97], v[170:173], v[214:217], v[94:97]
	v_mfma_f32_16x16x32_bf16 v[78:81], v[170:173], v[222:225], v[78:81]
	v_mfma_f32_16x16x32_bf16 v[78:81], v[174:177], v[226:229], v[78:81]
	v_mfma_f32_16x16x32_bf16 v[86:89], v[166:169], v[226:229], v[86:89]
	v_mfma_f32_16x16x32_bf16 v[86:89], v[158:161], v[222:225], v[86:89]
	s_setprio 0
	s_setprio 1
	v_mfma_f32_16x16x32_bf16 v[114:117], v[178:181], v[194:197], v[114:117]
	v_mfma_f32_16x16x32_bf16 v[114:117], v[182:185], v[202:205], v[114:117]
	v_mfma_f32_16x16x32_bf16 v[106:109], v[190:193], v[202:205], v[106:109]
	v_mfma_f32_16x16x32_bf16 v[106:109], v[186:189], v[194:197], v[106:109]
	v_mfma_f32_16x16x32_bf16 v[90:93], v[186:189], v[206:209], v[90:93]
	v_mfma_f32_16x16x32_bf16 v[90:93], v[190:193], v[210:213], v[90:93]
	v_mfma_f32_16x16x32_bf16 v[98:101], v[182:185], v[210:213], v[98:101]
	v_mfma_f32_16x16x32_bf16 v[98:101], v[178:181], v[206:209], v[98:101]
	v_mfma_f32_16x16x32_bf16 v[82:85], v[178:181], v[214:217], v[82:85]
	v_mfma_f32_16x16x32_bf16 v[82:85], v[182:185], v[218:221], v[82:85]
	v_mfma_f32_16x16x32_bf16 v[74:77], v[190:193], v[218:221], v[74:77]
	v_mfma_f32_16x16x32_bf16 v[74:77], v[186:189], v[214:217], v[74:77]
	v_mfma_f32_16x16x32_bf16 v[66:69], v[186:189], v[222:225], v[66:69]
	v_mfma_f32_16x16x32_bf16 v[66:69], v[190:193], v[226:229], v[66:69]
	v_mfma_f32_16x16x32_bf16 v[70:73], v[182:185], v[226:229], v[70:73]
	v_mfma_f32_16x16x32_bf16 v[70:73], v[178:181], v[222:225], v[70:73]
	s_setprio 0
	s_barrier
	s_mov_b32 m0, s92
	v_lshl_add_u64 v[198:199], v[198:199], 0, s[14:15]
	ds_read_b128 v[194:197], v156 offset:49152
	ds_read_b128 v[202:205], v156 offset:50176
	ds_read_b128 v[206:209], v156 offset:51200
	ds_read_b128 v[210:213], v156 offset:52224
	ds_read_b128 v[214:217], v156 offset:53248
	ds_read_b128 v[218:221], v156 offset:54272
	ds_read_b128 v[222:225], v156 offset:55296
	ds_read_b128 v[226:229], v156 offset:56320
	global_load_lds_dwordx4 v[198:199], off
	v_lshl_add_u64 v[198:199], v[230:231], 0, s[14:15]
	s_mov_b32 m0, s90
	s_nop 0
	global_load_lds_dwordx4 v[198:199], off
	v_lshl_add_u64 v[198:199], s[60:61], 0, v[136:137]
	s_mov_b32 m0, s91
	s_nop 0
	global_load_lds_dwordx4 v[198:199], off
	v_lshl_add_u64 v[198:199], s[60:61], 0, v[132:133]
	s_mov_b32 m0, s44
	s_nop 0
	global_load_lds_dwordx4 v[198:199], off
	v_lshl_add_u64 v[198:199], v[232:233], 0, s[14:15]
	s_mov_b32 m0, s80
	s_nop 0
	global_load_lds_dwordx4 v[198:199], off
	v_lshl_add_u64 v[198:199], v[234:235], 0, s[14:15]
	s_mov_b32 m0, s81
	s_nop 0
	global_load_lds_dwordx4 v[198:199], off
	s_waitcnt vmcnt(8)
	s_waitcnt lgkmcnt(0)
	s_barrier
	s_setprio 1
	s_waitcnt lgkmcnt(0)
	v_mfma_f32_16x16x32_bf16 v[62:65], v[158:161], v[194:197], v[62:65]
	v_mfma_f32_16x16x32_bf16 v[62:65], v[166:169], v[202:205], v[62:65]
	v_mfma_f32_16x16x32_bf16 v[58:61], v[174:177], v[202:205], v[58:61]
	v_mfma_f32_16x16x32_bf16 v[58:61], v[170:173], v[194:197], v[58:61]
	v_mfma_f32_16x16x32_bf16 v[46:49], v[170:173], v[206:209], v[46:49]
	v_mfma_f32_16x16x32_bf16 v[46:49], v[174:177], v[210:213], v[46:49]
	v_mfma_f32_16x16x32_bf16 v[54:57], v[166:169], v[210:213], v[54:57]
	v_mfma_f32_16x16x32_bf16 v[54:57], v[158:161], v[206:209], v[54:57]
	v_mfma_f32_16x16x32_bf16 v[38:41], v[158:161], v[214:217], v[38:41]
	v_mfma_f32_16x16x32_bf16 v[38:41], v[166:169], v[218:221], v[38:41]
	v_mfma_f32_16x16x32_bf16 v[30:33], v[174:177], v[218:221], v[30:33]
	v_mfma_f32_16x16x32_bf16 v[30:33], v[170:173], v[214:217], v[30:33]
	v_mfma_f32_16x16x32_bf16 v[14:17], v[170:173], v[222:225], v[14:17]
	v_mfma_f32_16x16x32_bf16 v[14:17], v[174:177], v[226:229], v[14:17]
	v_mfma_f32_16x16x32_bf16 v[22:25], v[166:169], v[226:229], v[22:25]
	v_mfma_f32_16x16x32_bf16 v[22:25], v[158:161], v[222:225], v[22:25]
	s_setprio 0
	s_setprio 1
	v_mfma_f32_16x16x32_bf16 v[50:53], v[178:181], v[194:197], v[50:53]
	v_mfma_f32_16x16x32_bf16 v[50:53], v[182:185], v[202:205], v[50:53]
	v_mfma_f32_16x16x32_bf16 v[42:45], v[190:193], v[202:205], v[42:45]
	v_mfma_f32_16x16x32_bf16 v[42:45], v[186:189], v[194:197], v[42:45]
	v_mfma_f32_16x16x32_bf16 v[26:29], v[186:189], v[206:209], v[26:29]
	v_mfma_f32_16x16x32_bf16 v[26:29], v[190:193], v[210:213], v[26:29]
	v_mfma_f32_16x16x32_bf16 v[34:37], v[182:185], v[210:213], v[34:37]
	v_mfma_f32_16x16x32_bf16 v[34:37], v[178:181], v[206:209], v[34:37]
	v_mfma_f32_16x16x32_bf16 v[18:21], v[178:181], v[214:217], v[18:21]
	v_mfma_f32_16x16x32_bf16 v[18:21], v[182:185], v[218:221], v[18:21]
	v_mfma_f32_16x16x32_bf16 v[10:13], v[190:193], v[218:221], v[10:13]
	v_mfma_f32_16x16x32_bf16 v[10:13], v[186:189], v[214:217], v[10:13]
	v_mfma_f32_16x16x32_bf16 v[2:5], v[186:189], v[222:225], v[2:5]
	v_mfma_f32_16x16x32_bf16 v[2:5], v[190:193], v[226:229], v[2:5]
	v_mfma_f32_16x16x32_bf16 v[6:9], v[182:185], v[226:229], v[6:9]
	v_mfma_f32_16x16x32_bf16 v[6:9], v[178:181], v[222:225], v[6:9]
	s_setprio 0
	s_barrier
	s_movk_i32 s44, 0x100
	s_andn2_b64 vcc, exec, s[58:59]
	s_mov_b64 s[60:61], -1
	s_mov_b64 s[58:59], 0
	s_cbranch_vccz .LBB0_1649
	s_and_b64 vcc, exec, s[16:17]
	s_cbranch_vccz .LBB0_1652
	s_barrier

.LBB0_1667:
	s_add_u32 s36, s56, s44
	s_addc_u32 s37, s57, 0
	s_add_u32 s64, s36, 0x100
	s_addc_u32 s65, s37, 0
	s_and_b64 s[62:63], s[60:61], exec
	s_cselect_b32 s65, s21, s65
	s_cselect_b32 s64, s86, s64
	s_add_u32 s44, s54, s44
	s_addc_u32 s62, s55, 0
	s_add_u32 s44, s44, 0x100
	s_addc_u32 s62, s62, 0
	s_and_b64 s[60:61], s[60:61], exec
	s_cselect_b32 s67, s19, s62
	s_cselect_b32 s66, s87, s44
	s_add_u32 s70, s36, 0x10080
	s_addc_u32 s71, s37, 0
	s_add_i32 s97, s82, s38
	ds_read_b128 v[150:153], v146
	ds_read_b128 v[154:157], v146 offset:1024
	ds_read_b128 v[158:161], v146 offset:2048
	ds_read_b128 v[166:169], v146 offset:3072
	ds_read_b128 v[170:173], v147
	ds_read_b128 v[174:177], v147 offset:1024
	ds_read_b128 v[178:181], v147 offset:2048
	ds_read_b128 v[182:185], v147 offset:3072
	s_add_i32 m0, s53, 0xc000
	s_add_i32 vcc_lo, s53, 0xe000
	s_add_i32 s94, s97, 0x2000
	s_add_u32 s68, s66, 0x10000
	s_addc_u32 s69, s67, 0
	s_add_i32 s96, s83, s38
	s_add_i32 s95, s96, 0x2000
	s_add_i32 s93, 0, 0x18000
	s_add_i32 s92, 0, 0x1c000
	s_add_u32 s62, s64, 0x10000
	s_addc_u32 s63, s65, 0
	s_add_i32 s91, s93, s38
	s_add_i32 s89, s91, 0x2000
	s_add_u32 s60, s66, 0x10080
	s_addc_u32 s61, s67, 0
	s_add_i32 s90, s92, s38
	s_add_i32 s44, s90, 0x2000
	v_lshl_add_u64 v[198:199], s[70:71], 0, v[138:139]
	ds_read_b128 v[186:189], v148
	ds_read_b128 v[190:193], v148 offset:1024
	ds_read_b128 v[194:197], v148 offset:2048
	ds_read_b128 v[202:205], v148 offset:3072
	ds_read_b128 v[206:209], v148 offset:4096
	ds_read_b128 v[210:213], v148 offset:5120
	ds_read_b128 v[214:217], v148 offset:6144
	ds_read_b128 v[218:221], v148 offset:7168
	global_load_lds_dwordx4 v[198:199], off
	v_lshl_add_u64 v[198:199], s[70:71], 0, v[134:135]
	s_mov_b32 m0, vcc_lo
	s_nop 0
	global_load_lds_dwordx4 v[198:199], off
	s_waitcnt vmcnt(8)
	s_waitcnt lgkmcnt(0)
	s_barrier
	s_setprio 1
	s_waitcnt lgkmcnt(0)
	v_mfma_f32_16x16x32_bf16 v[126:129], v[150:153], v[186:189], v[126:129]
	v_mfma_f32_16x16x32_bf16 v[126:129], v[154:157], v[190:193], v[126:129]
	v_mfma_f32_16x16x32_bf16 v[122:125], v[166:169], v[190:193], v[122:125]
	v_mfma_f32_16x16x32_bf16 v[122:125], v[158:161], v[186:189], v[122:125]
	v_mfma_f32_16x16x32_bf16 v[110:113], v[158:161], v[194:197], v[110:113]
	v_mfma_f32_16x16x32_bf16 v[110:113], v[166:169], v[202:205], v[110:113]
	v_mfma_f32_16x16x32_bf16 v[118:121], v[154:157], v[202:205], v[118:121]
	v_mfma_f32_16x16x32_bf16 v[118:121], v[150:153], v[194:197], v[118:121]
	v_mfma_f32_16x16x32_bf16 v[102:105], v[150:153], v[206:209], v[102:105]
	v_mfma_f32_16x16x32_bf16 v[102:105], v[154:157], v[210:213], v[102:105]
	v_mfma_f32_16x16x32_bf16 v[94:97], v[166:169], v[210:213], v[94:97]
	v_mfma_f32_16x16x32_bf16 v[94:97], v[158:161], v[206:209], v[94:97]
	v_mfma_f32_16x16x32_bf16 v[78:81], v[158:161], v[214:217], v[78:81]
	v_mfma_f32_16x16x32_bf16 v[78:81], v[166:169], v[218:221], v[78:81]
	v_mfma_f32_16x16x32_bf16 v[86:89], v[154:157], v[218:221], v[86:89]
	v_mfma_f32_16x16x32_bf16 v[86:89], v[150:153], v[214:217], v[86:89]
	s_setprio 0
	s_setprio 1
	v_mfma_f32_16x16x32_bf16 v[114:117], v[170:173], v[186:189], v[114:117]
	v_mfma_f32_16x16x32_bf16 v[114:117], v[174:177], v[190:193], v[114:117]
	v_mfma_f32_16x16x32_bf16 v[106:109], v[182:185], v[190:193], v[106:109]
	v_mfma_f32_16x16x32_bf16 v[106:109], v[178:181], v[186:189], v[106:109]
	v_mfma_f32_16x16x32_bf16 v[90:93], v[178:181], v[194:197], v[90:93]
	v_mfma_f32_16x16x32_bf16 v[90:93], v[182:185], v[202:205], v[90:93]
	v_mfma_f32_16x16x32_bf16 v[98:101], v[174:177], v[202:205], v[98:101]
	v_mfma_f32_16x16x32_bf16 v[98:101], v[170:173], v[194:197], v[98:101]
	v_mfma_f32_16x16x32_bf16 v[82:85], v[170:173], v[206:209], v[82:85]
	v_mfma_f32_16x16x32_bf16 v[82:85], v[174:177], v[210:213], v[82:85]
	v_mfma_f32_16x16x32_bf16 v[74:77], v[182:185], v[210:213], v[74:77]
	v_mfma_f32_16x16x32_bf16 v[74:77], v[178:181], v[206:209], v[74:77]
	v_mfma_f32_16x16x32_bf16 v[66:69], v[178:181], v[214:217], v[66:69]
	v_mfma_f32_16x16x32_bf16 v[66:69], v[182:185], v[218:221], v[66:69]
	v_mfma_f32_16x16x32_bf16 v[70:73], v[174:177], v[218:221], v[70:73]
	v_mfma_f32_16x16x32_bf16 v[70:73], v[170:173], v[214:217], v[70:73]
	s_setprio 0
	s_barrier
	s_mov_b32 m0, s97
	v_lshl_add_u64 v[198:199], s[66:67], 0, v[136:137]
	ds_read_b128 v[186:189], v148 offset:16384
	ds_read_b128 v[190:193], v148 offset:17408
	ds_read_b128 v[194:197], v148 offset:18432
	ds_read_b128 v[202:205], v148 offset:19456
	ds_read_b128 v[206:209], v148 offset:20480
	ds_read_b128 v[210:213], v148 offset:21504
	ds_read_b128 v[214:217], v148 offset:22528
	ds_read_b128 v[218:221], v148 offset:23552
	global_load_lds_dwordx4 v[198:199], off
	v_lshl_add_u64 v[222:223], s[66:67], 0, v[132:133]
	s_mov_b32 m0, s94
	v_lshl_add_u64 v[224:225], s[68:69], 0, v[136:137]
	global_load_lds_dwordx4 v[222:223], off
	s_mov_b32 m0, s96
	v_lshl_add_u64 v[226:227], s[64:65], 0, v[134:135]
	global_load_lds_dwordx4 v[224:225], off
	v_lshl_add_u64 v[224:225], s[68:69], 0, v[132:133]
	s_mov_b32 m0, s95
	s_nop 0
	global_load_lds_dwordx4 v[224:225], off
	v_lshl_add_u64 v[224:225], s[64:65], 0, v[138:139]
	s_mov_b32 m0, s53
	s_nop 0
	global_load_lds_dwordx4 v[224:225], off
	s_mov_b32 m0, s75
	s_nop 0
	global_load_lds_dwordx4 v[226:227], off
	s_waitcnt vmcnt(8)
	s_waitcnt lgkmcnt(0)
	s_barrier
	s_setprio 1
	s_waitcnt lgkmcnt(0)
	v_mfma_f32_16x16x32_bf16 v[62:65], v[150:153], v[186:189], v[62:65]
	v_mfma_f32_16x16x32_bf16 v[62:65], v[154:157], v[190:193], v[62:65]
	v_mfma_f32_16x16x32_bf16 v[58:61], v[166:169], v[190:193], v[58:61]
	v_mfma_f32_16x16x32_bf16 v[58:61], v[158:161], v[186:189], v[58:61]
	v_mfma_f32_16x16x32_bf16 v[46:49], v[158:161], v[194:197], v[46:49]
	v_mfma_f32_16x16x32_bf16 v[46:49], v[166:169], v[202:205], v[46:49]
	v_mfma_f32_16x16x32_bf16 v[54:57], v[154:157], v[202:205], v[54:57]
	v_mfma_f32_16x16x32_bf16 v[54:57], v[150:153], v[194:197], v[54:57]
	v_mfma_f32_16x16x32_bf16 v[38:41], v[150:153], v[206:209], v[38:41]
	v_mfma_f32_16x16x32_bf16 v[38:41], v[154:157], v[210:213], v[38:41]
	v_mfma_f32_16x16x32_bf16 v[30:33], v[166:169], v[210:213], v[30:33]
	v_mfma_f32_16x16x32_bf16 v[30:33], v[158:161], v[206:209], v[30:33]
	v_mfma_f32_16x16x32_bf16 v[14:17], v[158:161], v[214:217], v[14:17]
	v_mfma_f32_16x16x32_bf16 v[14:17], v[166:169], v[218:221], v[14:17]
	v_mfma_f32_16x16x32_bf16 v[22:25], v[154:157], v[218:221], v[22:25]
	v_mfma_f32_16x16x32_bf16 v[22:25], v[150:153], v[214:217], v[22:25]
	s_setprio 0
	s_setprio 1
	v_mfma_f32_16x16x32_bf16 v[50:53], v[170:173], v[186:189], v[50:53]
	v_mfma_f32_16x16x32_bf16 v[50:53], v[174:177], v[190:193], v[50:53]
	v_mfma_f32_16x16x32_bf16 v[42:45], v[182:185], v[190:193], v[42:45]
	v_mfma_f32_16x16x32_bf16 v[42:45], v[178:181], v[186:189], v[42:45]
	v_mfma_f32_16x16x32_bf16 v[26:29], v[178:181], v[194:197], v[26:29]
	v_mfma_f32_16x16x32_bf16 v[26:29], v[182:185], v[202:205], v[26:29]
	v_mfma_f32_16x16x32_bf16 v[34:37], v[174:177], v[202:205], v[34:37]
	v_mfma_f32_16x16x32_bf16 v[34:37], v[170:173], v[194:197], v[34:37]
	v_mfma_f32_16x16x32_bf16 v[18:21], v[170:173], v[206:209], v[18:21]
	v_mfma_f32_16x16x32_bf16 v[18:21], v[174:177], v[210:213], v[18:21]
	v_mfma_f32_16x16x32_bf16 v[10:13], v[182:185], v[210:213], v[10:13]
	v_mfma_f32_16x16x32_bf16 v[10:13], v[178:181], v[206:209], v[10:13]
	v_mfma_f32_16x16x32_bf16 v[2:5], v[178:181], v[214:217], v[2:5]
	v_mfma_f32_16x16x32_bf16 v[2:5], v[182:185], v[218:221], v[2:5]
	v_mfma_f32_16x16x32_bf16 v[6:9], v[174:177], v[218:221], v[6:9]
	v_mfma_f32_16x16x32_bf16 v[6:9], v[170:173], v[214:217], v[6:9]
	s_setprio 0
	s_barrier
	v_add_u32_e32 v149, s93, v145
	ds_read_b128 v[150:153], v149
	ds_read_b128 v[154:157], v149 offset:1024
	ds_read_b128 v[158:161], v149 offset:2048
	ds_read_b128 v[166:169], v149 offset:3072
	v_add_u32_e32 v149, s92, v145
	ds_read_b128 v[170:173], v149
	ds_read_b128 v[174:177], v149 offset:1024
	ds_read_b128 v[178:181], v149 offset:2048
	ds_read_b128 v[182:185], v149 offset:3072
	s_mov_b32 m0, s76
	v_lshl_add_u64 v[228:229], s[62:63], 0, v[138:139]
	ds_read_b128 v[186:189], v148 offset:32768
	ds_read_b128 v[190:193], v148 offset:33792
	ds_read_b128 v[194:197], v148 offset:34816
	ds_read_b128 v[202:205], v148 offset:35840
	ds_read_b128 v[206:209], v148 offset:36864
	ds_read_b128 v[210:213], v148 offset:37888
	ds_read_b128 v[214:217], v148 offset:38912
	ds_read_b128 v[218:221], v148 offset:39936
	global_load_lds_dwordx4 v[228:229], off
	v_lshl_add_u64 v[228:229], s[62:63], 0, v[134:135]
	s_mov_b32 m0, s77
	s_nop 0
	global_load_lds_dwordx4 v[228:229], off
	s_waitcnt vmcnt(8)
	s_waitcnt lgkmcnt(0)
	s_barrier
	s_setprio 1
	s_waitcnt lgkmcnt(0)
	v_mfma_f32_16x16x32_bf16 v[126:129], v[150:153], v[186:189], v[126:129]
	v_mfma_f32_16x16x32_bf16 v[126:129], v[154:157], v[190:193], v[126:129]
	v_mfma_f32_16x16x32_bf16 v[122:125], v[166:169], v[190:193], v[122:125]
	v_mfma_f32_16x16x32_bf16 v[122:125], v[158:161], v[186:189], v[122:125]
	v_mfma_f32_16x16x32_bf16 v[110:113], v[158:161], v[194:197], v[110:113]
	v_mfma_f32_16x16x32_bf16 v[110:113], v[166:169], v[202:205], v[110:113]
	v_mfma_f32_16x16x32_bf16 v[118:121], v[154:157], v[202:205], v[118:121]
	v_mfma_f32_16x16x32_bf16 v[118:121], v[150:153], v[194:197], v[118:121]
	v_mfma_f32_16x16x32_bf16 v[102:105], v[150:153], v[206:209], v[102:105]
	v_mfma_f32_16x16x32_bf16 v[102:105], v[154:157], v[210:213], v[102:105]
	v_mfma_f32_16x16x32_bf16 v[94:97], v[166:169], v[210:213], v[94:97]
	v_mfma_f32_16x16x32_bf16 v[94:97], v[158:161], v[206:209], v[94:97]
	v_mfma_f32_16x16x32_bf16 v[78:81], v[158:161], v[214:217], v[78:81]
	v_mfma_f32_16x16x32_bf16 v[78:81], v[166:169], v[218:221], v[78:81]
	v_mfma_f32_16x16x32_bf16 v[86:89], v[154:157], v[218:221], v[86:89]
	v_mfma_f32_16x16x32_bf16 v[86:89], v[150:153], v[214:217], v[86:89]
	s_setprio 0
	s_setprio 1
	v_mfma_f32_16x16x32_bf16 v[114:117], v[170:173], v[186:189], v[114:117]
	v_mfma_f32_16x16x32_bf16 v[114:117], v[174:177], v[190:193], v[114:117]
	v_mfma_f32_16x16x32_bf16 v[106:109], v[182:185], v[190:193], v[106:109]
	v_mfma_f32_16x16x32_bf16 v[106:109], v[178:181], v[186:189], v[106:109]
	v_mfma_f32_16x16x32_bf16 v[90:93], v[178:181], v[194:197], v[90:93]
	v_mfma_f32_16x16x32_bf16 v[90:93], v[182:185], v[202:205], v[90:93]
	v_mfma_f32_16x16x32_bf16 v[98:101], v[174:177], v[202:205], v[98:101]
	v_mfma_f32_16x16x32_bf16 v[98:101], v[170:173], v[194:197], v[98:101]
	v_mfma_f32_16x16x32_bf16 v[82:85], v[170:173], v[206:209], v[82:85]
	v_mfma_f32_16x16x32_bf16 v[82:85], v[174:177], v[210:213], v[82:85]
	v_mfma_f32_16x16x32_bf16 v[74:77], v[182:185], v[210:213], v[74:77]
	v_mfma_f32_16x16x32_bf16 v[74:77], v[178:181], v[206:209], v[74:77]
	v_mfma_f32_16x16x32_bf16 v[66:69], v[178:181], v[214:217], v[66:69]
	v_mfma_f32_16x16x32_bf16 v[66:69], v[182:185], v[218:221], v[66:69]
	v_mfma_f32_16x16x32_bf16 v[70:73], v[174:177], v[218:221], v[70:73]
	v_mfma_f32_16x16x32_bf16 v[70:73], v[170:173], v[214:217], v[70:73]
	s_setprio 0
	s_barrier
	s_mov_b32 m0, s91
	v_lshl_add_u64 v[198:199], v[198:199], 0, s[14:15]
	ds_read_b128 v[186:189], v148 offset:49152
	ds_read_b128 v[190:193], v148 offset:50176
	ds_read_b128 v[194:197], v148 offset:51200
	ds_read_b128 v[202:205], v148 offset:52224
	ds_read_b128 v[206:209], v148 offset:53248
	ds_read_b128 v[210:213], v148 offset:54272
	ds_read_b128 v[214:217], v148 offset:55296
	ds_read_b128 v[218:221], v148 offset:56320
	global_load_lds_dwordx4 v[198:199], off
	v_lshl_add_u64 v[198:199], v[222:223], 0, s[14:15]
	s_mov_b32 m0, s89
	s_nop 0
	global_load_lds_dwordx4 v[198:199], off
	v_lshl_add_u64 v[198:199], s[60:61], 0, v[136:137]
	s_mov_b32 m0, s90
	s_nop 0
	global_load_lds_dwordx4 v[198:199], off
	v_lshl_add_u64 v[198:199], s[60:61], 0, v[132:133]
	s_mov_b32 m0, s44
	s_nop 0
	global_load_lds_dwordx4 v[198:199], off
	v_lshl_add_u64 v[198:199], v[224:225], 0, s[14:15]
	s_mov_b32 m0, s79
	s_nop 0
	global_load_lds_dwordx4 v[198:199], off
	v_lshl_add_u64 v[198:199], v[226:227], 0, s[14:15]
	s_mov_b32 m0, s80
	s_nop 0
	global_load_lds_dwordx4 v[198:199], off
	s_waitcnt vmcnt(8)
	s_waitcnt lgkmcnt(0)
	s_barrier
	s_setprio 1
	s_waitcnt lgkmcnt(0)
	v_mfma_f32_16x16x32_bf16 v[62:65], v[150:153], v[186:189], v[62:65]
	v_mfma_f32_16x16x32_bf16 v[62:65], v[154:157], v[190:193], v[62:65]
	v_mfma_f32_16x16x32_bf16 v[58:61], v[166:169], v[190:193], v[58:61]
	v_mfma_f32_16x16x32_bf16 v[58:61], v[158:161], v[186:189], v[58:61]
	v_mfma_f32_16x16x32_bf16 v[46:49], v[158:161], v[194:197], v[46:49]
	v_mfma_f32_16x16x32_bf16 v[46:49], v[166:169], v[202:205], v[46:49]
	v_mfma_f32_16x16x32_bf16 v[54:57], v[154:157], v[202:205], v[54:57]
	v_mfma_f32_16x16x32_bf16 v[54:57], v[150:153], v[194:197], v[54:57]
	v_mfma_f32_16x16x32_bf16 v[38:41], v[150:153], v[206:209], v[38:41]
	v_mfma_f32_16x16x32_bf16 v[38:41], v[154:157], v[210:213], v[38:41]
	v_mfma_f32_16x16x32_bf16 v[30:33], v[166:169], v[210:213], v[30:33]
	v_mfma_f32_16x16x32_bf16 v[30:33], v[158:161], v[206:209], v[30:33]
	v_mfma_f32_16x16x32_bf16 v[14:17], v[158:161], v[214:217], v[14:17]
	v_mfma_f32_16x16x32_bf16 v[14:17], v[166:169], v[218:221], v[14:17]
	v_mfma_f32_16x16x32_bf16 v[22:25], v[154:157], v[218:221], v[22:25]
	v_mfma_f32_16x16x32_bf16 v[22:25], v[150:153], v[214:217], v[22:25]
	s_setprio 0
	s_setprio 1
	v_mfma_f32_16x16x32_bf16 v[50:53], v[170:173], v[186:189], v[50:53]
	v_mfma_f32_16x16x32_bf16 v[50:53], v[174:177], v[190:193], v[50:53]
	v_mfma_f32_16x16x32_bf16 v[42:45], v[182:185], v[190:193], v[42:45]
	v_mfma_f32_16x16x32_bf16 v[42:45], v[178:181], v[186:189], v[42:45]
	v_mfma_f32_16x16x32_bf16 v[26:29], v[178:181], v[194:197], v[26:29]
	v_mfma_f32_16x16x32_bf16 v[26:29], v[182:185], v[202:205], v[26:29]
	v_mfma_f32_16x16x32_bf16 v[34:37], v[174:177], v[202:205], v[34:37]
	v_mfma_f32_16x16x32_bf16 v[34:37], v[170:173], v[194:197], v[34:37]
	v_mfma_f32_16x16x32_bf16 v[18:21], v[170:173], v[206:209], v[18:21]
	v_mfma_f32_16x16x32_bf16 v[18:21], v[174:177], v[210:213], v[18:21]
	v_mfma_f32_16x16x32_bf16 v[10:13], v[182:185], v[210:213], v[10:13]
	v_mfma_f32_16x16x32_bf16 v[10:13], v[178:181], v[206:209], v[10:13]
	v_mfma_f32_16x16x32_bf16 v[2:5], v[178:181], v[214:217], v[2:5]
	v_mfma_f32_16x16x32_bf16 v[2:5], v[182:185], v[218:221], v[2:5]
	v_mfma_f32_16x16x32_bf16 v[6:9], v[174:177], v[218:221], v[6:9]
	v_mfma_f32_16x16x32_bf16 v[6:9], v[170:173], v[214:217], v[6:9]
	s_setprio 0
	s_barrier
	s_movk_i32 s44, 0x100
	s_andn2_b64 vcc, exec, s[58:59]
	s_mov_b64 s[60:61], -1
	s_mov_b64 s[58:59], 0
	s_cbranch_vccz .LBB0_1667
	s_and_b64 vcc, exec, s[16:17]
	s_cbranch_vccz .LBB0_1670
	s_barrier

.LBB0_1685:
	ds_read_b128 v[156:159], v153
	ds_read_b128 v[166:169], v153 offset:1024
	ds_read_b128 v[170:173], v153 offset:2048
	ds_read_b128 v[174:177], v153 offset:3072
	ds_read_b128 v[178:181], v154
	ds_read_b128 v[182:185], v154 offset:1024
	ds_read_b128 v[186:189], v154 offset:2048
	ds_read_b128 v[190:193], v154 offset:3072
	s_add_u32 s36, s56, 0xfff00080
	s_addc_u32 s37, s57, -1
	s_cmp_eq_u32 s78, 60
	s_cselect_b32 s61, s25, s37
	s_cselect_b32 s60, s74, s36
	s_cselect_b32 s59, s21, s77
	s_cselect_b32 s58, s75, s76
	v_lshl_add_u64 v[160:161], s[56:57], 0, v[140:141]
	s_add_i32 m0, s55, 0xc000
	ds_read_b128 v[194:197], v155
	ds_read_b128 v[202:205], v155 offset:1024
	ds_read_b128 v[206:209], v155 offset:2048
	ds_read_b128 v[210:213], v155 offset:3072
	ds_read_b128 v[214:217], v155 offset:4096
	ds_read_b128 v[218:221], v155 offset:5120
	ds_read_b128 v[222:225], v155 offset:6144
	ds_read_b128 v[226:229], v155 offset:7168
	global_load_lds_dwordx4 v[160:161], off
	v_lshl_add_u64 v[160:161], s[56:57], 0, v[142:143]
	s_add_i32 m0, s55, 0xe000
	s_nop 0
	global_load_lds_dwordx4 v[160:161], off
	s_waitcnt vmcnt(8)
	s_waitcnt lgkmcnt(0)
	s_barrier
	s_setprio 1
	s_waitcnt lgkmcnt(0)
	v_mfma_f32_16x16x32_bf16 v[126:129], v[156:159], v[194:197], v[126:129]
	v_mfma_f32_16x16x32_bf16 v[126:129], v[166:169], v[202:205], v[126:129]
	v_mfma_f32_16x16x32_bf16 v[122:125], v[174:177], v[202:205], v[122:125]
	v_mfma_f32_16x16x32_bf16 v[122:125], v[170:173], v[194:197], v[122:125]
	v_mfma_f32_16x16x32_bf16 v[110:113], v[170:173], v[206:209], v[110:113]
	v_mfma_f32_16x16x32_bf16 v[110:113], v[174:177], v[210:213], v[110:113]
	v_mfma_f32_16x16x32_bf16 v[118:121], v[166:169], v[210:213], v[118:121]
	v_mfma_f32_16x16x32_bf16 v[118:121], v[156:159], v[206:209], v[118:121]
	v_mfma_f32_16x16x32_bf16 v[102:105], v[156:159], v[214:217], v[102:105]
	v_mfma_f32_16x16x32_bf16 v[102:105], v[166:169], v[218:221], v[102:105]
	v_mfma_f32_16x16x32_bf16 v[94:97], v[174:177], v[218:221], v[94:97]
	v_mfma_f32_16x16x32_bf16 v[94:97], v[170:173], v[214:217], v[94:97]
	v_mfma_f32_16x16x32_bf16 v[78:81], v[170:173], v[222:225], v[78:81]
	v_mfma_f32_16x16x32_bf16 v[78:81], v[174:177], v[226:229], v[78:81]
	v_mfma_f32_16x16x32_bf16 v[86:89], v[166:169], v[226:229], v[86:89]
	v_mfma_f32_16x16x32_bf16 v[86:89], v[156:159], v[222:225], v[86:89]
	s_setprio 0
	s_setprio 1
	v_mfma_f32_16x16x32_bf16 v[114:117], v[178:181], v[194:197], v[114:117]
	v_mfma_f32_16x16x32_bf16 v[114:117], v[182:185], v[202:205], v[114:117]
	v_mfma_f32_16x16x32_bf16 v[106:109], v[190:193], v[202:205], v[106:109]
	v_mfma_f32_16x16x32_bf16 v[106:109], v[186:189], v[194:197], v[106:109]
	v_mfma_f32_16x16x32_bf16 v[90:93], v[186:189], v[206:209], v[90:93]
	v_mfma_f32_16x16x32_bf16 v[90:93], v[190:193], v[210:213], v[90:93]
	v_mfma_f32_16x16x32_bf16 v[98:101], v[182:185], v[210:213], v[98:101]
	v_mfma_f32_16x16x32_bf16 v[98:101], v[178:181], v[206:209], v[98:101]
	v_mfma_f32_16x16x32_bf16 v[82:85], v[178:181], v[214:217], v[82:85]
	v_mfma_f32_16x16x32_bf16 v[82:85], v[182:185], v[218:221], v[82:85]
	v_mfma_f32_16x16x32_bf16 v[74:77], v[190:193], v[218:221], v[74:77]
	v_mfma_f32_16x16x32_bf16 v[74:77], v[186:189], v[214:217], v[74:77]
	v_mfma_f32_16x16x32_bf16 v[66:69], v[186:189], v[222:225], v[66:69]
	v_mfma_f32_16x16x32_bf16 v[66:69], v[190:193], v[226:229], v[66:69]
	v_mfma_f32_16x16x32_bf16 v[70:73], v[182:185], v[226:229], v[70:73]
	v_mfma_f32_16x16x32_bf16 v[70:73], v[178:181], v[222:225], v[70:73]
	s_setprio 0
	s_barrier
	s_add_i32 s36, s68, s38
	v_lshl_add_u64 v[160:161], s[58:59], 0, v[136:137]
	s_mov_b32 m0, s36
	ds_read_b128 v[194:197], v155 offset:16384
	ds_read_b128 v[202:205], v155 offset:17408
	ds_read_b128 v[206:209], v155 offset:18432
	ds_read_b128 v[210:213], v155 offset:19456
	ds_read_b128 v[214:217], v155 offset:20480
	ds_read_b128 v[218:221], v155 offset:21504
	ds_read_b128 v[222:225], v155 offset:22528
	ds_read_b128 v[226:229], v155 offset:23552
	global_load_lds_dwordx4 v[160:161], off
	s_add_i32 m0, s36, 0x2000
	s_add_u32 s80, s58, 0x100000
	v_lshl_add_u64 v[198:199], s[58:59], 0, v[132:133]
	s_addc_u32 s81, s59, 0
	s_add_i32 s36, s69, s38
	global_load_lds_dwordx4 v[198:199], off
	v_lshl_add_u64 v[230:231], s[80:81], 0, v[136:137]
	s_mov_b32 m0, s36
	v_lshl_add_u64 v[232:233], s[60:61], 0, v[134:135]
	global_load_lds_dwordx4 v[230:231], off
	v_lshl_add_u64 v[230:231], s[80:81], 0, v[132:133]
	s_add_i32 m0, s36, 0x2000
	s_nop 0
	global_load_lds_dwordx4 v[230:231], off
	v_lshl_add_u64 v[230:231], s[60:61], 0, v[138:139]
	s_mov_b32 m0, s55
	s_nop 0
	global_load_lds_dwordx4 v[230:231], off
	s_mov_b32 m0, s63
	s_nop 0
	global_load_lds_dwordx4 v[232:233], off
	s_waitcnt vmcnt(8)
	s_waitcnt lgkmcnt(0)
	s_barrier
	s_setprio 1
	s_waitcnt lgkmcnt(0)
	v_mfma_f32_16x16x32_bf16 v[62:65], v[156:159], v[194:197], v[62:65]
	v_mfma_f32_16x16x32_bf16 v[62:65], v[166:169], v[202:205], v[62:65]
	v_mfma_f32_16x16x32_bf16 v[58:61], v[174:177], v[202:205], v[58:61]
	v_mfma_f32_16x16x32_bf16 v[58:61], v[170:173], v[194:197], v[58:61]
	v_mfma_f32_16x16x32_bf16 v[46:49], v[170:173], v[206:209], v[46:49]
	v_mfma_f32_16x16x32_bf16 v[46:49], v[174:177], v[210:213], v[46:49]
	v_mfma_f32_16x16x32_bf16 v[54:57], v[166:169], v[210:213], v[54:57]
	v_mfma_f32_16x16x32_bf16 v[54:57], v[156:159], v[206:209], v[54:57]
	v_mfma_f32_16x16x32_bf16 v[38:41], v[156:159], v[214:217], v[38:41]
	v_mfma_f32_16x16x32_bf16 v[38:41], v[166:169], v[218:221], v[38:41]
	v_mfma_f32_16x16x32_bf16 v[30:33], v[174:177], v[218:221], v[30:33]
	v_mfma_f32_16x16x32_bf16 v[30:33], v[170:173], v[214:217], v[30:33]
	v_mfma_f32_16x16x32_bf16 v[14:17], v[170:173], v[222:225], v[14:17]
	v_mfma_f32_16x16x32_bf16 v[14:17], v[174:177], v[226:229], v[14:17]
	v_mfma_f32_16x16x32_bf16 v[22:25], v[166:169], v[226:229], v[22:25]
	v_mfma_f32_16x16x32_bf16 v[22:25], v[156:159], v[222:225], v[22:25]
	s_setprio 0
	s_setprio 1
	v_mfma_f32_16x16x32_bf16 v[50:53], v[178:181], v[194:197], v[50:53]
	v_mfma_f32_16x16x32_bf16 v[50:53], v[182:185], v[202:205], v[50:53]
	v_mfma_f32_16x16x32_bf16 v[42:45], v[190:193], v[202:205], v[42:45]
	v_mfma_f32_16x16x32_bf16 v[42:45], v[186:189], v[194:197], v[42:45]
	v_mfma_f32_16x16x32_bf16 v[26:29], v[186:189], v[206:209], v[26:29]
	v_mfma_f32_16x16x32_bf16 v[26:29], v[190:193], v[210:213], v[26:29]
	v_mfma_f32_16x16x32_bf16 v[34:37], v[182:185], v[210:213], v[34:37]
	v_mfma_f32_16x16x32_bf16 v[34:37], v[178:181], v[206:209], v[34:37]
	v_mfma_f32_16x16x32_bf16 v[18:21], v[178:181], v[214:217], v[18:21]
	v_mfma_f32_16x16x32_bf16 v[18:21], v[182:185], v[218:221], v[18:21]
	v_mfma_f32_16x16x32_bf16 v[10:13], v[190:193], v[218:221], v[10:13]
	v_mfma_f32_16x16x32_bf16 v[10:13], v[186:189], v[214:217], v[10:13]
	v_mfma_f32_16x16x32_bf16 v[2:5], v[186:189], v[222:225], v[2:5]
	v_mfma_f32_16x16x32_bf16 v[2:5], v[190:193], v[226:229], v[2:5]
	v_mfma_f32_16x16x32_bf16 v[6:9], v[182:185], v[226:229], v[6:9]
	v_mfma_f32_16x16x32_bf16 v[6:9], v[178:181], v[222:225], v[6:9]
	s_setprio 0
	s_barrier
	s_add_i32 s36, 0, 0x18000
	v_add_u32_e32 v165, s36, v151
	s_add_i32 s37, 0, 0x1c000
	ds_read_b128 v[156:159], v165
	ds_read_b128 v[166:169], v165 offset:1024
	ds_read_b128 v[170:173], v165 offset:2048
	ds_read_b128 v[174:177], v165 offset:3072
	v_add_u32_e32 v165, s37, v151
	ds_read_b128 v[178:181], v165
	ds_read_b128 v[182:185], v165 offset:1024
	ds_read_b128 v[186:189], v165 offset:2048
	ds_read_b128 v[190:193], v165 offset:3072
	s_add_u32 s60, s60, 0x100000
	s_addc_u32 s61, s61, 0
	s_mov_b32 m0, s64
	v_lshl_add_u64 v[234:235], s[60:61], 0, v[138:139]
	ds_read_b128 v[194:197], v155 offset:32768
	ds_read_b128 v[202:205], v155 offset:33792
	ds_read_b128 v[206:209], v155 offset:34816
	ds_read_b128 v[210:213], v155 offset:35840
	ds_read_b128 v[214:217], v155 offset:36864
	ds_read_b128 v[218:221], v155 offset:37888
	ds_read_b128 v[222:225], v155 offset:38912
	ds_read_b128 v[226:229], v155 offset:39936
	global_load_lds_dwordx4 v[234:235], off
	v_lshl_add_u64 v[234:235], s[60:61], 0, v[134:135]
	s_mov_b32 m0, s65
	s_nop 0
	global_load_lds_dwordx4 v[234:235], off
	s_waitcnt vmcnt(8)
	s_waitcnt lgkmcnt(0)
	s_barrier
	s_setprio 1
	s_waitcnt lgkmcnt(0)
	v_mfma_f32_16x16x32_bf16 v[126:129], v[156:159], v[194:197], v[126:129]
	v_mfma_f32_16x16x32_bf16 v[126:129], v[166:169], v[202:205], v[126:129]
	v_mfma_f32_16x16x32_bf16 v[122:125], v[174:177], v[202:205], v[122:125]
	v_mfma_f32_16x16x32_bf16 v[122:125], v[170:173], v[194:197], v[122:125]
	v_mfma_f32_16x16x32_bf16 v[110:113], v[170:173], v[206:209], v[110:113]
	v_mfma_f32_16x16x32_bf16 v[110:113], v[174:177], v[210:213], v[110:113]
	v_mfma_f32_16x16x32_bf16 v[118:121], v[166:169], v[210:213], v[118:121]
	v_mfma_f32_16x16x32_bf16 v[118:121], v[156:159], v[206:209], v[118:121]
	v_mfma_f32_16x16x32_bf16 v[102:105], v[156:159], v[214:217], v[102:105]
	v_mfma_f32_16x16x32_bf16 v[102:105], v[166:169], v[218:221], v[102:105]
	v_mfma_f32_16x16x32_bf16 v[94:97], v[174:177], v[218:221], v[94:97]
	v_mfma_f32_16x16x32_bf16 v[94:97], v[170:173], v[214:217], v[94:97]
	v_mfma_f32_16x16x32_bf16 v[78:81], v[170:173], v[222:225], v[78:81]
	v_mfma_f32_16x16x32_bf16 v[78:81], v[174:177], v[226:229], v[78:81]
	v_mfma_f32_16x16x32_bf16 v[86:89], v[166:169], v[226:229], v[86:89]
	v_mfma_f32_16x16x32_bf16 v[86:89], v[156:159], v[222:225], v[86:89]
	s_setprio 0
	s_setprio 1
	v_mfma_f32_16x16x32_bf16 v[114:117], v[178:181], v[194:197], v[114:117]
	v_mfma_f32_16x16x32_bf16 v[114:117], v[182:185], v[202:205], v[114:117]
	v_mfma_f32_16x16x32_bf16 v[106:109], v[190:193], v[202:205], v[106:109]
	v_mfma_f32_16x16x32_bf16 v[106:109], v[186:189], v[194:197], v[106:109]
	v_mfma_f32_16x16x32_bf16 v[90:93], v[186:189], v[206:209], v[90:93]
	v_mfma_f32_16x16x32_bf16 v[90:93], v[190:193], v[210:213], v[90:93]
	v_mfma_f32_16x16x32_bf16 v[98:101], v[182:185], v[210:213], v[98:101]
	v_mfma_f32_16x16x32_bf16 v[98:101], v[178:181], v[206:209], v[98:101]
	v_mfma_f32_16x16x32_bf16 v[82:85], v[178:181], v[214:217], v[82:85]
	v_mfma_f32_16x16x32_bf16 v[82:85], v[182:185], v[218:221], v[82:85]
	v_mfma_f32_16x16x32_bf16 v[74:77], v[190:193], v[218:221], v[74:77]
	v_mfma_f32_16x16x32_bf16 v[74:77], v[186:189], v[214:217], v[74:77]
	v_mfma_f32_16x16x32_bf16 v[66:69], v[186:189], v[222:225], v[66:69]
	v_mfma_f32_16x16x32_bf16 v[66:69], v[190:193], v[226:229], v[66:69]
	v_mfma_f32_16x16x32_bf16 v[70:73], v[182:185], v[226:229], v[70:73]
	v_mfma_f32_16x16x32_bf16 v[70:73], v[178:181], v[222:225], v[70:73]
	s_setprio 0
	s_barrier
	s_add_i32 s36, s36, s38
	v_lshl_add_u64 v[160:161], v[160:161], 0, s[16:17]
	s_mov_b32 m0, s36
	ds_read_b128 v[194:197], v155 offset:49152
	ds_read_b128 v[202:205], v155 offset:50176
	ds_read_b128 v[206:209], v155 offset:51200
	ds_read_b128 v[210:213], v155 offset:52224
	ds_read_b128 v[214:217], v155 offset:53248
	ds_read_b128 v[218:221], v155 offset:54272
	ds_read_b128 v[222:225], v155 offset:55296
	ds_read_b128 v[226:229], v155 offset:56320
	global_load_lds_dwordx4 v[160:161], off
	s_add_i32 m0, s36, 0x2000
	s_add_u32 s58, s58, 0x100080
	v_lshl_add_u64 v[160:161], v[198:199], 0, s[16:17]
	s_addc_u32 s59, s59, 0
	s_add_i32 s36, s37, s38
	global_load_lds_dwordx4 v[160:161], off
	v_lshl_add_u64 v[160:161], s[58:59], 0, v[136:137]
	s_mov_b32 m0, s36
	s_nop 0
	global_load_lds_dwordx4 v[160:161], off
	v_lshl_add_u64 v[160:161], s[58:59], 0, v[132:133]
	s_add_i32 m0, s36, 0x2000
	s_nop 0
	global_load_lds_dwordx4 v[160:161], off
	v_lshl_add_u64 v[160:161], v[230:231], 0, s[16:17]
	s_mov_b32 m0, s66
	s_nop 0
	global_load_lds_dwordx4 v[160:161], off
	v_lshl_add_u64 v[160:161], v[232:233], 0, s[16:17]
	s_mov_b32 m0, s67
	s_nop 0
	global_load_lds_dwordx4 v[160:161], off
	s_waitcnt vmcnt(8)
	s_waitcnt lgkmcnt(0)
	s_barrier
	s_setprio 1
	s_waitcnt lgkmcnt(0)
	v_mfma_f32_16x16x32_bf16 v[62:65], v[156:159], v[194:197], v[62:65]
	v_mfma_f32_16x16x32_bf16 v[62:65], v[166:169], v[202:205], v[62:65]
	v_mfma_f32_16x16x32_bf16 v[58:61], v[174:177], v[202:205], v[58:61]
	v_mfma_f32_16x16x32_bf16 v[58:61], v[170:173], v[194:197], v[58:61]
	v_mfma_f32_16x16x32_bf16 v[46:49], v[170:173], v[206:209], v[46:49]
	v_mfma_f32_16x16x32_bf16 v[46:49], v[174:177], v[210:213], v[46:49]
	v_mfma_f32_16x16x32_bf16 v[54:57], v[166:169], v[210:213], v[54:57]
	v_mfma_f32_16x16x32_bf16 v[54:57], v[156:159], v[206:209], v[54:57]
	v_mfma_f32_16x16x32_bf16 v[38:41], v[156:159], v[214:217], v[38:41]
	v_mfma_f32_16x16x32_bf16 v[38:41], v[166:169], v[218:221], v[38:41]
	v_mfma_f32_16x16x32_bf16 v[30:33], v[174:177], v[218:221], v[30:33]
	v_mfma_f32_16x16x32_bf16 v[30:33], v[170:173], v[214:217], v[30:33]
	v_mfma_f32_16x16x32_bf16 v[14:17], v[170:173], v[222:225], v[14:17]
	v_mfma_f32_16x16x32_bf16 v[14:17], v[174:177], v[226:229], v[14:17]
	v_mfma_f32_16x16x32_bf16 v[22:25], v[166:169], v[226:229], v[22:25]
	v_mfma_f32_16x16x32_bf16 v[22:25], v[156:159], v[222:225], v[22:25]
	s_setprio 0
	s_setprio 1
	v_mfma_f32_16x16x32_bf16 v[50:53], v[178:181], v[194:197], v[50:53]
	v_mfma_f32_16x16x32_bf16 v[50:53], v[182:185], v[202:205], v[50:53]
	v_mfma_f32_16x16x32_bf16 v[42:45], v[190:193], v[202:205], v[42:45]
	v_mfma_f32_16x16x32_bf16 v[42:45], v[186:189], v[194:197], v[42:45]
	v_mfma_f32_16x16x32_bf16 v[26:29], v[186:189], v[206:209], v[26:29]
	v_mfma_f32_16x16x32_bf16 v[26:29], v[190:193], v[210:213], v[26:29]
	v_mfma_f32_16x16x32_bf16 v[34:37], v[182:185], v[210:213], v[34:37]
	v_mfma_f32_16x16x32_bf16 v[34:37], v[178:181], v[206:209], v[34:37]
	v_mfma_f32_16x16x32_bf16 v[18:21], v[178:181], v[214:217], v[18:21]
	v_mfma_f32_16x16x32_bf16 v[18:21], v[182:185], v[218:221], v[18:21]
	v_mfma_f32_16x16x32_bf16 v[10:13], v[190:193], v[218:221], v[10:13]
	v_mfma_f32_16x16x32_bf16 v[10:13], v[186:189], v[214:217], v[10:13]
	v_mfma_f32_16x16x32_bf16 v[2:5], v[186:189], v[222:225], v[2:5]
	v_mfma_f32_16x16x32_bf16 v[2:5], v[190:193], v[226:229], v[2:5]
	v_mfma_f32_16x16x32_bf16 v[6:9], v[182:185], v[226:229], v[6:9]
	v_mfma_f32_16x16x32_bf16 v[6:9], v[178:181], v[222:225], v[6:9]
	s_setprio 0
	s_barrier
	s_add_i32 s78, s78, 2
	s_add_u32 s56, s56, 0x100
	s_addc_u32 s57, s57, 0
	s_add_u32 s76, s76, 0x100
	s_addc_u32 s77, s77, 0
	s_cmp_gt_u32 s78, 61
	s_cbranch_scc0 .LBB0_1685
	s_and_b64 vcc, exec, s[18:19]
	s_cbranch_vccz .LBB0_1688
	s_barrier

.LBB0_1701:
	s_add_u32 s36, s56, s44
	s_addc_u32 s37, s57, 0
	s_add_u32 s64, s36, 0x100
	s_addc_u32 s65, s37, 0
	s_and_b64 s[62:63], s[60:61], exec
	s_cselect_b32 s65, s21, s65
	s_cselect_b32 s64, s86, s64
	s_add_u32 s44, s54, s44
	s_addc_u32 s62, s55, 0
	s_add_u32 s44, s44, 0x100
	s_addc_u32 s62, s62, 0
	s_and_b64 s[60:61], s[60:61], exec
	s_cselect_b32 s67, s25, s62
	s_cselect_b32 s66, s87, s44
	s_add_u32 s70, s36, 0x10080
	s_addc_u32 s71, s37, 0
	s_add_i32 s97, s81, s39
	ds_read_b128 v[152:155], v147
	ds_read_b128 v[156:159], v147 offset:1024
	ds_read_b128 v[166:169], v147 offset:2048
	ds_read_b128 v[170:173], v147 offset:3072
	ds_read_b128 v[174:177], v150
	ds_read_b128 v[178:181], v150 offset:1024
	ds_read_b128 v[182:185], v150 offset:2048
	ds_read_b128 v[186:189], v150 offset:3072
	s_add_i32 m0, s74, 0xc000
	s_add_i32 vcc_lo, s74, 0xe000
	s_add_i32 s94, s97, 0x2000
	s_add_u32 s68, s66, 0x10000
	s_addc_u32 s69, s67, 0
	s_add_i32 s96, s82, s39
	s_add_i32 s95, s96, 0x2000
	s_add_i32 s93, 0, 0x18000
	s_add_i32 s92, 0, 0x1c000
	s_add_u32 s62, s64, 0x10000
	s_addc_u32 s63, s65, 0
	s_add_i32 s91, s93, s39
	s_add_i32 s89, s91, 0x2000
	s_add_u32 s60, s66, 0x10080
	s_addc_u32 s61, s67, 0
	s_add_i32 s90, s92, s39
	s_add_i32 s44, s90, 0x2000
	v_lshl_add_u64 v[160:161], s[70:71], 0, v[138:139]
	ds_read_b128 v[190:193], v151
	ds_read_b128 v[194:197], v151 offset:1024
	ds_read_b128 v[202:205], v151 offset:2048
	ds_read_b128 v[206:209], v151 offset:3072
	ds_read_b128 v[210:213], v151 offset:4096
	ds_read_b128 v[214:217], v151 offset:5120
	ds_read_b128 v[218:221], v151 offset:6144
	ds_read_b128 v[222:225], v151 offset:7168
	global_load_lds_dwordx4 v[160:161], off
	v_lshl_add_u64 v[160:161], s[70:71], 0, v[134:135]
	s_mov_b32 m0, vcc_lo
	s_nop 0
	global_load_lds_dwordx4 v[160:161], off
	s_waitcnt vmcnt(8)
	s_waitcnt lgkmcnt(0)
	s_barrier
	s_setprio 1
	s_waitcnt lgkmcnt(0)
	v_mfma_f32_16x16x32_bf16 v[126:129], v[152:155], v[190:193], v[126:129]
	v_mfma_f32_16x16x32_bf16 v[126:129], v[156:159], v[194:197], v[126:129]
	v_mfma_f32_16x16x32_bf16 v[122:125], v[170:173], v[194:197], v[122:125]
	v_mfma_f32_16x16x32_bf16 v[122:125], v[166:169], v[190:193], v[122:125]
	v_mfma_f32_16x16x32_bf16 v[110:113], v[166:169], v[202:205], v[110:113]
	v_mfma_f32_16x16x32_bf16 v[110:113], v[170:173], v[206:209], v[110:113]
	v_mfma_f32_16x16x32_bf16 v[118:121], v[156:159], v[206:209], v[118:121]
	v_mfma_f32_16x16x32_bf16 v[118:121], v[152:155], v[202:205], v[118:121]
	v_mfma_f32_16x16x32_bf16 v[102:105], v[152:155], v[210:213], v[102:105]
	v_mfma_f32_16x16x32_bf16 v[102:105], v[156:159], v[214:217], v[102:105]
	v_mfma_f32_16x16x32_bf16 v[94:97], v[170:173], v[214:217], v[94:97]
	v_mfma_f32_16x16x32_bf16 v[94:97], v[166:169], v[210:213], v[94:97]
	v_mfma_f32_16x16x32_bf16 v[78:81], v[166:169], v[218:221], v[78:81]
	v_mfma_f32_16x16x32_bf16 v[78:81], v[170:173], v[222:225], v[78:81]
	v_mfma_f32_16x16x32_bf16 v[86:89], v[156:159], v[222:225], v[86:89]
	v_mfma_f32_16x16x32_bf16 v[86:89], v[152:155], v[218:221], v[86:89]
	s_setprio 0
	s_setprio 1
	v_mfma_f32_16x16x32_bf16 v[114:117], v[174:177], v[190:193], v[114:117]
	v_mfma_f32_16x16x32_bf16 v[114:117], v[178:181], v[194:197], v[114:117]
	v_mfma_f32_16x16x32_bf16 v[106:109], v[186:189], v[194:197], v[106:109]
	v_mfma_f32_16x16x32_bf16 v[106:109], v[182:185], v[190:193], v[106:109]
	v_mfma_f32_16x16x32_bf16 v[90:93], v[182:185], v[202:205], v[90:93]
	v_mfma_f32_16x16x32_bf16 v[90:93], v[186:189], v[206:209], v[90:93]
	v_mfma_f32_16x16x32_bf16 v[98:101], v[178:181], v[206:209], v[98:101]
	v_mfma_f32_16x16x32_bf16 v[98:101], v[174:177], v[202:205], v[98:101]
	v_mfma_f32_16x16x32_bf16 v[82:85], v[174:177], v[210:213], v[82:85]
	v_mfma_f32_16x16x32_bf16 v[82:85], v[178:181], v[214:217], v[82:85]
	v_mfma_f32_16x16x32_bf16 v[74:77], v[186:189], v[214:217], v[74:77]
	v_mfma_f32_16x16x32_bf16 v[74:77], v[182:185], v[210:213], v[74:77]
	v_mfma_f32_16x16x32_bf16 v[66:69], v[182:185], v[218:221], v[66:69]
	v_mfma_f32_16x16x32_bf16 v[66:69], v[186:189], v[222:225], v[66:69]
	v_mfma_f32_16x16x32_bf16 v[70:73], v[178:181], v[222:225], v[70:73]
	v_mfma_f32_16x16x32_bf16 v[70:73], v[174:177], v[218:221], v[70:73]
	s_setprio 0
	s_barrier
	s_mov_b32 m0, s97
	v_lshl_add_u64 v[160:161], s[66:67], 0, v[136:137]
	ds_read_b128 v[190:193], v151 offset:16384
	ds_read_b128 v[194:197], v151 offset:17408
	ds_read_b128 v[202:205], v151 offset:18432
	ds_read_b128 v[206:209], v151 offset:19456
	ds_read_b128 v[210:213], v151 offset:20480
	ds_read_b128 v[214:217], v151 offset:21504
	ds_read_b128 v[218:221], v151 offset:22528
	ds_read_b128 v[222:225], v151 offset:23552
	global_load_lds_dwordx4 v[160:161], off
	v_lshl_add_u64 v[198:199], s[66:67], 0, v[132:133]
	s_mov_b32 m0, s94
	v_lshl_add_u64 v[226:227], s[68:69], 0, v[136:137]
	global_load_lds_dwordx4 v[198:199], off
	s_mov_b32 m0, s96
	v_lshl_add_u64 v[228:229], s[64:65], 0, v[134:135]
	global_load_lds_dwordx4 v[226:227], off
	v_lshl_add_u64 v[226:227], s[68:69], 0, v[132:133]
	s_mov_b32 m0, s95
	s_nop 0
	global_load_lds_dwordx4 v[226:227], off
	v_lshl_add_u64 v[226:227], s[64:65], 0, v[138:139]
	s_mov_b32 m0, s74
	s_nop 0
	global_load_lds_dwordx4 v[226:227], off
	s_mov_b32 m0, s75
	s_nop 0
	global_load_lds_dwordx4 v[228:229], off
	s_waitcnt vmcnt(8)
	s_waitcnt lgkmcnt(0)
	s_barrier
	s_setprio 1
	s_waitcnt lgkmcnt(0)
	v_mfma_f32_16x16x32_bf16 v[62:65], v[152:155], v[190:193], v[62:65]
	v_mfma_f32_16x16x32_bf16 v[62:65], v[156:159], v[194:197], v[62:65]
	v_mfma_f32_16x16x32_bf16 v[58:61], v[170:173], v[194:197], v[58:61]
	v_mfma_f32_16x16x32_bf16 v[58:61], v[166:169], v[190:193], v[58:61]
	v_mfma_f32_16x16x32_bf16 v[46:49], v[166:169], v[202:205], v[46:49]
	v_mfma_f32_16x16x32_bf16 v[46:49], v[170:173], v[206:209], v[46:49]
	v_mfma_f32_16x16x32_bf16 v[54:57], v[156:159], v[206:209], v[54:57]
	v_mfma_f32_16x16x32_bf16 v[54:57], v[152:155], v[202:205], v[54:57]
	v_mfma_f32_16x16x32_bf16 v[38:41], v[152:155], v[210:213], v[38:41]
	v_mfma_f32_16x16x32_bf16 v[38:41], v[156:159], v[214:217], v[38:41]
	v_mfma_f32_16x16x32_bf16 v[30:33], v[170:173], v[214:217], v[30:33]
	v_mfma_f32_16x16x32_bf16 v[30:33], v[166:169], v[210:213], v[30:33]
	v_mfma_f32_16x16x32_bf16 v[14:17], v[166:169], v[218:221], v[14:17]
	v_mfma_f32_16x16x32_bf16 v[14:17], v[170:173], v[222:225], v[14:17]
	v_mfma_f32_16x16x32_bf16 v[22:25], v[156:159], v[222:225], v[22:25]
	v_mfma_f32_16x16x32_bf16 v[22:25], v[152:155], v[218:221], v[22:25]
	s_setprio 0
	s_setprio 1
	v_mfma_f32_16x16x32_bf16 v[50:53], v[174:177], v[190:193], v[50:53]
	v_mfma_f32_16x16x32_bf16 v[50:53], v[178:181], v[194:197], v[50:53]
	v_mfma_f32_16x16x32_bf16 v[42:45], v[186:189], v[194:197], v[42:45]
	v_mfma_f32_16x16x32_bf16 v[42:45], v[182:185], v[190:193], v[42:45]
	v_mfma_f32_16x16x32_bf16 v[26:29], v[182:185], v[202:205], v[26:29]
	v_mfma_f32_16x16x32_bf16 v[26:29], v[186:189], v[206:209], v[26:29]
	v_mfma_f32_16x16x32_bf16 v[34:37], v[178:181], v[206:209], v[34:37]
	v_mfma_f32_16x16x32_bf16 v[34:37], v[174:177], v[202:205], v[34:37]
	v_mfma_f32_16x16x32_bf16 v[18:21], v[174:177], v[210:213], v[18:21]
	v_mfma_f32_16x16x32_bf16 v[18:21], v[178:181], v[214:217], v[18:21]
	v_mfma_f32_16x16x32_bf16 v[10:13], v[186:189], v[214:217], v[10:13]
	v_mfma_f32_16x16x32_bf16 v[10:13], v[182:185], v[210:213], v[10:13]
	v_mfma_f32_16x16x32_bf16 v[2:5], v[182:185], v[218:221], v[2:5]
	v_mfma_f32_16x16x32_bf16 v[2:5], v[186:189], v[222:225], v[2:5]
	v_mfma_f32_16x16x32_bf16 v[6:9], v[178:181], v[222:225], v[6:9]
	v_mfma_f32_16x16x32_bf16 v[6:9], v[174:177], v[218:221], v[6:9]
	s_setprio 0
	s_barrier
	v_add_u32_e32 v165, s93, v145
	ds_read_b128 v[152:155], v165
	ds_read_b128 v[156:159], v165 offset:1024
	ds_read_b128 v[166:169], v165 offset:2048
	ds_read_b128 v[170:173], v165 offset:3072
	v_add_u32_e32 v165, s92, v145
	ds_read_b128 v[174:177], v165
	ds_read_b128 v[178:181], v165 offset:1024
	ds_read_b128 v[182:185], v165 offset:2048
	ds_read_b128 v[186:189], v165 offset:3072
	s_mov_b32 m0, s76
	v_lshl_add_u64 v[230:231], s[62:63], 0, v[138:139]
	ds_read_b128 v[190:193], v151 offset:32768
	ds_read_b128 v[194:197], v151 offset:33792
	ds_read_b128 v[202:205], v151 offset:34816
	ds_read_b128 v[206:209], v151 offset:35840
	ds_read_b128 v[210:213], v151 offset:36864
	ds_read_b128 v[214:217], v151 offset:37888
	ds_read_b128 v[218:221], v151 offset:38912
	ds_read_b128 v[222:225], v151 offset:39936
	global_load_lds_dwordx4 v[230:231], off
	v_lshl_add_u64 v[230:231], s[62:63], 0, v[134:135]
	s_mov_b32 m0, s77
	s_nop 0
	global_load_lds_dwordx4 v[230:231], off
	s_waitcnt vmcnt(8)
	s_waitcnt lgkmcnt(0)
	s_barrier
	s_setprio 1
	s_waitcnt lgkmcnt(0)
	v_mfma_f32_16x16x32_bf16 v[126:129], v[152:155], v[190:193], v[126:129]
	v_mfma_f32_16x16x32_bf16 v[126:129], v[156:159], v[194:197], v[126:129]
	v_mfma_f32_16x16x32_bf16 v[122:125], v[170:173], v[194:197], v[122:125]
	v_mfma_f32_16x16x32_bf16 v[122:125], v[166:169], v[190:193], v[122:125]
	v_mfma_f32_16x16x32_bf16 v[110:113], v[166:169], v[202:205], v[110:113]
	v_mfma_f32_16x16x32_bf16 v[110:113], v[170:173], v[206:209], v[110:113]
	v_mfma_f32_16x16x32_bf16 v[118:121], v[156:159], v[206:209], v[118:121]
	v_mfma_f32_16x16x32_bf16 v[118:121], v[152:155], v[202:205], v[118:121]
	v_mfma_f32_16x16x32_bf16 v[102:105], v[152:155], v[210:213], v[102:105]
	v_mfma_f32_16x16x32_bf16 v[102:105], v[156:159], v[214:217], v[102:105]
	v_mfma_f32_16x16x32_bf16 v[94:97], v[170:173], v[214:217], v[94:97]
	v_mfma_f32_16x16x32_bf16 v[94:97], v[166:169], v[210:213], v[94:97]
	v_mfma_f32_16x16x32_bf16 v[78:81], v[166:169], v[218:221], v[78:81]
	v_mfma_f32_16x16x32_bf16 v[78:81], v[170:173], v[222:225], v[78:81]
	v_mfma_f32_16x16x32_bf16 v[86:89], v[156:159], v[222:225], v[86:89]
	v_mfma_f32_16x16x32_bf16 v[86:89], v[152:155], v[218:221], v[86:89]
	s_setprio 0
	s_setprio 1
	v_mfma_f32_16x16x32_bf16 v[114:117], v[174:177], v[190:193], v[114:117]
	v_mfma_f32_16x16x32_bf16 v[114:117], v[178:181], v[194:197], v[114:117]
	v_mfma_f32_16x16x32_bf16 v[106:109], v[186:189], v[194:197], v[106:109]
	v_mfma_f32_16x16x32_bf16 v[106:109], v[182:185], v[190:193], v[106:109]
	v_mfma_f32_16x16x32_bf16 v[90:93], v[182:185], v[202:205], v[90:93]
	v_mfma_f32_16x16x32_bf16 v[90:93], v[186:189], v[206:209], v[90:93]
	v_mfma_f32_16x16x32_bf16 v[98:101], v[178:181], v[206:209], v[98:101]
	v_mfma_f32_16x16x32_bf16 v[98:101], v[174:177], v[202:205], v[98:101]
	v_mfma_f32_16x16x32_bf16 v[82:85], v[174:177], v[210:213], v[82:85]
	v_mfma_f32_16x16x32_bf16 v[82:85], v[178:181], v[214:217], v[82:85]
	v_mfma_f32_16x16x32_bf16 v[74:77], v[186:189], v[214:217], v[74:77]
	v_mfma_f32_16x16x32_bf16 v[74:77], v[182:185], v[210:213], v[74:77]
	v_mfma_f32_16x16x32_bf16 v[66:69], v[182:185], v[218:221], v[66:69]
	v_mfma_f32_16x16x32_bf16 v[66:69], v[186:189], v[222:225], v[66:69]
	v_mfma_f32_16x16x32_bf16 v[70:73], v[178:181], v[222:225], v[70:73]
	v_mfma_f32_16x16x32_bf16 v[70:73], v[174:177], v[218:221], v[70:73]
	s_setprio 0
	s_barrier
	s_mov_b32 m0, s91
	v_lshl_add_u64 v[160:161], v[160:161], 0, s[14:15]
	ds_read_b128 v[190:193], v151 offset:49152
	ds_read_b128 v[194:197], v151 offset:50176
	ds_read_b128 v[202:205], v151 offset:51200
	ds_read_b128 v[206:209], v151 offset:52224
	ds_read_b128 v[210:213], v151 offset:53248
	ds_read_b128 v[214:217], v151 offset:54272
	ds_read_b128 v[218:221], v151 offset:55296
	ds_read_b128 v[222:225], v151 offset:56320
	global_load_lds_dwordx4 v[160:161], off
	v_lshl_add_u64 v[160:161], v[198:199], 0, s[14:15]
	s_mov_b32 m0, s89
	s_nop 0
	global_load_lds_dwordx4 v[160:161], off
	v_lshl_add_u64 v[160:161], s[60:61], 0, v[136:137]
	s_mov_b32 m0, s90
	s_nop 0
	global_load_lds_dwordx4 v[160:161], off
	v_lshl_add_u64 v[160:161], s[60:61], 0, v[132:133]
	s_mov_b32 m0, s44
	s_nop 0
	global_load_lds_dwordx4 v[160:161], off
	v_lshl_add_u64 v[160:161], v[226:227], 0, s[14:15]
	s_mov_b32 m0, s79
	s_nop 0
	global_load_lds_dwordx4 v[160:161], off
	v_lshl_add_u64 v[160:161], v[228:229], 0, s[14:15]
	s_mov_b32 m0, s80
	s_nop 0
	global_load_lds_dwordx4 v[160:161], off
	s_waitcnt vmcnt(8)
	s_waitcnt lgkmcnt(0)
	s_barrier
	s_setprio 1
	s_waitcnt lgkmcnt(0)
	v_mfma_f32_16x16x32_bf16 v[62:65], v[152:155], v[190:193], v[62:65]
	v_mfma_f32_16x16x32_bf16 v[62:65], v[156:159], v[194:197], v[62:65]
	v_mfma_f32_16x16x32_bf16 v[58:61], v[170:173], v[194:197], v[58:61]
	v_mfma_f32_16x16x32_bf16 v[58:61], v[166:169], v[190:193], v[58:61]
	v_mfma_f32_16x16x32_bf16 v[46:49], v[166:169], v[202:205], v[46:49]
	v_mfma_f32_16x16x32_bf16 v[46:49], v[170:173], v[206:209], v[46:49]
	v_mfma_f32_16x16x32_bf16 v[54:57], v[156:159], v[206:209], v[54:57]
	v_mfma_f32_16x16x32_bf16 v[54:57], v[152:155], v[202:205], v[54:57]
	v_mfma_f32_16x16x32_bf16 v[38:41], v[152:155], v[210:213], v[38:41]
	v_mfma_f32_16x16x32_bf16 v[38:41], v[156:159], v[214:217], v[38:41]
	v_mfma_f32_16x16x32_bf16 v[30:33], v[170:173], v[214:217], v[30:33]
	v_mfma_f32_16x16x32_bf16 v[30:33], v[166:169], v[210:213], v[30:33]
	v_mfma_f32_16x16x32_bf16 v[14:17], v[166:169], v[218:221], v[14:17]
	v_mfma_f32_16x16x32_bf16 v[14:17], v[170:173], v[222:225], v[14:17]
	v_mfma_f32_16x16x32_bf16 v[22:25], v[156:159], v[222:225], v[22:25]
	v_mfma_f32_16x16x32_bf16 v[22:25], v[152:155], v[218:221], v[22:25]
	s_setprio 0
	s_setprio 1
	v_mfma_f32_16x16x32_bf16 v[50:53], v[174:177], v[190:193], v[50:53]
	v_mfma_f32_16x16x32_bf16 v[50:53], v[178:181], v[194:197], v[50:53]
	v_mfma_f32_16x16x32_bf16 v[42:45], v[186:189], v[194:197], v[42:45]
	v_mfma_f32_16x16x32_bf16 v[42:45], v[182:185], v[190:193], v[42:45]
	v_mfma_f32_16x16x32_bf16 v[26:29], v[182:185], v[202:205], v[26:29]
	v_mfma_f32_16x16x32_bf16 v[26:29], v[186:189], v[206:209], v[26:29]
	v_mfma_f32_16x16x32_bf16 v[34:37], v[178:181], v[206:209], v[34:37]
	v_mfma_f32_16x16x32_bf16 v[34:37], v[174:177], v[202:205], v[34:37]
	v_mfma_f32_16x16x32_bf16 v[18:21], v[174:177], v[210:213], v[18:21]
	v_mfma_f32_16x16x32_bf16 v[18:21], v[178:181], v[214:217], v[18:21]
	v_mfma_f32_16x16x32_bf16 v[10:13], v[186:189], v[214:217], v[10:13]
	v_mfma_f32_16x16x32_bf16 v[10:13], v[182:185], v[210:213], v[10:13]
	v_mfma_f32_16x16x32_bf16 v[2:5], v[182:185], v[218:221], v[2:5]
	v_mfma_f32_16x16x32_bf16 v[2:5], v[186:189], v[222:225], v[2:5]
	v_mfma_f32_16x16x32_bf16 v[6:9], v[178:181], v[222:225], v[6:9]
	v_mfma_f32_16x16x32_bf16 v[6:9], v[174:177], v[218:221], v[6:9]
	s_setprio 0
	s_barrier
	s_movk_i32 s44, 0x100
	s_andn2_b64 vcc, exec, s[58:59]
	s_mov_b64 s[60:61], -1
	s_mov_b64 s[58:59], 0
	s_cbranch_vccz .LBB0_1701
	s_and_b64 vcc, exec, s[16:17]
	s_cbranch_vccz .LBB0_1704
	s_barrier

.LBB0_1902:
	ds_read_b128 v[148:151], v156
	ds_read_b128 v[166:169], v156 offset:1024
	ds_read_b128 v[170:173], v156 offset:2048
	ds_read_b128 v[174:177], v156 offset:3072
	ds_read_b128 v[178:181], v157
	ds_read_b128 v[182:185], v157 offset:1024
	ds_read_b128 v[186:189], v157 offset:2048
	ds_read_b128 v[190:193], v157 offset:3072
	s_add_i32 s92, s58, 2
	s_add_u32 s36, s56, 0xffd50080
	s_addc_u32 s37, s57, -1
	s_cmp_eq_u32 s89, s58
	s_cselect_b32 s58, s54, s90
	s_cselect_b32 s61, s53, s37
	s_cselect_b32 s60, s52, s36
	s_cselect_b32 s59, s55, s91
	v_lshl_add_u64 v[152:153], s[56:57], 0, v[142:143]
	s_add_i32 m0, s67, 0xc000
	ds_read_b128 v[194:197], v158
	ds_read_b128 v[202:205], v158 offset:1024
	ds_read_b128 v[206:209], v158 offset:2048
	ds_read_b128 v[210:213], v158 offset:3072
	ds_read_b128 v[214:217], v158 offset:4096
	ds_read_b128 v[218:221], v158 offset:5120
	ds_read_b128 v[222:225], v158 offset:6144
	ds_read_b128 v[226:229], v158 offset:7168
	global_load_lds_dwordx4 v[152:153], off
	v_lshl_add_u64 v[152:153], s[56:57], 0, v[144:145]
	s_add_i32 m0, s67, 0xe000
	s_nop 0
	global_load_lds_dwordx4 v[152:153], off
	s_waitcnt vmcnt(8)
	s_waitcnt lgkmcnt(0)
	s_barrier
	s_setprio 1
	s_waitcnt lgkmcnt(0)
	v_mfma_f32_16x16x32_bf16 v[126:129], v[148:151], v[194:197], v[126:129]
	v_mfma_f32_16x16x32_bf16 v[126:129], v[166:169], v[202:205], v[126:129]
	v_mfma_f32_16x16x32_bf16 v[122:125], v[174:177], v[202:205], v[122:125]
	v_mfma_f32_16x16x32_bf16 v[122:125], v[170:173], v[194:197], v[122:125]
	v_mfma_f32_16x16x32_bf16 v[106:109], v[170:173], v[206:209], v[106:109]
	v_mfma_f32_16x16x32_bf16 v[106:109], v[174:177], v[210:213], v[106:109]
	v_mfma_f32_16x16x32_bf16 v[110:113], v[166:169], v[210:213], v[110:113]
	v_mfma_f32_16x16x32_bf16 v[110:113], v[148:151], v[206:209], v[110:113]
	v_mfma_f32_16x16x32_bf16 v[94:97], v[148:151], v[214:217], v[94:97]
	v_mfma_f32_16x16x32_bf16 v[94:97], v[166:169], v[218:221], v[94:97]
	v_mfma_f32_16x16x32_bf16 v[90:93], v[174:177], v[218:221], v[90:93]
	v_mfma_f32_16x16x32_bf16 v[90:93], v[170:173], v[214:217], v[90:93]
	v_mfma_f32_16x16x32_bf16 v[74:77], v[170:173], v[222:225], v[74:77]
	v_mfma_f32_16x16x32_bf16 v[74:77], v[174:177], v[226:229], v[74:77]
	v_mfma_f32_16x16x32_bf16 v[78:81], v[166:169], v[226:229], v[78:81]
	v_mfma_f32_16x16x32_bf16 v[78:81], v[148:151], v[222:225], v[78:81]
	s_setprio 0
	s_setprio 1
	v_mfma_f32_16x16x32_bf16 v[118:121], v[178:181], v[194:197], v[118:121]
	v_mfma_f32_16x16x32_bf16 v[118:121], v[182:185], v[202:205], v[118:121]
	v_mfma_f32_16x16x32_bf16 v[114:117], v[190:193], v[202:205], v[114:117]
	v_mfma_f32_16x16x32_bf16 v[114:117], v[186:189], v[194:197], v[114:117]
	v_mfma_f32_16x16x32_bf16 v[98:101], v[186:189], v[206:209], v[98:101]
	v_mfma_f32_16x16x32_bf16 v[98:101], v[190:193], v[210:213], v[98:101]
	v_mfma_f32_16x16x32_bf16 v[102:105], v[182:185], v[210:213], v[102:105]
	v_mfma_f32_16x16x32_bf16 v[102:105], v[178:181], v[206:209], v[102:105]
	v_mfma_f32_16x16x32_bf16 v[86:89], v[178:181], v[214:217], v[86:89]
	v_mfma_f32_16x16x32_bf16 v[86:89], v[182:185], v[218:221], v[86:89]
	v_mfma_f32_16x16x32_bf16 v[82:85], v[190:193], v[218:221], v[82:85]
	v_mfma_f32_16x16x32_bf16 v[82:85], v[186:189], v[214:217], v[82:85]
	v_mfma_f32_16x16x32_bf16 v[66:69], v[186:189], v[222:225], v[66:69]
	v_mfma_f32_16x16x32_bf16 v[66:69], v[190:193], v[226:229], v[66:69]
	v_mfma_f32_16x16x32_bf16 v[70:73], v[182:185], v[226:229], v[70:73]
	v_mfma_f32_16x16x32_bf16 v[70:73], v[178:181], v[222:225], v[70:73]
	s_setprio 0
	s_barrier
	s_add_i32 s36, s77, s64
	v_lshl_add_u64 v[152:153], s[58:59], 0, v[134:135]
	s_mov_b32 m0, s36
	ds_read_b128 v[194:197], v158 offset:16384
	ds_read_b128 v[202:205], v158 offset:17408
	ds_read_b128 v[206:209], v158 offset:18432
	ds_read_b128 v[210:213], v158 offset:19456
	ds_read_b128 v[214:217], v158 offset:20480
	ds_read_b128 v[218:221], v158 offset:21504
	ds_read_b128 v[222:225], v158 offset:22528
	ds_read_b128 v[226:229], v158 offset:23552
	global_load_lds_dwordx4 v[152:153], off
	s_add_i32 m0, s36, 0x2000
	s_add_u32 s94, s58, 0x2b0000
	v_lshl_add_u64 v[160:161], s[58:59], 0, v[138:139]
	s_addc_u32 s95, s59, 0
	s_add_i32 s36, s78, s64
	global_load_lds_dwordx4 v[160:161], off
	v_lshl_add_u64 v[198:199], s[94:95], 0, v[134:135]
	s_mov_b32 m0, s36
	v_lshl_add_u64 v[230:231], s[60:61], 0, v[136:137]
	global_load_lds_dwordx4 v[198:199], off
	v_lshl_add_u64 v[198:199], s[94:95], 0, v[138:139]
	s_add_i32 m0, s36, 0x2000
	s_nop 0
	global_load_lds_dwordx4 v[198:199], off
	v_lshl_add_u64 v[198:199], s[60:61], 0, v[132:133]
	s_mov_b32 m0, s67
	s_nop 0
	global_load_lds_dwordx4 v[198:199], off
	s_mov_b32 m0, s68
	s_nop 0
	global_load_lds_dwordx4 v[230:231], off
	s_waitcnt vmcnt(8)
	s_waitcnt lgkmcnt(0)
	s_barrier
	s_setprio 1
	s_waitcnt lgkmcnt(0)
	v_mfma_f32_16x16x32_bf16 v[62:65], v[148:151], v[194:197], v[62:65]
	v_mfma_f32_16x16x32_bf16 v[62:65], v[166:169], v[202:205], v[62:65]
	v_mfma_f32_16x16x32_bf16 v[58:61], v[174:177], v[202:205], v[58:61]
	v_mfma_f32_16x16x32_bf16 v[58:61], v[170:173], v[194:197], v[58:61]
	v_mfma_f32_16x16x32_bf16 v[42:45], v[170:173], v[206:209], v[42:45]
	v_mfma_f32_16x16x32_bf16 v[42:45], v[174:177], v[210:213], v[42:45]
	v_mfma_f32_16x16x32_bf16 v[46:49], v[166:169], v[210:213], v[46:49]
	v_mfma_f32_16x16x32_bf16 v[46:49], v[148:151], v[206:209], v[46:49]
	v_mfma_f32_16x16x32_bf16 v[30:33], v[148:151], v[214:217], v[30:33]
	v_mfma_f32_16x16x32_bf16 v[30:33], v[166:169], v[218:221], v[30:33]
	v_mfma_f32_16x16x32_bf16 v[26:29], v[174:177], v[218:221], v[26:29]
	v_mfma_f32_16x16x32_bf16 v[26:29], v[170:173], v[214:217], v[26:29]
	v_mfma_f32_16x16x32_bf16 v[10:13], v[170:173], v[222:225], v[10:13]
	v_mfma_f32_16x16x32_bf16 v[10:13], v[174:177], v[226:229], v[10:13]
	v_mfma_f32_16x16x32_bf16 v[14:17], v[166:169], v[226:229], v[14:17]
	v_mfma_f32_16x16x32_bf16 v[14:17], v[148:151], v[222:225], v[14:17]
	s_setprio 0
	s_setprio 1
	v_mfma_f32_16x16x32_bf16 v[54:57], v[178:181], v[194:197], v[54:57]
	v_mfma_f32_16x16x32_bf16 v[54:57], v[182:185], v[202:205], v[54:57]
	v_mfma_f32_16x16x32_bf16 v[50:53], v[190:193], v[202:205], v[50:53]
	v_mfma_f32_16x16x32_bf16 v[50:53], v[186:189], v[194:197], v[50:53]
	v_mfma_f32_16x16x32_bf16 v[34:37], v[186:189], v[206:209], v[34:37]
	v_mfma_f32_16x16x32_bf16 v[34:37], v[190:193], v[210:213], v[34:37]
	v_mfma_f32_16x16x32_bf16 v[38:41], v[182:185], v[210:213], v[38:41]
	v_mfma_f32_16x16x32_bf16 v[38:41], v[178:181], v[206:209], v[38:41]
	v_mfma_f32_16x16x32_bf16 v[22:25], v[178:181], v[214:217], v[22:25]
	v_mfma_f32_16x16x32_bf16 v[22:25], v[182:185], v[218:221], v[22:25]
	v_mfma_f32_16x16x32_bf16 v[18:21], v[190:193], v[218:221], v[18:21]
	v_mfma_f32_16x16x32_bf16 v[18:21], v[186:189], v[214:217], v[18:21]
	v_mfma_f32_16x16x32_bf16 v[2:5], v[186:189], v[222:225], v[2:5]
	v_mfma_f32_16x16x32_bf16 v[2:5], v[190:193], v[226:229], v[2:5]
	v_mfma_f32_16x16x32_bf16 v[6:9], v[182:185], v[226:229], v[6:9]
	v_mfma_f32_16x16x32_bf16 v[6:9], v[178:181], v[222:225], v[6:9]
	s_setprio 0
	s_barrier
	s_add_i32 s36, 0, 0x18000
	v_add_u32_e32 v140, s36, v154
	s_add_i32 s37, 0, 0x1c000
	ds_read_b128 v[148:151], v140
	ds_read_b128 v[166:169], v140 offset:1024
	ds_read_b128 v[170:173], v140 offset:2048
	ds_read_b128 v[174:177], v140 offset:3072
	v_add_u32_e32 v140, s37, v154
	ds_read_b128 v[178:181], v140
	ds_read_b128 v[182:185], v140 offset:1024
	ds_read_b128 v[186:189], v140 offset:2048
	ds_read_b128 v[190:193], v140 offset:3072
	s_add_u32 s60, s60, 0x2b0000
	s_addc_u32 s61, s61, 0
	s_mov_b32 m0, s69
	v_lshl_add_u64 v[232:233], s[60:61], 0, v[132:133]
	ds_read_b128 v[194:197], v158 offset:32768
	ds_read_b128 v[202:205], v158 offset:33792
	ds_read_b128 v[206:209], v158 offset:34816
	ds_read_b128 v[210:213], v158 offset:35840
	ds_read_b128 v[214:217], v158 offset:36864
	ds_read_b128 v[218:221], v158 offset:37888
	ds_read_b128 v[222:225], v158 offset:38912
	ds_read_b128 v[226:229], v158 offset:39936
	global_load_lds_dwordx4 v[232:233], off
	v_lshl_add_u64 v[232:233], s[60:61], 0, v[136:137]
	s_mov_b32 m0, s70
	s_nop 0
	global_load_lds_dwordx4 v[232:233], off
	s_waitcnt vmcnt(8)
	s_waitcnt lgkmcnt(0)
	s_barrier
	s_setprio 1
	s_waitcnt lgkmcnt(0)
	v_mfma_f32_16x16x32_bf16 v[126:129], v[148:151], v[194:197], v[126:129]
	v_mfma_f32_16x16x32_bf16 v[126:129], v[166:169], v[202:205], v[126:129]
	v_mfma_f32_16x16x32_bf16 v[122:125], v[174:177], v[202:205], v[122:125]
	v_mfma_f32_16x16x32_bf16 v[122:125], v[170:173], v[194:197], v[122:125]
	v_mfma_f32_16x16x32_bf16 v[106:109], v[170:173], v[206:209], v[106:109]
	v_mfma_f32_16x16x32_bf16 v[106:109], v[174:177], v[210:213], v[106:109]
	v_mfma_f32_16x16x32_bf16 v[110:113], v[166:169], v[210:213], v[110:113]
	v_mfma_f32_16x16x32_bf16 v[110:113], v[148:151], v[206:209], v[110:113]
	v_mfma_f32_16x16x32_bf16 v[94:97], v[148:151], v[214:217], v[94:97]
	v_mfma_f32_16x16x32_bf16 v[94:97], v[166:169], v[218:221], v[94:97]
	v_mfma_f32_16x16x32_bf16 v[90:93], v[174:177], v[218:221], v[90:93]
	v_mfma_f32_16x16x32_bf16 v[90:93], v[170:173], v[214:217], v[90:93]
	v_mfma_f32_16x16x32_bf16 v[74:77], v[170:173], v[222:225], v[74:77]
	v_mfma_f32_16x16x32_bf16 v[74:77], v[174:177], v[226:229], v[74:77]
	v_mfma_f32_16x16x32_bf16 v[78:81], v[166:169], v[226:229], v[78:81]
	v_mfma_f32_16x16x32_bf16 v[78:81], v[148:151], v[222:225], v[78:81]
	s_setprio 0
	s_setprio 1
	v_mfma_f32_16x16x32_bf16 v[118:121], v[178:181], v[194:197], v[118:121]
	v_mfma_f32_16x16x32_bf16 v[118:121], v[182:185], v[202:205], v[118:121]
	v_mfma_f32_16x16x32_bf16 v[114:117], v[190:193], v[202:205], v[114:117]
	v_mfma_f32_16x16x32_bf16 v[114:117], v[186:189], v[194:197], v[114:117]
	v_mfma_f32_16x16x32_bf16 v[98:101], v[186:189], v[206:209], v[98:101]
	v_mfma_f32_16x16x32_bf16 v[98:101], v[190:193], v[210:213], v[98:101]
	v_mfma_f32_16x16x32_bf16 v[102:105], v[182:185], v[210:213], v[102:105]
	v_mfma_f32_16x16x32_bf16 v[102:105], v[178:181], v[206:209], v[102:105]
	v_mfma_f32_16x16x32_bf16 v[86:89], v[178:181], v[214:217], v[86:89]
	v_mfma_f32_16x16x32_bf16 v[86:89], v[182:185], v[218:221], v[86:89]
	v_mfma_f32_16x16x32_bf16 v[82:85], v[190:193], v[218:221], v[82:85]
	v_mfma_f32_16x16x32_bf16 v[82:85], v[186:189], v[214:217], v[82:85]
	v_mfma_f32_16x16x32_bf16 v[66:69], v[186:189], v[222:225], v[66:69]
	v_mfma_f32_16x16x32_bf16 v[66:69], v[190:193], v[226:229], v[66:69]
	v_mfma_f32_16x16x32_bf16 v[70:73], v[182:185], v[226:229], v[70:73]
	v_mfma_f32_16x16x32_bf16 v[70:73], v[178:181], v[222:225], v[70:73]
	s_setprio 0
	s_barrier
	s_add_i32 s36, s36, s64
	v_lshl_add_u64 v[152:153], v[152:153], 0, s[20:21]
	s_mov_b32 m0, s36
	ds_read_b128 v[194:197], v158 offset:49152
	ds_read_b128 v[202:205], v158 offset:50176
	ds_read_b128 v[206:209], v158 offset:51200
	ds_read_b128 v[210:213], v158 offset:52224
	ds_read_b128 v[214:217], v158 offset:53248
	ds_read_b128 v[218:221], v158 offset:54272
	ds_read_b128 v[222:225], v158 offset:55296
	ds_read_b128 v[226:229], v158 offset:56320
	global_load_lds_dwordx4 v[152:153], off
	s_add_i32 m0, s36, 0x2000
	s_add_u32 s58, s58, 0x2b0080
	v_lshl_add_u64 v[152:153], v[160:161], 0, s[20:21]
	s_addc_u32 s59, s59, 0
	s_add_i32 s36, s37, s64
	global_load_lds_dwordx4 v[152:153], off
	v_lshl_add_u64 v[152:153], s[58:59], 0, v[134:135]
	s_mov_b32 m0, s36
	s_nop 0
	global_load_lds_dwordx4 v[152:153], off
	v_lshl_add_u64 v[152:153], s[58:59], 0, v[138:139]
	s_add_i32 m0, s36, 0x2000
	s_nop 0
	global_load_lds_dwordx4 v[152:153], off
	v_lshl_add_u64 v[152:153], v[198:199], 0, s[20:21]
	s_mov_b32 m0, s73
	s_nop 0
	global_load_lds_dwordx4 v[152:153], off
	v_lshl_add_u64 v[152:153], v[230:231], 0, s[20:21]
	s_mov_b32 m0, s74
	s_nop 0
	global_load_lds_dwordx4 v[152:153], off
	s_waitcnt vmcnt(8)
	s_waitcnt lgkmcnt(0)
	s_barrier
	s_setprio 1
	s_waitcnt lgkmcnt(0)
	v_mfma_f32_16x16x32_bf16 v[62:65], v[148:151], v[194:197], v[62:65]
	v_mfma_f32_16x16x32_bf16 v[62:65], v[166:169], v[202:205], v[62:65]
	v_mfma_f32_16x16x32_bf16 v[58:61], v[174:177], v[202:205], v[58:61]
	v_mfma_f32_16x16x32_bf16 v[58:61], v[170:173], v[194:197], v[58:61]
	v_mfma_f32_16x16x32_bf16 v[42:45], v[170:173], v[206:209], v[42:45]
	v_mfma_f32_16x16x32_bf16 v[42:45], v[174:177], v[210:213], v[42:45]
	v_mfma_f32_16x16x32_bf16 v[46:49], v[166:169], v[210:213], v[46:49]
	v_mfma_f32_16x16x32_bf16 v[46:49], v[148:151], v[206:209], v[46:49]
	v_mfma_f32_16x16x32_bf16 v[30:33], v[148:151], v[214:217], v[30:33]
	v_mfma_f32_16x16x32_bf16 v[30:33], v[166:169], v[218:221], v[30:33]
	v_mfma_f32_16x16x32_bf16 v[26:29], v[174:177], v[218:221], v[26:29]
	v_mfma_f32_16x16x32_bf16 v[26:29], v[170:173], v[214:217], v[26:29]
	v_mfma_f32_16x16x32_bf16 v[10:13], v[170:173], v[222:225], v[10:13]
	v_mfma_f32_16x16x32_bf16 v[10:13], v[174:177], v[226:229], v[10:13]
	v_mfma_f32_16x16x32_bf16 v[14:17], v[166:169], v[226:229], v[14:17]
	v_mfma_f32_16x16x32_bf16 v[14:17], v[148:151], v[222:225], v[14:17]
	s_setprio 0
	s_setprio 1
	v_mfma_f32_16x16x32_bf16 v[54:57], v[178:181], v[194:197], v[54:57]
	v_mfma_f32_16x16x32_bf16 v[54:57], v[182:185], v[202:205], v[54:57]
	v_mfma_f32_16x16x32_bf16 v[50:53], v[190:193], v[202:205], v[50:53]
	v_mfma_f32_16x16x32_bf16 v[50:53], v[186:189], v[194:197], v[50:53]
	v_mfma_f32_16x16x32_bf16 v[34:37], v[186:189], v[206:209], v[34:37]
	v_mfma_f32_16x16x32_bf16 v[34:37], v[190:193], v[210:213], v[34:37]
	v_mfma_f32_16x16x32_bf16 v[38:41], v[182:185], v[210:213], v[38:41]
	v_mfma_f32_16x16x32_bf16 v[38:41], v[178:181], v[206:209], v[38:41]
	v_mfma_f32_16x16x32_bf16 v[22:25], v[178:181], v[214:217], v[22:25]
	v_mfma_f32_16x16x32_bf16 v[22:25], v[182:185], v[218:221], v[22:25]
	v_mfma_f32_16x16x32_bf16 v[18:21], v[190:193], v[218:221], v[18:21]
	v_mfma_f32_16x16x32_bf16 v[18:21], v[186:189], v[214:217], v[18:21]
	v_mfma_f32_16x16x32_bf16 v[2:5], v[186:189], v[222:225], v[2:5]
	v_mfma_f32_16x16x32_bf16 v[2:5], v[190:193], v[226:229], v[2:5]
	v_mfma_f32_16x16x32_bf16 v[6:9], v[182:185], v[226:229], v[6:9]
	v_mfma_f32_16x16x32_bf16 v[6:9], v[178:181], v[222:225], v[6:9]
	s_setprio 0
	s_barrier
	s_add_u32 s56, s56, 0x100
	s_addc_u32 s57, s57, 0
	s_add_u32 s90, s90, 0x100
	s_addc_u32 s91, s91, 0
	s_cmp_ge_i32 s92, s39
	s_mov_b32 s58, s92
	s_cbranch_scc0 .LBB0_1902
	s_and_b64 vcc, exec, s[24:25]
	s_cbranch_vccz .LBB0_1905

.LBB0_2138:
	ds_read_b128 v[146:149], v157
	ds_read_b128 v[164:167], v157 offset:1024
	ds_read_b128 v[168:171], v157 offset:2048
	ds_read_b128 v[172:175], v157 offset:3072
	ds_read_b128 v[176:179], v158
	ds_read_b128 v[180:183], v158 offset:1024
	ds_read_b128 v[184:187], v158 offset:2048
	ds_read_b128 v[188:191], v158 offset:3072
	s_add_u32 s24, s22, 0xfff00080
	s_addc_u32 s25, s23, -1
	s_cmp_eq_u32 s54, 60
	s_cselect_b32 s35, s15, s25
	s_cselect_b32 s34, s50, s24
	s_cselect_b32 s25, s13, s53
	s_cselect_b32 s24, s51, s52
	v_lshl_add_u64 v[150:151], s[22:23], 0, v[138:139]
	s_add_i32 m0, s21, 0xc000
	ds_read_b128 v[192:195], v159
	ds_read_b128 v[196:199], v159 offset:1024
	ds_read_b128 v[200:203], v159 offset:2048
	ds_read_b128 v[204:207], v159 offset:3072
	ds_read_b128 v[208:211], v159 offset:4096
	ds_read_b128 v[212:215], v159 offset:5120
	ds_read_b128 v[216:219], v159 offset:6144
	ds_read_b128 v[220:223], v159 offset:7168
	global_load_lds_dwordx4 v[150:151], off
	v_lshl_add_u64 v[150:151], s[22:23], 0, v[140:141]
	s_add_i32 m0, s21, 0xe000
	s_nop 0
	global_load_lds_dwordx4 v[150:151], off
	s_waitcnt vmcnt(8)
	s_waitcnt lgkmcnt(0)
	s_barrier
	s_setprio 1
	s_waitcnt lgkmcnt(0)
	v_mfma_f32_16x16x32_bf16 v[126:129], v[146:149], v[192:195], v[126:129]
	v_mfma_f32_16x16x32_bf16 v[126:129], v[164:167], v[196:199], v[126:129]
	v_mfma_f32_16x16x32_bf16 v[122:125], v[172:175], v[196:199], v[122:125]
	v_mfma_f32_16x16x32_bf16 v[122:125], v[168:171], v[192:195], v[122:125]
	v_mfma_f32_16x16x32_bf16 v[106:109], v[168:171], v[200:203], v[106:109]
	v_mfma_f32_16x16x32_bf16 v[106:109], v[172:175], v[204:207], v[106:109]
	v_mfma_f32_16x16x32_bf16 v[110:113], v[164:167], v[204:207], v[110:113]
	v_mfma_f32_16x16x32_bf16 v[110:113], v[146:149], v[200:203], v[110:113]
	v_mfma_f32_16x16x32_bf16 v[94:97], v[146:149], v[208:211], v[94:97]
	v_mfma_f32_16x16x32_bf16 v[94:97], v[164:167], v[212:215], v[94:97]
	v_mfma_f32_16x16x32_bf16 v[90:93], v[172:175], v[212:215], v[90:93]
	v_mfma_f32_16x16x32_bf16 v[90:93], v[168:171], v[208:211], v[90:93]
	v_mfma_f32_16x16x32_bf16 v[74:77], v[168:171], v[216:219], v[74:77]
	v_mfma_f32_16x16x32_bf16 v[74:77], v[172:175], v[220:223], v[74:77]
	v_mfma_f32_16x16x32_bf16 v[78:81], v[164:167], v[220:223], v[78:81]
	v_mfma_f32_16x16x32_bf16 v[78:81], v[146:149], v[216:219], v[78:81]
	s_setprio 0
	s_setprio 1
	v_mfma_f32_16x16x32_bf16 v[118:121], v[176:179], v[192:195], v[118:121]
	v_mfma_f32_16x16x32_bf16 v[118:121], v[180:183], v[196:199], v[118:121]
	v_mfma_f32_16x16x32_bf16 v[114:117], v[188:191], v[196:199], v[114:117]
	v_mfma_f32_16x16x32_bf16 v[114:117], v[184:187], v[192:195], v[114:117]
	v_mfma_f32_16x16x32_bf16 v[98:101], v[184:187], v[200:203], v[98:101]
	v_mfma_f32_16x16x32_bf16 v[98:101], v[188:191], v[204:207], v[98:101]
	v_mfma_f32_16x16x32_bf16 v[102:105], v[180:183], v[204:207], v[102:105]
	v_mfma_f32_16x16x32_bf16 v[102:105], v[176:179], v[200:203], v[102:105]
	v_mfma_f32_16x16x32_bf16 v[86:89], v[176:179], v[208:211], v[86:89]
	v_mfma_f32_16x16x32_bf16 v[86:89], v[180:183], v[212:215], v[86:89]
	v_mfma_f32_16x16x32_bf16 v[82:85], v[188:191], v[212:215], v[82:85]
	v_mfma_f32_16x16x32_bf16 v[82:85], v[184:187], v[208:211], v[82:85]
	v_mfma_f32_16x16x32_bf16 v[66:69], v[184:187], v[216:219], v[66:69]
	v_mfma_f32_16x16x32_bf16 v[66:69], v[188:191], v[220:223], v[66:69]
	v_mfma_f32_16x16x32_bf16 v[70:73], v[180:183], v[220:223], v[70:73]
	v_mfma_f32_16x16x32_bf16 v[70:73], v[176:179], v[216:219], v[70:73]
	s_setprio 0
	s_barrier
	s_add_i32 s55, s47, s27
	v_lshl_add_u64 v[150:151], s[24:25], 0, v[134:135]
	s_mov_b32 m0, s55
	ds_read_b128 v[192:195], v159 offset:16384
	ds_read_b128 v[196:199], v159 offset:17408
	ds_read_b128 v[200:203], v159 offset:18432
	ds_read_b128 v[204:207], v159 offset:19456
	ds_read_b128 v[208:211], v159 offset:20480
	ds_read_b128 v[212:215], v159 offset:21504
	ds_read_b128 v[216:219], v159 offset:22528
	ds_read_b128 v[220:223], v159 offset:23552
	global_load_lds_dwordx4 v[150:151], off
	s_add_i32 m0, s55, 0x2000
	s_add_u32 s56, s24, 0x100000
	v_lshl_add_u64 v[160:161], s[24:25], 0, v[130:131]
	s_addc_u32 s57, s25, 0
	s_add_i32 s55, s48, s27
	global_load_lds_dwordx4 v[160:161], off
	v_lshl_add_u64 v[224:225], s[56:57], 0, v[134:135]
	s_mov_b32 m0, s55
	v_lshl_add_u64 v[226:227], s[34:35], 0, v[132:133]
	global_load_lds_dwordx4 v[224:225], off
	v_lshl_add_u64 v[224:225], s[56:57], 0, v[130:131]
	s_add_i32 m0, s55, 0x2000
	s_nop 0
	global_load_lds_dwordx4 v[224:225], off
	v_lshl_add_u64 v[224:225], s[34:35], 0, v[136:137]
	s_mov_b32 m0, s21
	s_nop 0
	global_load_lds_dwordx4 v[224:225], off
	s_mov_b32 m0, s40
	s_nop 0
	global_load_lds_dwordx4 v[226:227], off
	s_waitcnt vmcnt(8)
	s_waitcnt lgkmcnt(0)
	s_barrier
	s_setprio 1
	s_waitcnt lgkmcnt(0)
	v_mfma_f32_16x16x32_bf16 v[62:65], v[146:149], v[192:195], v[62:65]
	v_mfma_f32_16x16x32_bf16 v[62:65], v[164:167], v[196:199], v[62:65]
	v_mfma_f32_16x16x32_bf16 v[58:61], v[172:175], v[196:199], v[58:61]
	v_mfma_f32_16x16x32_bf16 v[58:61], v[168:171], v[192:195], v[58:61]
	v_mfma_f32_16x16x32_bf16 v[42:45], v[168:171], v[200:203], v[42:45]
	v_mfma_f32_16x16x32_bf16 v[42:45], v[172:175], v[204:207], v[42:45]
	v_mfma_f32_16x16x32_bf16 v[46:49], v[164:167], v[204:207], v[46:49]
	v_mfma_f32_16x16x32_bf16 v[46:49], v[146:149], v[200:203], v[46:49]
	v_mfma_f32_16x16x32_bf16 v[30:33], v[146:149], v[208:211], v[30:33]
	v_mfma_f32_16x16x32_bf16 v[30:33], v[164:167], v[212:215], v[30:33]
	v_mfma_f32_16x16x32_bf16 v[26:29], v[172:175], v[212:215], v[26:29]
	v_mfma_f32_16x16x32_bf16 v[26:29], v[168:171], v[208:211], v[26:29]
	v_mfma_f32_16x16x32_bf16 v[10:13], v[168:171], v[216:219], v[10:13]
	v_mfma_f32_16x16x32_bf16 v[10:13], v[172:175], v[220:223], v[10:13]
	v_mfma_f32_16x16x32_bf16 v[14:17], v[164:167], v[220:223], v[14:17]
	v_mfma_f32_16x16x32_bf16 v[14:17], v[146:149], v[216:219], v[14:17]
	s_setprio 0
	s_setprio 1
	v_mfma_f32_16x16x32_bf16 v[54:57], v[176:179], v[192:195], v[54:57]
	v_mfma_f32_16x16x32_bf16 v[54:57], v[180:183], v[196:199], v[54:57]
	v_mfma_f32_16x16x32_bf16 v[50:53], v[188:191], v[196:199], v[50:53]
	v_mfma_f32_16x16x32_bf16 v[50:53], v[184:187], v[192:195], v[50:53]
	v_mfma_f32_16x16x32_bf16 v[34:37], v[184:187], v[200:203], v[34:37]
	v_mfma_f32_16x16x32_bf16 v[34:37], v[188:191], v[204:207], v[34:37]
	v_mfma_f32_16x16x32_bf16 v[38:41], v[180:183], v[204:207], v[38:41]
	v_mfma_f32_16x16x32_bf16 v[38:41], v[176:179], v[200:203], v[38:41]
	v_mfma_f32_16x16x32_bf16 v[22:25], v[176:179], v[208:211], v[22:25]
	v_mfma_f32_16x16x32_bf16 v[22:25], v[180:183], v[212:215], v[22:25]
	v_mfma_f32_16x16x32_bf16 v[18:21], v[188:191], v[212:215], v[18:21]
	v_mfma_f32_16x16x32_bf16 v[18:21], v[184:187], v[208:211], v[18:21]
	v_mfma_f32_16x16x32_bf16 v[2:5], v[184:187], v[216:219], v[2:5]
	v_mfma_f32_16x16x32_bf16 v[2:5], v[188:191], v[220:223], v[2:5]
	v_mfma_f32_16x16x32_bf16 v[6:9], v[180:183], v[220:223], v[6:9]
	v_mfma_f32_16x16x32_bf16 v[6:9], v[176:179], v[216:219], v[6:9]
	s_setprio 0
	s_barrier
	s_add_i32 s55, 0, 0x18000
	v_add_u32_e32 v162, s55, v155
	s_add_i32 s56, 0, 0x1c000
	ds_read_b128 v[146:149], v162
	ds_read_b128 v[164:167], v162 offset:1024
	ds_read_b128 v[168:171], v162 offset:2048
	ds_read_b128 v[172:175], v162 offset:3072
	v_add_u32_e32 v162, s56, v155
	ds_read_b128 v[176:179], v162
	ds_read_b128 v[180:183], v162 offset:1024
	ds_read_b128 v[184:187], v162 offset:2048
	ds_read_b128 v[188:191], v162 offset:3072
	s_add_u32 s34, s34, 0x100000
	s_addc_u32 s35, s35, 0
	s_mov_b32 m0, s41
	v_lshl_add_u64 v[228:229], s[34:35], 0, v[136:137]
	ds_read_b128 v[192:195], v159 offset:32768
	ds_read_b128 v[196:199], v159 offset:33792
	ds_read_b128 v[200:203], v159 offset:34816
	ds_read_b128 v[204:207], v159 offset:35840
	ds_read_b128 v[208:211], v159 offset:36864
	ds_read_b128 v[212:215], v159 offset:37888
	ds_read_b128 v[216:219], v159 offset:38912
	ds_read_b128 v[220:223], v159 offset:39936
	global_load_lds_dwordx4 v[228:229], off
	v_lshl_add_u64 v[228:229], s[34:35], 0, v[132:133]
	s_mov_b32 m0, s42
	s_nop 0
	global_load_lds_dwordx4 v[228:229], off
	s_waitcnt vmcnt(8)
	s_waitcnt lgkmcnt(0)
	s_barrier
	s_setprio 1
	s_waitcnt lgkmcnt(0)
	v_mfma_f32_16x16x32_bf16 v[126:129], v[146:149], v[192:195], v[126:129]
	v_mfma_f32_16x16x32_bf16 v[126:129], v[164:167], v[196:199], v[126:129]
	v_mfma_f32_16x16x32_bf16 v[122:125], v[172:175], v[196:199], v[122:125]
	v_mfma_f32_16x16x32_bf16 v[122:125], v[168:171], v[192:195], v[122:125]
	v_mfma_f32_16x16x32_bf16 v[106:109], v[168:171], v[200:203], v[106:109]
	v_mfma_f32_16x16x32_bf16 v[106:109], v[172:175], v[204:207], v[106:109]
	v_mfma_f32_16x16x32_bf16 v[110:113], v[164:167], v[204:207], v[110:113]
	v_mfma_f32_16x16x32_bf16 v[110:113], v[146:149], v[200:203], v[110:113]
	v_mfma_f32_16x16x32_bf16 v[94:97], v[146:149], v[208:211], v[94:97]
	v_mfma_f32_16x16x32_bf16 v[94:97], v[164:167], v[212:215], v[94:97]
	v_mfma_f32_16x16x32_bf16 v[90:93], v[172:175], v[212:215], v[90:93]
	v_mfma_f32_16x16x32_bf16 v[90:93], v[168:171], v[208:211], v[90:93]
	v_mfma_f32_16x16x32_bf16 v[74:77], v[168:171], v[216:219], v[74:77]
	v_mfma_f32_16x16x32_bf16 v[74:77], v[172:175], v[220:223], v[74:77]
	v_mfma_f32_16x16x32_bf16 v[78:81], v[164:167], v[220:223], v[78:81]
	v_mfma_f32_16x16x32_bf16 v[78:81], v[146:149], v[216:219], v[78:81]
	s_setprio 0
	s_setprio 1
	v_mfma_f32_16x16x32_bf16 v[118:121], v[176:179], v[192:195], v[118:121]
	v_mfma_f32_16x16x32_bf16 v[118:121], v[180:183], v[196:199], v[118:121]
	v_mfma_f32_16x16x32_bf16 v[114:117], v[188:191], v[196:199], v[114:117]
	v_mfma_f32_16x16x32_bf16 v[114:117], v[184:187], v[192:195], v[114:117]
	v_mfma_f32_16x16x32_bf16 v[98:101], v[184:187], v[200:203], v[98:101]
	v_mfma_f32_16x16x32_bf16 v[98:101], v[188:191], v[204:207], v[98:101]
	v_mfma_f32_16x16x32_bf16 v[102:105], v[180:183], v[204:207], v[102:105]
	v_mfma_f32_16x16x32_bf16 v[102:105], v[176:179], v[200:203], v[102:105]
	v_mfma_f32_16x16x32_bf16 v[86:89], v[176:179], v[208:211], v[86:89]
	v_mfma_f32_16x16x32_bf16 v[86:89], v[180:183], v[212:215], v[86:89]
	v_mfma_f32_16x16x32_bf16 v[82:85], v[188:191], v[212:215], v[82:85]
	v_mfma_f32_16x16x32_bf16 v[82:85], v[184:187], v[208:211], v[82:85]
	v_mfma_f32_16x16x32_bf16 v[66:69], v[184:187], v[216:219], v[66:69]
	v_mfma_f32_16x16x32_bf16 v[66:69], v[188:191], v[220:223], v[66:69]
	v_mfma_f32_16x16x32_bf16 v[70:73], v[180:183], v[220:223], v[70:73]
	v_mfma_f32_16x16x32_bf16 v[70:73], v[176:179], v[216:219], v[70:73]
	s_setprio 0
	s_barrier
	s_add_i32 s34, s55, s27
	v_lshl_add_u64 v[150:151], v[150:151], 0, s[8:9]
	s_mov_b32 m0, s34
	ds_read_b128 v[192:195], v159 offset:49152
	ds_read_b128 v[196:199], v159 offset:50176
	ds_read_b128 v[200:203], v159 offset:51200
	ds_read_b128 v[204:207], v159 offset:52224
	ds_read_b128 v[208:211], v159 offset:53248
	ds_read_b128 v[212:215], v159 offset:54272
	ds_read_b128 v[216:219], v159 offset:55296
	ds_read_b128 v[220:223], v159 offset:56320
	global_load_lds_dwordx4 v[150:151], off
	s_add_i32 m0, s34, 0x2000
	s_add_u32 s24, s24, 0x100080
	v_lshl_add_u64 v[150:151], v[160:161], 0, s[8:9]
	s_addc_u32 s25, s25, 0
	s_add_i32 s34, s56, s27
	global_load_lds_dwordx4 v[150:151], off
	v_lshl_add_u64 v[150:151], s[24:25], 0, v[134:135]
	s_mov_b32 m0, s34
	s_nop 0
	global_load_lds_dwordx4 v[150:151], off
	v_lshl_add_u64 v[150:151], s[24:25], 0, v[130:131]
	s_add_i32 m0, s34, 0x2000
	s_nop 0
	global_load_lds_dwordx4 v[150:151], off
	v_lshl_add_u64 v[150:151], v[224:225], 0, s[8:9]
	s_mov_b32 m0, s44
	s_nop 0
	global_load_lds_dwordx4 v[150:151], off
	v_lshl_add_u64 v[150:151], v[226:227], 0, s[8:9]
	s_mov_b32 m0, s45
	s_nop 0
	global_load_lds_dwordx4 v[150:151], off
	s_waitcnt vmcnt(8)
	s_waitcnt lgkmcnt(0)
	s_barrier
	s_setprio 1
	s_waitcnt lgkmcnt(0)
	v_mfma_f32_16x16x32_bf16 v[62:65], v[146:149], v[192:195], v[62:65]
	v_mfma_f32_16x16x32_bf16 v[62:65], v[164:167], v[196:199], v[62:65]
	v_mfma_f32_16x16x32_bf16 v[58:61], v[172:175], v[196:199], v[58:61]
	v_mfma_f32_16x16x32_bf16 v[58:61], v[168:171], v[192:195], v[58:61]
	v_mfma_f32_16x16x32_bf16 v[42:45], v[168:171], v[200:203], v[42:45]
	v_mfma_f32_16x16x32_bf16 v[42:45], v[172:175], v[204:207], v[42:45]
	v_mfma_f32_16x16x32_bf16 v[46:49], v[164:167], v[204:207], v[46:49]
	v_mfma_f32_16x16x32_bf16 v[46:49], v[146:149], v[200:203], v[46:49]
	v_mfma_f32_16x16x32_bf16 v[30:33], v[146:149], v[208:211], v[30:33]
	v_mfma_f32_16x16x32_bf16 v[30:33], v[164:167], v[212:215], v[30:33]
	v_mfma_f32_16x16x32_bf16 v[26:29], v[172:175], v[212:215], v[26:29]
	v_mfma_f32_16x16x32_bf16 v[26:29], v[168:171], v[208:211], v[26:29]
	v_mfma_f32_16x16x32_bf16 v[10:13], v[168:171], v[216:219], v[10:13]
	v_mfma_f32_16x16x32_bf16 v[10:13], v[172:175], v[220:223], v[10:13]
	v_mfma_f32_16x16x32_bf16 v[14:17], v[164:167], v[220:223], v[14:17]
	v_mfma_f32_16x16x32_bf16 v[14:17], v[146:149], v[216:219], v[14:17]
	s_setprio 0
	s_setprio 1
	v_mfma_f32_16x16x32_bf16 v[54:57], v[176:179], v[192:195], v[54:57]
	v_mfma_f32_16x16x32_bf16 v[54:57], v[180:183], v[196:199], v[54:57]
	v_mfma_f32_16x16x32_bf16 v[50:53], v[188:191], v[196:199], v[50:53]
	v_mfma_f32_16x16x32_bf16 v[50:53], v[184:187], v[192:195], v[50:53]
	v_mfma_f32_16x16x32_bf16 v[34:37], v[184:187], v[200:203], v[34:37]
	v_mfma_f32_16x16x32_bf16 v[34:37], v[188:191], v[204:207], v[34:37]
	v_mfma_f32_16x16x32_bf16 v[38:41], v[180:183], v[204:207], v[38:41]
	v_mfma_f32_16x16x32_bf16 v[38:41], v[176:179], v[200:203], v[38:41]
	v_mfma_f32_16x16x32_bf16 v[22:25], v[176:179], v[208:211], v[22:25]
	v_mfma_f32_16x16x32_bf16 v[22:25], v[180:183], v[212:215], v[22:25]
	v_mfma_f32_16x16x32_bf16 v[18:21], v[188:191], v[212:215], v[18:21]
	v_mfma_f32_16x16x32_bf16 v[18:21], v[184:187], v[208:211], v[18:21]
	v_mfma_f32_16x16x32_bf16 v[2:5], v[184:187], v[216:219], v[2:5]
	v_mfma_f32_16x16x32_bf16 v[2:5], v[188:191], v[220:223], v[2:5]
	v_mfma_f32_16x16x32_bf16 v[6:9], v[180:183], v[220:223], v[6:9]
	v_mfma_f32_16x16x32_bf16 v[6:9], v[176:179], v[216:219], v[6:9]
	s_setprio 0
	s_barrier
	s_add_i32 s54, s54, 2
	s_add_u32 s22, s22, 0x100
	s_addc_u32 s23, s23, 0
	s_add_u32 s52, s52, 0x100
	s_addc_u32 s53, s53, 0
	s_cmp_gt_u32 s54, 61
	s_cbranch_scc0 .LBB0_2138
	s_and_b64 vcc, exec, s[10:11]
	s_cbranch_vccz .LBB0_2141
	s_barrier

.LBB0_2158:
	ds_read_b128 v[146:149], v157
	ds_read_b128 v[164:167], v157 offset:1024
	ds_read_b128 v[168:171], v157 offset:2048
	ds_read_b128 v[172:175], v157 offset:3072
	ds_read_b128 v[176:179], v158
	ds_read_b128 v[180:183], v158 offset:1024
	ds_read_b128 v[184:187], v158 offset:2048
	ds_read_b128 v[188:191], v158 offset:3072
	s_add_u32 s26, s24, 0xfff00080
	s_addc_u32 s27, s25, -1
	s_cmp_eq_u32 s52, 60
	s_cselect_b32 s35, s17, s27
	s_cselect_b32 s34, s48, s26
	s_cselect_b32 s27, s15, s51
	s_cselect_b32 s26, s49, s50
	v_lshl_add_u64 v[150:151], s[24:25], 0, v[138:139]
	s_add_i32 m0, s23, 0xc000
	ds_read_b128 v[192:195], v159
	ds_read_b128 v[196:199], v159 offset:1024
	ds_read_b128 v[200:203], v159 offset:2048
	ds_read_b128 v[204:207], v159 offset:3072
	ds_read_b128 v[208:211], v159 offset:4096
	ds_read_b128 v[212:215], v159 offset:5120
	ds_read_b128 v[216:219], v159 offset:6144
	ds_read_b128 v[220:223], v159 offset:7168
	global_load_lds_dwordx4 v[150:151], off
	v_lshl_add_u64 v[150:151], s[24:25], 0, v[140:141]
	s_add_i32 m0, s23, 0xe000
	s_nop 0
	global_load_lds_dwordx4 v[150:151], off
	s_waitcnt vmcnt(8)
	s_waitcnt lgkmcnt(0)
	s_barrier
	s_setprio 1
	s_waitcnt lgkmcnt(0)
	v_mfma_f32_16x16x32_bf16 v[126:129], v[146:149], v[192:195], v[126:129]
	v_mfma_f32_16x16x32_bf16 v[126:129], v[164:167], v[196:199], v[126:129]
	v_mfma_f32_16x16x32_bf16 v[122:125], v[172:175], v[196:199], v[122:125]
	v_mfma_f32_16x16x32_bf16 v[122:125], v[168:171], v[192:195], v[122:125]
	v_mfma_f32_16x16x32_bf16 v[106:109], v[168:171], v[200:203], v[106:109]
	v_mfma_f32_16x16x32_bf16 v[106:109], v[172:175], v[204:207], v[106:109]
	v_mfma_f32_16x16x32_bf16 v[110:113], v[164:167], v[204:207], v[110:113]
	v_mfma_f32_16x16x32_bf16 v[110:113], v[146:149], v[200:203], v[110:113]
	v_mfma_f32_16x16x32_bf16 v[94:97], v[146:149], v[208:211], v[94:97]
	v_mfma_f32_16x16x32_bf16 v[94:97], v[164:167], v[212:215], v[94:97]
	v_mfma_f32_16x16x32_bf16 v[90:93], v[172:175], v[212:215], v[90:93]
	v_mfma_f32_16x16x32_bf16 v[90:93], v[168:171], v[208:211], v[90:93]
	v_mfma_f32_16x16x32_bf16 v[74:77], v[168:171], v[216:219], v[74:77]
	v_mfma_f32_16x16x32_bf16 v[74:77], v[172:175], v[220:223], v[74:77]
	v_mfma_f32_16x16x32_bf16 v[78:81], v[164:167], v[220:223], v[78:81]
	v_mfma_f32_16x16x32_bf16 v[78:81], v[146:149], v[216:219], v[78:81]
	s_setprio 0
	s_setprio 1
	v_mfma_f32_16x16x32_bf16 v[118:121], v[176:179], v[192:195], v[118:121]
	v_mfma_f32_16x16x32_bf16 v[118:121], v[180:183], v[196:199], v[118:121]
	v_mfma_f32_16x16x32_bf16 v[114:117], v[188:191], v[196:199], v[114:117]
	v_mfma_f32_16x16x32_bf16 v[114:117], v[184:187], v[192:195], v[114:117]
	v_mfma_f32_16x16x32_bf16 v[98:101], v[184:187], v[200:203], v[98:101]
	v_mfma_f32_16x16x32_bf16 v[98:101], v[188:191], v[204:207], v[98:101]
	v_mfma_f32_16x16x32_bf16 v[102:105], v[180:183], v[204:207], v[102:105]
	v_mfma_f32_16x16x32_bf16 v[102:105], v[176:179], v[200:203], v[102:105]
	v_mfma_f32_16x16x32_bf16 v[86:89], v[176:179], v[208:211], v[86:89]
	v_mfma_f32_16x16x32_bf16 v[86:89], v[180:183], v[212:215], v[86:89]
	v_mfma_f32_16x16x32_bf16 v[82:85], v[188:191], v[212:215], v[82:85]
	v_mfma_f32_16x16x32_bf16 v[82:85], v[184:187], v[208:211], v[82:85]
	v_mfma_f32_16x16x32_bf16 v[66:69], v[184:187], v[216:219], v[66:69]
	v_mfma_f32_16x16x32_bf16 v[66:69], v[188:191], v[220:223], v[66:69]
	v_mfma_f32_16x16x32_bf16 v[70:73], v[180:183], v[220:223], v[70:73]
	v_mfma_f32_16x16x32_bf16 v[70:73], v[176:179], v[216:219], v[70:73]
	s_setprio 0
	s_barrier
	s_add_i32 s53, s45, s38
	v_lshl_add_u64 v[150:151], s[26:27], 0, v[132:133]
	s_mov_b32 m0, s53
	ds_read_b128 v[192:195], v159 offset:16384
	ds_read_b128 v[196:199], v159 offset:17408
	ds_read_b128 v[200:203], v159 offset:18432
	ds_read_b128 v[204:207], v159 offset:19456
	ds_read_b128 v[208:211], v159 offset:20480
	ds_read_b128 v[212:215], v159 offset:21504
	ds_read_b128 v[216:219], v159 offset:22528
	ds_read_b128 v[220:223], v159 offset:23552
	global_load_lds_dwordx4 v[150:151], off
	s_add_i32 m0, s53, 0x2000
	s_add_u32 s54, s26, 0x100000
	v_lshl_add_u64 v[160:161], s[26:27], 0, v[134:135]
	s_addc_u32 s55, s27, 0
	s_add_i32 s53, s46, s38
	global_load_lds_dwordx4 v[160:161], off
	v_lshl_add_u64 v[224:225], s[54:55], 0, v[132:133]
	s_mov_b32 m0, s53
	v_lshl_add_u64 v[226:227], s[34:35], 0, v[136:137]
	global_load_lds_dwordx4 v[224:225], off
	v_lshl_add_u64 v[224:225], s[54:55], 0, v[134:135]
	s_add_i32 m0, s53, 0x2000
	s_nop 0
	global_load_lds_dwordx4 v[224:225], off
	v_lshl_add_u64 v[224:225], s[34:35], 0, v[130:131]
	s_mov_b32 m0, s23
	s_nop 0
	global_load_lds_dwordx4 v[224:225], off
	s_mov_b32 m0, s40
	s_nop 0
	global_load_lds_dwordx4 v[226:227], off
	s_waitcnt vmcnt(8)
	s_waitcnt lgkmcnt(0)
	s_barrier
	s_setprio 1
	s_waitcnt lgkmcnt(0)
	v_mfma_f32_16x16x32_bf16 v[62:65], v[146:149], v[192:195], v[62:65]
	v_mfma_f32_16x16x32_bf16 v[62:65], v[164:167], v[196:199], v[62:65]
	v_mfma_f32_16x16x32_bf16 v[58:61], v[172:175], v[196:199], v[58:61]
	v_mfma_f32_16x16x32_bf16 v[58:61], v[168:171], v[192:195], v[58:61]
	v_mfma_f32_16x16x32_bf16 v[42:45], v[168:171], v[200:203], v[42:45]
	v_mfma_f32_16x16x32_bf16 v[42:45], v[172:175], v[204:207], v[42:45]
	v_mfma_f32_16x16x32_bf16 v[46:49], v[164:167], v[204:207], v[46:49]
	v_mfma_f32_16x16x32_bf16 v[46:49], v[146:149], v[200:203], v[46:49]
	v_mfma_f32_16x16x32_bf16 v[30:33], v[146:149], v[208:211], v[30:33]
	v_mfma_f32_16x16x32_bf16 v[30:33], v[164:167], v[212:215], v[30:33]
	v_mfma_f32_16x16x32_bf16 v[26:29], v[172:175], v[212:215], v[26:29]
	v_mfma_f32_16x16x32_bf16 v[26:29], v[168:171], v[208:211], v[26:29]
	v_mfma_f32_16x16x32_bf16 v[10:13], v[168:171], v[216:219], v[10:13]
	v_mfma_f32_16x16x32_bf16 v[10:13], v[172:175], v[220:223], v[10:13]
	v_mfma_f32_16x16x32_bf16 v[14:17], v[164:167], v[220:223], v[14:17]
	v_mfma_f32_16x16x32_bf16 v[14:17], v[146:149], v[216:219], v[14:17]
	s_setprio 0
	s_setprio 1
	v_mfma_f32_16x16x32_bf16 v[54:57], v[176:179], v[192:195], v[54:57]
	v_mfma_f32_16x16x32_bf16 v[54:57], v[180:183], v[196:199], v[54:57]
	v_mfma_f32_16x16x32_bf16 v[50:53], v[188:191], v[196:199], v[50:53]
	v_mfma_f32_16x16x32_bf16 v[50:53], v[184:187], v[192:195], v[50:53]
	v_mfma_f32_16x16x32_bf16 v[34:37], v[184:187], v[200:203], v[34:37]
	v_mfma_f32_16x16x32_bf16 v[34:37], v[188:191], v[204:207], v[34:37]
	v_mfma_f32_16x16x32_bf16 v[38:41], v[180:183], v[204:207], v[38:41]
	v_mfma_f32_16x16x32_bf16 v[38:41], v[176:179], v[200:203], v[38:41]
	v_mfma_f32_16x16x32_bf16 v[22:25], v[176:179], v[208:211], v[22:25]
	v_mfma_f32_16x16x32_bf16 v[22:25], v[180:183], v[212:215], v[22:25]
	v_mfma_f32_16x16x32_bf16 v[18:21], v[188:191], v[212:215], v[18:21]
	v_mfma_f32_16x16x32_bf16 v[18:21], v[184:187], v[208:211], v[18:21]
	v_mfma_f32_16x16x32_bf16 v[2:5], v[184:187], v[216:219], v[2:5]
	v_mfma_f32_16x16x32_bf16 v[2:5], v[188:191], v[220:223], v[2:5]
	v_mfma_f32_16x16x32_bf16 v[6:9], v[180:183], v[220:223], v[6:9]
	v_mfma_f32_16x16x32_bf16 v[6:9], v[176:179], v[216:219], v[6:9]
	s_setprio 0
	s_barrier
	s_add_i32 s53, 0, 0x18000
	v_add_u32_e32 v162, s53, v155
	s_add_i32 s54, 0, 0x1c000
	ds_read_b128 v[146:149], v162
	ds_read_b128 v[164:167], v162 offset:1024
	ds_read_b128 v[168:171], v162 offset:2048
	ds_read_b128 v[172:175], v162 offset:3072
	v_add_u32_e32 v162, s54, v155
	ds_read_b128 v[176:179], v162
	ds_read_b128 v[180:183], v162 offset:1024
	ds_read_b128 v[184:187], v162 offset:2048
	ds_read_b128 v[188:191], v162 offset:3072
	s_add_u32 s34, s34, 0x100000
	s_addc_u32 s35, s35, 0
	s_mov_b32 m0, s41
	v_lshl_add_u64 v[228:229], s[34:35], 0, v[130:131]
	ds_read_b128 v[192:195], v159 offset:32768
	ds_read_b128 v[196:199], v159 offset:33792
	ds_read_b128 v[200:203], v159 offset:34816
	ds_read_b128 v[204:207], v159 offset:35840
	ds_read_b128 v[208:211], v159 offset:36864
	ds_read_b128 v[212:215], v159 offset:37888
	ds_read_b128 v[216:219], v159 offset:38912
	ds_read_b128 v[220:223], v159 offset:39936
	global_load_lds_dwordx4 v[228:229], off
	v_lshl_add_u64 v[228:229], s[34:35], 0, v[136:137]
	s_mov_b32 m0, s42
	s_nop 0
	global_load_lds_dwordx4 v[228:229], off
	s_waitcnt vmcnt(8)
	s_waitcnt lgkmcnt(0)
	s_barrier
	s_setprio 1
	s_waitcnt lgkmcnt(0)
	v_mfma_f32_16x16x32_bf16 v[126:129], v[146:149], v[192:195], v[126:129]
	v_mfma_f32_16x16x32_bf16 v[126:129], v[164:167], v[196:199], v[126:129]
	v_mfma_f32_16x16x32_bf16 v[122:125], v[172:175], v[196:199], v[122:125]
	v_mfma_f32_16x16x32_bf16 v[122:125], v[168:171], v[192:195], v[122:125]
	v_mfma_f32_16x16x32_bf16 v[106:109], v[168:171], v[200:203], v[106:109]
	v_mfma_f32_16x16x32_bf16 v[106:109], v[172:175], v[204:207], v[106:109]
	v_mfma_f32_16x16x32_bf16 v[110:113], v[164:167], v[204:207], v[110:113]
	v_mfma_f32_16x16x32_bf16 v[110:113], v[146:149], v[200:203], v[110:113]
	v_mfma_f32_16x16x32_bf16 v[94:97], v[146:149], v[208:211], v[94:97]
	v_mfma_f32_16x16x32_bf16 v[94:97], v[164:167], v[212:215], v[94:97]
	v_mfma_f32_16x16x32_bf16 v[90:93], v[172:175], v[212:215], v[90:93]
	v_mfma_f32_16x16x32_bf16 v[90:93], v[168:171], v[208:211], v[90:93]
	v_mfma_f32_16x16x32_bf16 v[74:77], v[168:171], v[216:219], v[74:77]
	v_mfma_f32_16x16x32_bf16 v[74:77], v[172:175], v[220:223], v[74:77]
	v_mfma_f32_16x16x32_bf16 v[78:81], v[164:167], v[220:223], v[78:81]
	v_mfma_f32_16x16x32_bf16 v[78:81], v[146:149], v[216:219], v[78:81]
	s_setprio 0
	s_setprio 1
	v_mfma_f32_16x16x32_bf16 v[118:121], v[176:179], v[192:195], v[118:121]
	v_mfma_f32_16x16x32_bf16 v[118:121], v[180:183], v[196:199], v[118:121]
	v_mfma_f32_16x16x32_bf16 v[114:117], v[188:191], v[196:199], v[114:117]
	v_mfma_f32_16x16x32_bf16 v[114:117], v[184:187], v[192:195], v[114:117]
	v_mfma_f32_16x16x32_bf16 v[98:101], v[184:187], v[200:203], v[98:101]
	v_mfma_f32_16x16x32_bf16 v[98:101], v[188:191], v[204:207], v[98:101]
	v_mfma_f32_16x16x32_bf16 v[102:105], v[180:183], v[204:207], v[102:105]
	v_mfma_f32_16x16x32_bf16 v[102:105], v[176:179], v[200:203], v[102:105]
	v_mfma_f32_16x16x32_bf16 v[86:89], v[176:179], v[208:211], v[86:89]
	v_mfma_f32_16x16x32_bf16 v[86:89], v[180:183], v[212:215], v[86:89]
	v_mfma_f32_16x16x32_bf16 v[82:85], v[188:191], v[212:215], v[82:85]
	v_mfma_f32_16x16x32_bf16 v[82:85], v[184:187], v[208:211], v[82:85]
	v_mfma_f32_16x16x32_bf16 v[66:69], v[184:187], v[216:219], v[66:69]
	v_mfma_f32_16x16x32_bf16 v[66:69], v[188:191], v[220:223], v[66:69]
	v_mfma_f32_16x16x32_bf16 v[70:73], v[180:183], v[220:223], v[70:73]
	v_mfma_f32_16x16x32_bf16 v[70:73], v[176:179], v[216:219], v[70:73]
	s_setprio 0
	s_barrier
	s_add_i32 s34, s53, s38
	v_lshl_add_u64 v[150:151], v[150:151], 0, s[10:11]
	s_mov_b32 m0, s34
	ds_read_b128 v[192:195], v159 offset:49152
	ds_read_b128 v[196:199], v159 offset:50176
	ds_read_b128 v[200:203], v159 offset:51200
	ds_read_b128 v[204:207], v159 offset:52224
	ds_read_b128 v[208:211], v159 offset:53248
	ds_read_b128 v[212:215], v159 offset:54272
	ds_read_b128 v[216:219], v159 offset:55296
	ds_read_b128 v[220:223], v159 offset:56320
	global_load_lds_dwordx4 v[150:151], off
	s_add_i32 m0, s34, 0x2000
	s_add_u32 s26, s26, 0x100080
	v_lshl_add_u64 v[150:151], v[160:161], 0, s[10:11]
	s_addc_u32 s27, s27, 0
	s_add_i32 s34, s54, s38
	global_load_lds_dwordx4 v[150:151], off
	v_lshl_add_u64 v[150:151], s[26:27], 0, v[132:133]
	s_mov_b32 m0, s34
	s_nop 0
	global_load_lds_dwordx4 v[150:151], off
	v_lshl_add_u64 v[150:151], s[26:27], 0, v[134:135]
	s_add_i32 m0, s34, 0x2000
	s_nop 0
	global_load_lds_dwordx4 v[150:151], off
	v_lshl_add_u64 v[150:151], v[224:225], 0, s[10:11]
	s_mov_b32 m0, s43
	s_nop 0
	global_load_lds_dwordx4 v[150:151], off
	v_lshl_add_u64 v[150:151], v[226:227], 0, s[10:11]
	s_mov_b32 m0, s44
	s_nop 0
	global_load_lds_dwordx4 v[150:151], off
	s_waitcnt vmcnt(8)
	s_waitcnt lgkmcnt(0)
	s_barrier
	s_setprio 1
	s_waitcnt lgkmcnt(0)
	v_mfma_f32_16x16x32_bf16 v[62:65], v[146:149], v[192:195], v[62:65]
	v_mfma_f32_16x16x32_bf16 v[62:65], v[164:167], v[196:199], v[62:65]
	v_mfma_f32_16x16x32_bf16 v[58:61], v[172:175], v[196:199], v[58:61]
	v_mfma_f32_16x16x32_bf16 v[58:61], v[168:171], v[192:195], v[58:61]
	v_mfma_f32_16x16x32_bf16 v[42:45], v[168:171], v[200:203], v[42:45]
	v_mfma_f32_16x16x32_bf16 v[42:45], v[172:175], v[204:207], v[42:45]
	v_mfma_f32_16x16x32_bf16 v[46:49], v[164:167], v[204:207], v[46:49]
	v_mfma_f32_16x16x32_bf16 v[46:49], v[146:149], v[200:203], v[46:49]
	v_mfma_f32_16x16x32_bf16 v[30:33], v[146:149], v[208:211], v[30:33]
	v_mfma_f32_16x16x32_bf16 v[30:33], v[164:167], v[212:215], v[30:33]
	v_mfma_f32_16x16x32_bf16 v[26:29], v[172:175], v[212:215], v[26:29]
	v_mfma_f32_16x16x32_bf16 v[26:29], v[168:171], v[208:211], v[26:29]
	v_mfma_f32_16x16x32_bf16 v[10:13], v[168:171], v[216:219], v[10:13]
	v_mfma_f32_16x16x32_bf16 v[10:13], v[172:175], v[220:223], v[10:13]
	v_mfma_f32_16x16x32_bf16 v[14:17], v[164:167], v[220:223], v[14:17]
	v_mfma_f32_16x16x32_bf16 v[14:17], v[146:149], v[216:219], v[14:17]
	s_setprio 0
	s_setprio 1
	v_mfma_f32_16x16x32_bf16 v[54:57], v[176:179], v[192:195], v[54:57]
	v_mfma_f32_16x16x32_bf16 v[54:57], v[180:183], v[196:199], v[54:57]
	v_mfma_f32_16x16x32_bf16 v[50:53], v[188:191], v[196:199], v[50:53]
	v_mfma_f32_16x16x32_bf16 v[50:53], v[184:187], v[192:195], v[50:53]
	v_mfma_f32_16x16x32_bf16 v[34:37], v[184:187], v[200:203], v[34:37]
	v_mfma_f32_16x16x32_bf16 v[34:37], v[188:191], v[204:207], v[34:37]
	v_mfma_f32_16x16x32_bf16 v[38:41], v[180:183], v[204:207], v[38:41]
	v_mfma_f32_16x16x32_bf16 v[38:41], v[176:179], v[200:203], v[38:41]
	v_mfma_f32_16x16x32_bf16 v[22:25], v[176:179], v[208:211], v[22:25]
	v_mfma_f32_16x16x32_bf16 v[22:25], v[180:183], v[212:215], v[22:25]
	v_mfma_f32_16x16x32_bf16 v[18:21], v[188:191], v[212:215], v[18:21]
	v_mfma_f32_16x16x32_bf16 v[18:21], v[184:187], v[208:211], v[18:21]
	v_mfma_f32_16x16x32_bf16 v[2:5], v[184:187], v[216:219], v[2:5]
	v_mfma_f32_16x16x32_bf16 v[2:5], v[188:191], v[220:223], v[2:5]
	v_mfma_f32_16x16x32_bf16 v[6:9], v[180:183], v[220:223], v[6:9]
	v_mfma_f32_16x16x32_bf16 v[6:9], v[176:179], v[216:219], v[6:9]
	s_setprio 0
	s_barrier
	s_add_i32 s52, s52, 2
	s_add_u32 s24, s24, 0x100
	s_addc_u32 s25, s25, 0
	s_add_u32 s50, s50, 0x100
	s_addc_u32 s51, s51, 0
	s_cmp_gt_u32 s52, 61
	s_cbranch_scc0 .LBB0_2158
	s_and_b64 vcc, exec, s[12:13]
	s_cbranch_vccz .LBB0_2161
	s_barrier
